# instruction selection: LDS-DMA tile loads in P1/P3/P5/P6 K-loops use the SGPR-base + 32-bit VGPR offset form, removing 64-bit VALU address adds from the load segments
# speedup vs baseline: 1.0118x; 1.0030x over previous
; #define PG8_STAGE(bufoff, gbase, voff) do { _Pragma("unroll") for (int _i = 0; _i < 2; ++_i) \
;         __builtin_amdgcn_global_load_lds((const unsigned*)((const char*)(gbase) + (voff)[_i]), (PG8_LAS unsigned*)(lds + (bufoff) + ldsw + _i * 8192), 16, 0, 0); } while (0)
; #define PG8_LDA(dst, b, h) do { _Pragma("unroll") for (int m = 0; m < 4; ++m) _Pragma("unroll") for (int k = 0; k < 2; ++k) dst[m][k] = *(const PG8_LAS bf16x8*)(lds + PG8_SA(b, h) + aoff + m * 2048 + k * 1024); } while (0)
; template <class Epi, class Sched, bool ALIGN_EPI = false, bool SP2 = false>
; __device__ __forceinline__ void gemm_phase(PG8_LAS unsigned char* lds, const Gemm g, const Sched& S, const Epi& E) {
;     ...
;         const char* nA = has_next ? (const char*)g.A + (size_t)nxt.pm * tstep : cA; const char* nB = has_next ? (const char*)g.Bt + (size_t)nxt.pn * tstep : cB;
;         for (int t = 0; t < nt; t += 2) {
;             const bool last = (t == nt - 2);
;             const char* a1 = cA + (size_t)(t + 1) * kstep;
;             const char* a2 = last ? nA : cA + (size_t)(t + 2) * kstep; const char* b2 = last ? nB : cB + (size_t)(t + 2) * kstep;
;             const char* a3 = a2 + kstep; const char* b3 = b2 + kstep;
;             if (last && has_next) S.a_ready(nxt);
;             if constexpr (SP2) {
;             PG8_LDB(B0, 0, 0); PG8_LDB(B1, 0, 1); PG8_SCHED; PG8_LDA(At, 0, 0); PG8_STAGE(PG8_SA(1, 1), a1 + hstep, voffA);
;     __device__ __forceinline__ void operator()(const f32x4 (&acc)[2][2][4][2], const pg8::Unit& u, int wr, int wc, int fr, int fq) const {
;         const int row0 = u.pm * 256 + wr * 64 + fr, col = u.pn * 128 + wc * 32 + 8 * fq;
; #pragma unroll
;         for (int ai = 0; ai < 2; ++ai)
; #pragma unroll
;             for (int m = 0; m < 4; ++m) {
;                 const int row = row0 + ai * 128 + m * 16;
;                 const float rs = sumsq ? rsqrtf(sumsq[row] * (1.f / 1024.f) + EPS) : 1.f;
;                 float o[8];
; #pragma unroll
;                 for (int n = 0; n < 2; ++n)
; #pragma unroll
;                     for (int e = 0; e < 4; ++e) { const float g = acc[ai][0][m][n][e] * rs, up = acc[ai][1][m][n][e] * rs; o[4 * n + e] = silu_f(g) * up; }
;                 u32x4 w; w.x = pk2(o[0], o[1]); w.y = pk2(o[2], o[3]); w.z = pk2(o[4], o[5]); w.w = pk2(o[6], o[7]);
;                 *(u32x4*)(H + (size_t)row * DFF + col) = w;
.LBB0_191:
	s_ashr_i32 s15, s14, 31
	s_lshl_b64 s[16:17], s[14:15], 19
	v_readlane_b32 s18, v235, 31
	v_readlane_b32 s19, v235, 32
	s_add_u32 s16, s18, s16
	s_addc_u32 s17, s19, s17
	s_and_b64 s[18:19], s[0:1], exec
	s_cselect_b32 s15, s17, s23
	s_cselect_b32 s50, s16, s22
	s_ashr_i32 s9, s8, 31
	s_lshl_b64 s[18:19], s[8:9], 19
	s_add_u32 s18, s33, s18
	s_addc_u32 s19, s34, s19
	s_and_b64 s[30:31], s[0:1], exec
	s_cselect_b32 s9, s19, s25
	s_cselect_b32 s51, s18, s24
	s_add_u32 s22, s22, 0x40080
	s_addc_u32 s23, s23, 0
	s_add_u32 s52, s24, 0x100
	s_addc_u32 s53, s25, 0
	s_mov_b32 s54, -2
	s_cmp_eq_u32 s98, 0
	s_cbranch_scc1 .Lp1_plain
	ds_read_b128 v[150:153], v147
	ds_read_b128 v[154:157], v147 offset:1024
	ds_read_b128 v[158:161], v147 offset:2048
	ds_read_b128 v[162:165], v147 offset:3072
	ds_read_b128 v[166:169], v148
	ds_read_b128 v[170:173], v148 offset:1024
	ds_read_b128 v[174:177], v148 offset:2048
	ds_read_b128 v[178:181], v148 offset:3072
	s_add_u32 s24, s22, 0xfffc0080
	s_addc_u32 s25, s23, -1
	s_cmp_eq_u32 s54, 12
	s_cselect_b32 s31, s15, s25
	s_cselect_b32 s30, s50, s24
	s_cselect_b32 s25, s9, s53
	s_cselect_b32 s24, s51, s52
	s_add_i32 m0, s21, 0xc000
	ds_read_b128 v[182:185], v149
	ds_read_b128 v[192:195], v149 offset:1024
	ds_read_b128 v[196:199], v149 offset:2048
	ds_read_b128 v[200:203], v149 offset:3072
	ds_read_b128 v[204:207], v149 offset:4096
	ds_read_b128 v[208:211], v149 offset:5120
	ds_read_b128 v[212:215], v149 offset:6144
	ds_read_b128 v[216:219], v149 offset:7168
	global_load_lds_dwordx4 v136, s[22:23]
	s_add_i32 m0, s21, 0xe000
	s_nop 0
	global_load_lds_dwordx4 v138, s[22:23]
	s_nop 1
	v_add_f32_e32 v64, 1.0, v70
	v_rcp_f32_e32 v64, v64
	v_add_f32_e32 v65, 1.0, v71
	v_rcp_f32_e32 v65, v65
	v_add_u32_e32 v66, 0x80, v228
	v_mul_f32_e32 v60, v60, v64
	v_mul_f32_e32 v52, v60, v52
	v_mul_f32_e32 v60, v61, v65
	v_mul_f32_e32 v61, 0xbfb8aa3b, v62
	v_exp_f32_e32 v61, v61
	v_mul_f32_e32 v64, 0xbfb8aa3b, v63
	v_exp_f32_e32 v64, v64
	v_mul_f32_e32 v53, v60, v53
	v_add_f32_e32 v60, 1.0, v61
	v_rcp_f32_e32 v60, v60
	v_add_f32_e32 v61, 1.0, v64
	v_mul_f32_e32 v64, 0xbfb8aa3b, v56
	v_rcp_f32_e32 v61, v61
	v_exp_f32_e32 v64, v64
	v_mul_f32_e32 v60, v62, v60
	v_mul_f32_e32 v54, v60, v54
	v_mul_f32_e32 v60, v63, v61
	v_add_f32_e32 v61, 1.0, v64
	v_rcp_f32_e32 v61, v61
	v_mul_f32_e32 v62, 0xbfb8aa3b, v57
	v_exp_f32_e32 v62, v62
	v_mul_f32_e32 v55, v60, v55
	v_mul_f32_e32 v56, v56, v61
	v_mul_f32_e32 v56, v56, v48
	v_add_f32_e32 v48, 1.0, v62
	v_mul_f32_e32 v60, 0xbfb8aa3b, v58
	v_rcp_f32_e32 v48, v48
	v_exp_f32_e32 v60, v60
	v_mul_f32_e32 v61, 0xbfb8aa3b, v59
	v_exp_f32_e32 v61, v61
	v_mul_f32_e32 v48, v57, v48
	v_add_f32_e32 v57, 1.0, v60
	v_rcp_f32_e32 v57, v57
	v_add_f32_e32 v60, 1.0, v61
	v_rcp_f32_e32 v60, v60
	v_mul_f32_e32 v61, v48, v49
	v_mul_f32_e32 v48, v58, v57
	v_mul_f32_e32 v57, v48, v50
	v_mul_f32_e32 v48, v59, v60
	v_mul_f32_e32 v51, v48, v51
	v_cvt_pk_bf16_f32 v48, v52, v53
	v_cvt_pk_bf16_f32 v49, v54, v55
	v_mul_f32_e32 v54, 0xbfb8aa3b, v44
	v_exp_f32_e32 v54, v54
	v_mul_f32_e32 v55, 0xbfb8aa3b, v45
	v_exp_f32_e32 v55, v55
	v_mad_i64_i32 v[52:53], s[100:101], v66, s48, v[112:113]
	v_lshl_add_u64 v[52:53], v[52:53], 0, v[114:115]
	v_cvt_pk_bf16_f32 v50, v56, v61
	v_cvt_pk_bf16_f32 v51, v57, v51
	global_store_dwordx4 v[52:53], v[48:51], off
	s_nop 1
	v_add_f32_e32 v48, 1.0, v54
	v_rcp_f32_e32 v48, v48
	v_add_f32_e32 v49, 1.0, v55
	v_rcp_f32_e32 v49, v49
	v_add_u32_e32 v50, 0x90, v228
	v_mul_f32_e32 v44, v44, v48
	v_mul_f32_e32 v36, v44, v36
	v_mul_f32_e32 v44, v45, v49
	v_mul_f32_e32 v45, 0xbfb8aa3b, v46
	v_exp_f32_e32 v45, v45
	v_mul_f32_e32 v48, 0xbfb8aa3b, v47
	v_exp_f32_e32 v48, v48
	v_mul_f32_e32 v37, v44, v37
	v_add_f32_e32 v44, 1.0, v45
	v_rcp_f32_e32 v44, v44
	v_add_f32_e32 v45, 1.0, v48
	v_mul_f32_e32 v48, 0xbfb8aa3b, v40
	v_rcp_f32_e32 v45, v45
	v_exp_f32_e32 v48, v48
	v_mul_f32_e32 v44, v46, v44
	v_mul_f32_e32 v38, v44, v38
	v_mul_f32_e32 v44, v47, v45
	v_add_f32_e32 v45, 1.0, v48
	v_rcp_f32_e32 v45, v45
	v_mul_f32_e32 v46, 0xbfb8aa3b, v41
	v_exp_f32_e32 v46, v46
	v_mul_f32_e32 v39, v44, v39
	v_mul_f32_e32 v40, v40, v45
	v_mul_f32_e32 v40, v40, v32
	v_add_f32_e32 v32, 1.0, v46
	v_mul_f32_e32 v44, 0xbfb8aa3b, v42
	v_rcp_f32_e32 v32, v32
	v_exp_f32_e32 v44, v44
	v_mul_f32_e32 v45, 0xbfb8aa3b, v43
	v_exp_f32_e32 v45, v45
	v_mul_f32_e32 v32, v41, v32
	v_add_f32_e32 v41, 1.0, v44
	v_rcp_f32_e32 v41, v41
	v_add_f32_e32 v44, 1.0, v45
	v_rcp_f32_e32 v44, v44
	v_mul_f32_e32 v45, v32, v33
	v_mul_f32_e32 v32, v42, v41
	v_mul_f32_e32 v41, v32, v34
	v_mul_f32_e32 v32, v43, v44
	v_mul_f32_e32 v35, v32, v35
	v_cvt_pk_bf16_f32 v32, v36, v37
	v_cvt_pk_bf16_f32 v33, v38, v39
	v_mul_f32_e32 v38, 0xbfb8aa3b, v28
	v_exp_f32_e32 v38, v38
	v_mul_f32_e32 v39, 0xbfb8aa3b, v29
	v_exp_f32_e32 v39, v39
	v_mad_i64_i32 v[36:37], s[100:101], v50, s48, v[112:113]
	v_lshl_add_u64 v[36:37], v[36:37], 0, v[114:115]
	v_cvt_pk_bf16_f32 v34, v40, v45
	v_cvt_pk_bf16_f32 v35, v41, v35
	global_store_dwordx4 v[36:37], v[32:35], off
	s_nop 1
	v_add_f32_e32 v32, 1.0, v38
	v_rcp_f32_e32 v32, v32
	v_add_f32_e32 v33, 1.0, v39
	v_rcp_f32_e32 v33, v33
	v_add_u32_e32 v34, 0xa0, v228
	v_mul_f32_e32 v28, v28, v32
	v_mul_f32_e32 v20, v28, v20
	v_mul_f32_e32 v28, v29, v33
	v_mul_f32_e32 v29, 0xbfb8aa3b, v30
	v_exp_f32_e32 v29, v29
	v_mul_f32_e32 v32, 0xbfb8aa3b, v31
	v_exp_f32_e32 v32, v32
	v_mul_f32_e32 v21, v28, v21
	v_add_f32_e32 v28, 1.0, v29
	v_rcp_f32_e32 v28, v28
	v_add_f32_e32 v29, 1.0, v32
	v_mul_f32_e32 v32, 0xbfb8aa3b, v24
	v_rcp_f32_e32 v29, v29
	v_exp_f32_e32 v32, v32
	v_mul_f32_e32 v28, v30, v28
	v_mul_f32_e32 v22, v28, v22
; #define PG8_STAGE(bufoff, gbase, voff) do { _Pragma("unroll") for (int _i = 0; _i < 2; ++_i) \
;         __builtin_amdgcn_global_load_lds((const unsigned*)((const char*)(gbase) + (voff)[_i]), (PG8_LAS unsigned*)(lds + (bufoff) + ldsw + _i * 8192), 16, 0, 0); } while (0)
; #define PG8_LDA(dst, b, h) do { _Pragma("unroll") for (int m = 0; m < 4; ++m) _Pragma("unroll") for (int k = 0; k < 2; ++k) dst[m][k] = *(const PG8_LAS bf16x8*)(lds + PG8_SA(b, h) + aoff + m * 2048 + k * 1024); } while (0)
; #define PG8_LDB(dst, b, h) do { _Pragma("unroll") for (int n = 0; n < 2; ++n) _Pragma("unroll") for (int k = 0; k < 2; ++k) dst[n][k] = *(const PG8_LAS bf16x8*)(lds + PG8_SB(b, h) + boff + n * 2048 + k * 1024); } while (0)
; #define PG8_WAIT_V(n) asm volatile("s_waitcnt vmcnt(" #n ")" ::: "memory")
; #define PG8_BAR __builtin_amdgcn_s_barrier()
; template <class Epi, class Sched, bool ALIGN_EPI = false, bool SP2 = false>
; __device__ __forceinline__ void gemm_phase(PG8_LAS unsigned char* lds, const Gemm g, const Sched& S, const Epi& E) {
;     ...
;             PG8_LDB(B0, 0, 0); PG8_LDB(B1, 0, 1); PG8_SCHED; PG8_LDA(At, 0, 0); PG8_STAGE(PG8_SA(1, 1), a1 + hstep, voffA);
;             PG8_WAIT_V(8); PG8_WAIT_L(0); PG8_BAR; PG8_MMA(0, 0, At, B0); PG8_MMA(0, 1, At, B1); PG8_BAR; PG8_SCHED;
;             PG8_LDA(At, 0, 1); PG8_STAGE(PG8_SB(0, 0), b2, voffB); PG8_STAGE(PG8_SB(0, 1), b2 + hstep, voffB); PG8_STAGE(PG8_SA(0, 0), a2, voffA);
;     __device__ __forceinline__ void operator()(const f32x4 (&acc)[2][2][4][2], const pg8::Unit& u, int wr, int wc, int fr, int fq) const {
;         const int row0 = u.pm * 256 + wr * 64 + fr, col = u.pn * 128 + wc * 32 + 8 * fq;
; #pragma unroll
;         for (int ai = 0; ai < 2; ++ai)
; #pragma unroll
;             for (int m = 0; m < 4; ++m) {
;                 const int row = row0 + ai * 128 + m * 16;
;                 const float rs = sumsq ? rsqrtf(sumsq[row] * (1.f / 1024.f) + EPS) : 1.f;
;                 float o[8];
; #pragma unroll
;                 for (int n = 0; n < 2; ++n)
; #pragma unroll
;                     for (int e = 0; e < 4; ++e) { const float g = acc[ai][0][m][n][e] * rs, up = acc[ai][1][m][n][e] * rs; o[4 * n + e] = silu_f(g) * up; }
;                 u32x4 w; w.x = pk2(o[0], o[1]); w.y = pk2(o[2], o[3]); w.z = pk2(o[4], o[5]); w.w = pk2(o[6], o[7]);
;                 *(u32x4*)(H + (size_t)row * DFF + col) = w;
	v_mul_f32_e32 v28, v31, v29
	v_add_f32_e32 v29, 1.0, v32
	v_rcp_f32_e32 v29, v29
	v_mul_f32_e32 v30, 0xbfb8aa3b, v25
	v_exp_f32_e32 v30, v30
	v_mul_f32_e32 v23, v28, v23
	v_mul_f32_e32 v24, v24, v29
	v_mul_f32_e32 v24, v24, v16
	v_add_f32_e32 v16, 1.0, v30
	v_mul_f32_e32 v28, 0xbfb8aa3b, v26
	v_rcp_f32_e32 v16, v16
	v_exp_f32_e32 v28, v28
	v_mul_f32_e32 v29, 0xbfb8aa3b, v27
	v_exp_f32_e32 v29, v29
	v_mul_f32_e32 v16, v25, v16
	v_add_f32_e32 v25, 1.0, v28
	v_rcp_f32_e32 v25, v25
	v_add_f32_e32 v28, 1.0, v29
	v_rcp_f32_e32 v28, v28
	v_mul_f32_e32 v29, v16, v17
	v_mul_f32_e32 v16, v26, v25
	v_mul_f32_e32 v25, v16, v18
	v_mul_f32_e32 v16, v27, v28
	v_mul_f32_e32 v19, v16, v19
	v_cvt_pk_bf16_f32 v16, v20, v21
	v_cvt_pk_bf16_f32 v17, v22, v23
	v_mul_f32_e32 v22, 0xbfb8aa3b, v12
	v_exp_f32_e32 v22, v22
	v_mul_f32_e32 v23, 0xbfb8aa3b, v13
	v_exp_f32_e32 v23, v23
	v_mad_i64_i32 v[20:21], s[100:101], v34, s48, v[112:113]
	v_lshl_add_u64 v[20:21], v[20:21], 0, v[114:115]
	v_cvt_pk_bf16_f32 v18, v24, v29
	v_cvt_pk_bf16_f32 v19, v25, v19
	global_store_dwordx4 v[20:21], v[16:19], off
	s_nop 1
	v_add_f32_e32 v16, 1.0, v22
	v_rcp_f32_e32 v16, v16
	v_add_f32_e32 v17, 1.0, v23
	v_rcp_f32_e32 v17, v17
	v_add_u32_e32 v18, 0xb0, v228
	v_mul_f32_e32 v12, v12, v16
	v_mul_f32_e32 v4, v12, v4
	v_mul_f32_e32 v12, v13, v17
	v_mul_f32_e32 v13, 0xbfb8aa3b, v14
	v_exp_f32_e32 v13, v13
	v_mul_f32_e32 v16, 0xbfb8aa3b, v15
	v_exp_f32_e32 v16, v16
	v_mul_f32_e32 v5, v12, v5
	v_add_f32_e32 v12, 1.0, v13
	v_rcp_f32_e32 v12, v12
	v_add_f32_e32 v13, 1.0, v16
	v_mul_f32_e32 v16, 0xbfb8aa3b, v8
	v_rcp_f32_e32 v13, v13
	v_exp_f32_e32 v16, v16
	v_mul_f32_e32 v12, v14, v12
	v_mul_f32_e32 v6, v12, v6
	v_mul_f32_e32 v12, v15, v13
	v_add_f32_e32 v13, 1.0, v16
	v_rcp_f32_e32 v13, v13
	v_mul_f32_e32 v14, 0xbfb8aa3b, v9
	v_exp_f32_e32 v14, v14
	v_mul_f32_e32 v7, v12, v7
	v_mul_f32_e32 v8, v8, v13
	v_mul_f32_e32 v8, v8, v0
	v_add_f32_e32 v0, 1.0, v14
	v_mul_f32_e32 v12, 0xbfb8aa3b, v10
	v_rcp_f32_e32 v0, v0
	v_exp_f32_e32 v12, v12
	v_mul_f32_e32 v13, 0xbfb8aa3b, v11
	v_exp_f32_e32 v13, v13
	v_mul_f32_e32 v0, v9, v0
	v_add_f32_e32 v9, 1.0, v12
	v_rcp_f32_e32 v9, v9
	v_add_f32_e32 v12, 1.0, v13
	v_rcp_f32_e32 v12, v12
	v_mul_f32_e32 v13, v0, v1
	v_mul_f32_e32 v0, v10, v9
	v_mul_f32_e32 v9, v0, v2
	v_mul_f32_e32 v0, v11, v12
	v_mul_f32_e32 v3, v0, v3
	v_cvt_pk_bf16_f32 v0, v4, v5
	v_mad_i64_i32 v[4:5], s[100:101], v18, s48, v[112:113]
	v_lshl_add_u64 v[4:5], v[4:5], 0, v[114:115]
	v_cvt_pk_bf16_f32 v1, v6, v7
	v_cvt_pk_bf16_f32 v2, v8, v13
	v_cvt_pk_bf16_f32 v3, v9, v3
	global_store_dwordx4 v[4:5], v[0:3], off
	s_waitcnt vmcnt(16)
	s_waitcnt lgkmcnt(0)
	s_barrier
	s_setprio 1
	v_mfma_f32_16x16x32_bf16 v[124:127], v[150:153], v[182:185], 0
	v_mfma_f32_16x16x32_bf16 v[120:123], v[158:161], v[182:185], 0
	v_mfma_f32_16x16x32_bf16 v[108:111], v[150:153], v[196:199], 0
	v_mfma_f32_16x16x32_bf16 v[104:107], v[158:161], v[196:199], 0
	v_mfma_f32_16x16x32_bf16 v[92:95], v[150:153], v[204:207], 0
	v_mfma_f32_16x16x32_bf16 v[88:91], v[158:161], v[204:207], 0
	v_mfma_f32_16x16x32_bf16 v[76:79], v[150:153], v[212:215], 0
	v_mfma_f32_16x16x32_bf16 v[72:75], v[158:161], v[212:215], 0
	v_mfma_f32_16x16x32_bf16 v[124:127], v[154:157], v[192:195], v[124:127]
	v_mfma_f32_16x16x32_bf16 v[120:123], v[162:165], v[192:195], v[120:123]
	v_mfma_f32_16x16x32_bf16 v[108:111], v[154:157], v[200:203], v[108:111]
	v_mfma_f32_16x16x32_bf16 v[104:107], v[162:165], v[200:203], v[104:107]
	v_mfma_f32_16x16x32_bf16 v[92:95], v[154:157], v[208:211], v[92:95]
	v_mfma_f32_16x16x32_bf16 v[88:91], v[162:165], v[208:211], v[88:91]
	v_mfma_f32_16x16x32_bf16 v[76:79], v[154:157], v[216:219], v[76:79]
	v_mfma_f32_16x16x32_bf16 v[72:75], v[162:165], v[216:219], v[72:75]
	v_mfma_f32_16x16x32_bf16 v[116:119], v[166:169], v[182:185], 0
	v_mfma_f32_16x16x32_bf16 v[112:115], v[174:177], v[182:185], 0
	v_mfma_f32_16x16x32_bf16 v[100:103], v[166:169], v[196:199], 0
	v_mfma_f32_16x16x32_bf16 v[96:99], v[174:177], v[196:199], 0
	v_mfma_f32_16x16x32_bf16 v[84:87], v[166:169], v[204:207], 0
	v_mfma_f32_16x16x32_bf16 v[80:83], v[174:177], v[204:207], 0
	v_mfma_f32_16x16x32_bf16 v[68:71], v[166:169], v[212:215], 0
	v_mfma_f32_16x16x32_bf16 v[64:67], v[174:177], v[212:215], 0
	v_mfma_f32_16x16x32_bf16 v[116:119], v[170:173], v[192:195], v[116:119]
	v_mfma_f32_16x16x32_bf16 v[112:115], v[178:181], v[192:195], v[112:115]
	v_mfma_f32_16x16x32_bf16 v[100:103], v[170:173], v[200:203], v[100:103]
	v_mfma_f32_16x16x32_bf16 v[96:99], v[178:181], v[200:203], v[96:99]
	v_mfma_f32_16x16x32_bf16 v[84:87], v[170:173], v[208:211], v[84:87]
	v_mfma_f32_16x16x32_bf16 v[80:83], v[178:181], v[208:211], v[80:83]
	v_mfma_f32_16x16x32_bf16 v[68:71], v[170:173], v[216:219], v[68:71]
	v_mfma_f32_16x16x32_bf16 v[64:67], v[178:181], v[216:219], v[64:67]
	s_setprio 0
	s_barrier
	s_add_i32 s55, s46, s35
	v_lshl_add_u64 v[186:187], s[24:25], 0, v[132:133]
	s_mov_b32 m0, s55
	ds_read_b128 v[182:185], v149 offset:16384
	ds_read_b128 v[192:195], v149 offset:17408
	ds_read_b128 v[196:199], v149 offset:18432
	ds_read_b128 v[200:203], v149 offset:19456
	ds_read_b128 v[204:207], v149 offset:20480
	ds_read_b128 v[208:211], v149 offset:21504
	ds_read_b128 v[212:215], v149 offset:22528
	ds_read_b128 v[216:219], v149 offset:23552
	global_load_lds_dwordx4 v[186:187], off
	s_add_i32 m0, s55, 0x2000
	s_add_u32 s56, s24, 0x40000
	v_lshl_add_u64 v[220:221], s[24:25], 0, v[128:129]
	s_addc_u32 s57, s25, 0
	s_add_i32 s55, s47, s35
	global_load_lds_dwordx4 v[220:221], off
	s_mov_b32 m0, s55
	v_lshl_add_u64 v[224:225], s[30:31], 0, v[130:131]
	global_load_lds_dwordx4 v132, s[56:57]
	s_add_i32 m0, s55, 0x2000
	s_nop 0
	global_load_lds_dwordx4 v128, s[56:57]
	v_lshl_add_u64 v[222:223], s[30:31], 0, v[134:135]
	s_mov_b32 m0, s21
	s_nop 0
	global_load_lds_dwordx4 v[222:223], off
	s_mov_b32 m0, s38
	s_nop 0
	global_load_lds_dwordx4 v[224:225], off
	s_waitcnt vmcnt(16)
	s_waitcnt lgkmcnt(0)
	s_barrier
; #define PG8_STAGE(bufoff, gbase, voff) do { _Pragma("unroll") for (int _i = 0; _i < 2; ++_i) \
;         __builtin_amdgcn_global_load_lds((const unsigned*)((const char*)(gbase) + (voff)[_i]), (PG8_LAS unsigned*)(lds + (bufoff) + ldsw + _i * 8192), 16, 0, 0); } while (0)
; #define PG8_LDA(dst, b, h) do { _Pragma("unroll") for (int m = 0; m < 4; ++m) _Pragma("unroll") for (int k = 0; k < 2; ++k) dst[m][k] = *(const PG8_LAS bf16x8*)(lds + PG8_SA(b, h) + aoff + m * 2048 + k * 1024); } while (0)
; #define PG8_LDB(dst, b, h) do { _Pragma("unroll") for (int n = 0; n < 2; ++n) _Pragma("unroll") for (int k = 0; k < 2; ++k) dst[n][k] = *(const PG8_LAS bf16x8*)(lds + PG8_SB(b, h) + boff + n * 2048 + k * 1024); } while (0)
; #define PG8_MMA(ai, bj, At, Bt) do { __builtin_amdgcn_s_setprio(1); _Pragma("unroll") for (int m = 0; m < 4; ++m) _Pragma("unroll") for (int n = 0; n < 2; ++n) _Pragma("unroll") for (int k = 0; k < 2; ++k) \
;         acc[ai][bj][m][n] = __builtin_amdgcn_mfma_f32_16x16x32_bf16(Bt[n][k], At[m][k], acc[ai][bj][m][n], 0, 0, 0); __builtin_amdgcn_s_setprio(0); } while (0)
; #define PG8_WAIT_V(n) asm volatile("s_waitcnt vmcnt(" #n ")" ::: "memory")
; #define PG8_WAIT_L(n) asm volatile("s_waitcnt lgkmcnt(" #n ")" ::: "memory")
; #define PG8_BAR __builtin_amdgcn_s_barrier()
; #define PG8_SCHED __builtin_amdgcn_sched_barrier(0)
; template <class Epi, class Sched, bool ALIGN_EPI = false, bool SP2 = false>
; __device__ __forceinline__ void gemm_phase(PG8_LAS unsigned char* lds, const Gemm g, const Sched& S, const Epi& E) {
;     ...
;             PG8_WAIT_V(8); PG8_WAIT_L(0); PG8_BAR; PG8_MMA(1, 0, At, B0); PG8_MMA(1, 1, At, B1); PG8_BAR; PG8_SCHED;
;             PG8_LDB(B0, 1, 0); PG8_LDB(B1, 1, 1); PG8_SCHED; PG8_LDA(At, 1, 0); PG8_STAGE(PG8_SA(0, 1), a2 + hstep, voffA);
;             PG8_WAIT_V(8); PG8_WAIT_L(0); PG8_BAR; PG8_MMA(0, 0, At, B0); PG8_MMA(0, 1, At, B1); PG8_BAR; PG8_SCHED;
	s_setprio 1
	v_mfma_f32_16x16x32_bf16 v[60:63], v[150:153], v[182:185], 0
	v_mfma_f32_16x16x32_bf16 v[56:59], v[158:161], v[182:185], 0
	v_mfma_f32_16x16x32_bf16 v[44:47], v[150:153], v[196:199], 0
	v_mfma_f32_16x16x32_bf16 v[40:43], v[158:161], v[196:199], 0
	v_mfma_f32_16x16x32_bf16 v[28:31], v[150:153], v[204:207], 0
	v_mfma_f32_16x16x32_bf16 v[24:27], v[158:161], v[204:207], 0
	v_mfma_f32_16x16x32_bf16 v[12:15], v[150:153], v[212:215], 0
	v_mfma_f32_16x16x32_bf16 v[8:11], v[158:161], v[212:215], 0
	v_mfma_f32_16x16x32_bf16 v[60:63], v[154:157], v[192:195], v[60:63]
	v_mfma_f32_16x16x32_bf16 v[56:59], v[162:165], v[192:195], v[56:59]
	v_mfma_f32_16x16x32_bf16 v[44:47], v[154:157], v[200:203], v[44:47]
	v_mfma_f32_16x16x32_bf16 v[40:43], v[162:165], v[200:203], v[40:43]
	v_mfma_f32_16x16x32_bf16 v[28:31], v[154:157], v[208:211], v[28:31]
	v_mfma_f32_16x16x32_bf16 v[24:27], v[162:165], v[208:211], v[24:27]
	v_mfma_f32_16x16x32_bf16 v[12:15], v[154:157], v[216:219], v[12:15]
	v_mfma_f32_16x16x32_bf16 v[8:11], v[162:165], v[216:219], v[8:11]
	v_mfma_f32_16x16x32_bf16 v[52:55], v[166:169], v[182:185], 0
	v_mfma_f32_16x16x32_bf16 v[48:51], v[174:177], v[182:185], 0
	v_mfma_f32_16x16x32_bf16 v[36:39], v[166:169], v[196:199], 0
	v_mfma_f32_16x16x32_bf16 v[32:35], v[174:177], v[196:199], 0
	v_mfma_f32_16x16x32_bf16 v[20:23], v[166:169], v[204:207], 0
	v_mfma_f32_16x16x32_bf16 v[16:19], v[174:177], v[204:207], 0
	v_mfma_f32_16x16x32_bf16 v[4:7], v[166:169], v[212:215], 0
	v_mfma_f32_16x16x32_bf16 v[0:3], v[174:177], v[212:215], 0
	v_mfma_f32_16x16x32_bf16 v[52:55], v[170:173], v[192:195], v[52:55]
	v_mfma_f32_16x16x32_bf16 v[48:51], v[178:181], v[192:195], v[48:51]
	v_mfma_f32_16x16x32_bf16 v[36:39], v[170:173], v[200:203], v[36:39]
	v_mfma_f32_16x16x32_bf16 v[32:35], v[178:181], v[200:203], v[32:35]
	v_mfma_f32_16x16x32_bf16 v[20:23], v[170:173], v[208:211], v[20:23]
	v_mfma_f32_16x16x32_bf16 v[16:19], v[178:181], v[208:211], v[16:19]
	v_mfma_f32_16x16x32_bf16 v[4:7], v[170:173], v[216:219], v[4:7]
	v_mfma_f32_16x16x32_bf16 v[0:3], v[178:181], v[216:219], v[0:3]
	s_setprio 0
	s_barrier
	s_add_i32 s55, 0, 0x18000
	s_add_i32 s56, 0, 0x1c000
	v_add_u32_e32 v162, s55, v145
	v_add_u32_e32 v178, s56, v145
	ds_read_b128 v[150:153], v162
	ds_read_b128 v[154:157], v162 offset:1024
	ds_read_b128 v[158:161], v162 offset:2048
	ds_read_b128 v[162:165], v162 offset:3072
	ds_read_b128 v[166:169], v178
	ds_read_b128 v[170:173], v178 offset:1024
	ds_read_b128 v[174:177], v178 offset:2048
	ds_read_b128 v[178:181], v178 offset:3072
	s_add_u32 s30, s30, 0x40000
	s_addc_u32 s31, s31, 0
	s_mov_b32 m0, s39
	ds_read_b128 v[182:185], v149 offset:32768
	ds_read_b128 v[192:195], v149 offset:33792
	ds_read_b128 v[196:199], v149 offset:34816
	ds_read_b128 v[200:203], v149 offset:35840
	ds_read_b128 v[204:207], v149 offset:36864
	ds_read_b128 v[208:211], v149 offset:37888
	ds_read_b128 v[212:215], v149 offset:38912
	ds_read_b128 v[216:219], v149 offset:39936
	global_load_lds_dwordx4 v134, s[30:31]
	v_lshl_add_u64 v[226:227], s[30:31], 0, v[130:131]
	s_mov_b32 m0, s40
	s_nop 0
	global_load_lds_dwordx4 v[226:227], off
	s_waitcnt vmcnt(8)
	s_waitcnt lgkmcnt(0)
	s_barrier
	s_setprio 1
	v_mfma_f32_16x16x32_bf16 v[124:127], v[150:153], v[182:185], v[124:127]
	v_mfma_f32_16x16x32_bf16 v[120:123], v[158:161], v[182:185], v[120:123]
	v_mfma_f32_16x16x32_bf16 v[108:111], v[150:153], v[196:199], v[108:111]
	v_mfma_f32_16x16x32_bf16 v[104:107], v[158:161], v[196:199], v[104:107]
	v_mfma_f32_16x16x32_bf16 v[92:95], v[150:153], v[204:207], v[92:95]
	v_mfma_f32_16x16x32_bf16 v[88:91], v[158:161], v[204:207], v[88:91]
	v_mfma_f32_16x16x32_bf16 v[76:79], v[150:153], v[212:215], v[76:79]
	v_mfma_f32_16x16x32_bf16 v[72:75], v[158:161], v[212:215], v[72:75]
	v_mfma_f32_16x16x32_bf16 v[124:127], v[154:157], v[192:195], v[124:127]
	v_mfma_f32_16x16x32_bf16 v[120:123], v[162:165], v[192:195], v[120:123]
	v_mfma_f32_16x16x32_bf16 v[108:111], v[154:157], v[200:203], v[108:111]
	v_mfma_f32_16x16x32_bf16 v[104:107], v[162:165], v[200:203], v[104:107]
	v_mfma_f32_16x16x32_bf16 v[92:95], v[154:157], v[208:211], v[92:95]
	v_mfma_f32_16x16x32_bf16 v[88:91], v[162:165], v[208:211], v[88:91]
	v_mfma_f32_16x16x32_bf16 v[76:79], v[154:157], v[216:219], v[76:79]
	v_mfma_f32_16x16x32_bf16 v[72:75], v[162:165], v[216:219], v[72:75]
	v_mfma_f32_16x16x32_bf16 v[116:119], v[166:169], v[182:185], v[116:119]
	v_mfma_f32_16x16x32_bf16 v[112:115], v[174:177], v[182:185], v[112:115]
	v_mfma_f32_16x16x32_bf16 v[100:103], v[166:169], v[196:199], v[100:103]
	v_mfma_f32_16x16x32_bf16 v[96:99], v[174:177], v[196:199], v[96:99]
	v_mfma_f32_16x16x32_bf16 v[84:87], v[166:169], v[204:207], v[84:87]
	v_mfma_f32_16x16x32_bf16 v[80:83], v[174:177], v[204:207], v[80:83]
	v_mfma_f32_16x16x32_bf16 v[68:71], v[166:169], v[212:215], v[68:71]
	v_mfma_f32_16x16x32_bf16 v[64:67], v[174:177], v[212:215], v[64:67]
	v_mfma_f32_16x16x32_bf16 v[116:119], v[170:173], v[192:195], v[116:119]
	v_mfma_f32_16x16x32_bf16 v[112:115], v[178:181], v[192:195], v[112:115]
	v_mfma_f32_16x16x32_bf16 v[100:103], v[170:173], v[200:203], v[100:103]
	v_mfma_f32_16x16x32_bf16 v[96:99], v[178:181], v[200:203], v[96:99]
	v_mfma_f32_16x16x32_bf16 v[84:87], v[170:173], v[208:211], v[84:87]
	v_mfma_f32_16x16x32_bf16 v[80:83], v[178:181], v[208:211], v[80:83]
	v_mfma_f32_16x16x32_bf16 v[68:71], v[170:173], v[216:219], v[68:71]
	v_mfma_f32_16x16x32_bf16 v[64:67], v[178:181], v[216:219], v[64:67]
	s_setprio 0
	s_barrier
; #define PG8_STAGE(bufoff, gbase, voff) do { _Pragma("unroll") for (int _i = 0; _i < 2; ++_i) \
;         __builtin_amdgcn_global_load_lds((const unsigned*)((const char*)(gbase) + (voff)[_i]), (PG8_LAS unsigned*)(lds + (bufoff) + ldsw + _i * 8192), 16, 0, 0); } while (0)
; #define PG8_LDA(dst, b, h) do { _Pragma("unroll") for (int m = 0; m < 4; ++m) _Pragma("unroll") for (int k = 0; k < 2; ++k) dst[m][k] = *(const PG8_LAS bf16x8*)(lds + PG8_SA(b, h) + aoff + m * 2048 + k * 1024); } while (0)
; #define PG8_LDB(dst, b, h) do { _Pragma("unroll") for (int n = 0; n < 2; ++n) _Pragma("unroll") for (int k = 0; k < 2; ++k) dst[n][k] = *(const PG8_LAS bf16x8*)(lds + PG8_SB(b, h) + boff + n * 2048 + k * 1024); } while (0)
; #define PG8_MMA(ai, bj, At, Bt) do { __builtin_amdgcn_s_setprio(1); _Pragma("unroll") for (int m = 0; m < 4; ++m) _Pragma("unroll") for (int n = 0; n < 2; ++n) _Pragma("unroll") for (int k = 0; k < 2; ++k) \
;         acc[ai][bj][m][n] = __builtin_amdgcn_mfma_f32_16x16x32_bf16(Bt[n][k], At[m][k], acc[ai][bj][m][n], 0, 0, 0); __builtin_amdgcn_s_setprio(0); } while (0)
; #define PG8_WAIT_V(n) asm volatile("s_waitcnt vmcnt(" #n ")" ::: "memory")
; #define PG8_WAIT_L(n) asm volatile("s_waitcnt lgkmcnt(" #n ")" ::: "memory")
; #define PG8_BAR __builtin_amdgcn_s_barrier()
; #define PG8_SCHED __builtin_amdgcn_sched_barrier(0)
; template <class Epi, class Sched, bool ALIGN_EPI = false, bool SP2 = false>
; __device__ __forceinline__ void gemm_phase(PG8_LAS unsigned char* lds, const Gemm g, const Sched& S, const Epi& E) {
;     ...
;             PG8_LDB(B0, 0, 0); PG8_LDB(B1, 0, 1); PG8_SCHED; PG8_LDA(At, 0, 0); PG8_STAGE(PG8_SA(1, 1), a1 + hstep, voffA);
;             PG8_WAIT_V(8); PG8_WAIT_L(0); PG8_BAR; PG8_MMA(0, 0, At, B0); PG8_MMA(0, 1, At, B1); PG8_BAR; PG8_SCHED;
;     ...
;             PG8_LDA(At, 1, 1); PG8_STAGE(PG8_SB(1, 0), b3, voffB); PG8_STAGE(PG8_SB(1, 1), b3 + hstep, voffB); PG8_STAGE(PG8_SA(1, 0), a3, voffA);
;             PG8_WAIT_V(8); PG8_WAIT_L(0); PG8_BAR; PG8_MMA(1, 0, At, B0); PG8_MMA(1, 1, At, B1); PG8_BAR; PG8_SCHED;
	s_add_i32 s30, s55, s35
	v_lshl_add_u64 v[186:187], v[186:187], 0, s[4:5]
	s_mov_b32 m0, s30
	ds_read_b128 v[182:185], v149 offset:49152
	ds_read_b128 v[192:195], v149 offset:50176
	ds_read_b128 v[196:199], v149 offset:51200
	ds_read_b128 v[200:203], v149 offset:52224
	ds_read_b128 v[204:207], v149 offset:53248
	ds_read_b128 v[208:211], v149 offset:54272
	ds_read_b128 v[212:215], v149 offset:55296
	ds_read_b128 v[216:219], v149 offset:56320
	global_load_lds_dwordx4 v[186:187], off
	s_add_i32 m0, s30, 0x2000
	s_add_u32 s24, s24, 0x40080
	v_lshl_add_u64 v[186:187], v[220:221], 0, s[4:5]
	s_addc_u32 s25, s25, 0
	s_add_i32 s30, s56, s35
	global_load_lds_dwordx4 v[186:187], off
	s_mov_b32 m0, s30
	s_nop 0
	global_load_lds_dwordx4 v132, s[24:25]
	s_add_i32 m0, s30, 0x2000
	s_nop 0
	global_load_lds_dwordx4 v128, s[24:25]
	v_lshl_add_u64 v[186:187], v[222:223], 0, s[4:5]
	s_mov_b32 m0, s42
	s_nop 0
	global_load_lds_dwordx4 v[186:187], off
	v_lshl_add_u64 v[186:187], v[224:225], 0, s[4:5]
	s_mov_b32 m0, s43
	s_nop 0
	global_load_lds_dwordx4 v[186:187], off
	s_waitcnt vmcnt(8)
	s_waitcnt lgkmcnt(0)
	s_barrier
	s_setprio 1
	v_mfma_f32_16x16x32_bf16 v[60:63], v[150:153], v[182:185], v[60:63]
	v_mfma_f32_16x16x32_bf16 v[56:59], v[158:161], v[182:185], v[56:59]
	v_mfma_f32_16x16x32_bf16 v[44:47], v[150:153], v[196:199], v[44:47]
	v_mfma_f32_16x16x32_bf16 v[40:43], v[158:161], v[196:199], v[40:43]
	v_mfma_f32_16x16x32_bf16 v[28:31], v[150:153], v[204:207], v[28:31]
	v_mfma_f32_16x16x32_bf16 v[24:27], v[158:161], v[204:207], v[24:27]
	v_mfma_f32_16x16x32_bf16 v[12:15], v[150:153], v[212:215], v[12:15]
	v_mfma_f32_16x16x32_bf16 v[8:11], v[158:161], v[212:215], v[8:11]
	v_mfma_f32_16x16x32_bf16 v[60:63], v[154:157], v[192:195], v[60:63]
	v_mfma_f32_16x16x32_bf16 v[56:59], v[162:165], v[192:195], v[56:59]
	v_mfma_f32_16x16x32_bf16 v[44:47], v[154:157], v[200:203], v[44:47]
	v_mfma_f32_16x16x32_bf16 v[40:43], v[162:165], v[200:203], v[40:43]
	v_mfma_f32_16x16x32_bf16 v[28:31], v[154:157], v[208:211], v[28:31]
	v_mfma_f32_16x16x32_bf16 v[24:27], v[162:165], v[208:211], v[24:27]
	v_mfma_f32_16x16x32_bf16 v[12:15], v[154:157], v[216:219], v[12:15]
	v_mfma_f32_16x16x32_bf16 v[8:11], v[162:165], v[216:219], v[8:11]
	v_mfma_f32_16x16x32_bf16 v[52:55], v[166:169], v[182:185], v[52:55]
	v_mfma_f32_16x16x32_bf16 v[48:51], v[174:177], v[182:185], v[48:51]
	v_mfma_f32_16x16x32_bf16 v[36:39], v[166:169], v[196:199], v[36:39]
	v_mfma_f32_16x16x32_bf16 v[32:35], v[174:177], v[196:199], v[32:35]
	v_mfma_f32_16x16x32_bf16 v[20:23], v[166:169], v[204:207], v[20:23]
	v_mfma_f32_16x16x32_bf16 v[16:19], v[174:177], v[204:207], v[16:19]
	v_mfma_f32_16x16x32_bf16 v[4:7], v[166:169], v[212:215], v[4:7]
	v_mfma_f32_16x16x32_bf16 v[0:3], v[174:177], v[212:215], v[0:3]
	v_mfma_f32_16x16x32_bf16 v[52:55], v[170:173], v[192:195], v[52:55]
	v_mfma_f32_16x16x32_bf16 v[48:51], v[178:181], v[192:195], v[48:51]
	v_mfma_f32_16x16x32_bf16 v[36:39], v[170:173], v[200:203], v[36:39]
	v_mfma_f32_16x16x32_bf16 v[32:35], v[178:181], v[200:203], v[32:35]
	v_mfma_f32_16x16x32_bf16 v[20:23], v[170:173], v[208:211], v[20:23]
	v_mfma_f32_16x16x32_bf16 v[16:19], v[178:181], v[208:211], v[16:19]
	v_mfma_f32_16x16x32_bf16 v[4:7], v[170:173], v[216:219], v[4:7]
	v_mfma_f32_16x16x32_bf16 v[0:3], v[178:181], v[216:219], v[0:3]
	s_setprio 0
	s_barrier
	s_add_i32 s54, s54, 2
	s_add_u32 s22, s22, 0x100
	s_addc_u32 s23, s23, 0
	s_add_u32 s52, s52, 0x100
	s_addc_u32 s53, s53, 0
	s_branch .LBB0_192
.Lp1_plain:
	ds_read_b128 v[150:153], v147
	ds_read_b128 v[154:157], v147 offset:1024
	ds_read_b128 v[158:161], v147 offset:2048
	ds_read_b128 v[162:165], v147 offset:3072
	ds_read_b128 v[166:169], v148
	ds_read_b128 v[170:173], v148 offset:1024
	ds_read_b128 v[174:177], v148 offset:2048
	ds_read_b128 v[178:181], v148 offset:3072
	s_add_u32 s24, s22, 0xfffc0080
	s_addc_u32 s25, s23, -1
	s_cmp_eq_u32 s54, 12
	s_cselect_b32 s31, s15, s25
	s_cselect_b32 s30, s50, s24
	s_cselect_b32 s25, s9, s53
	s_cselect_b32 s24, s51, s52
	s_add_i32 m0, s21, 0xc000
	ds_read_b128 v[182:185], v149
	ds_read_b128 v[192:195], v149 offset:1024
	ds_read_b128 v[196:199], v149 offset:2048
	ds_read_b128 v[200:203], v149 offset:3072
	ds_read_b128 v[204:207], v149 offset:4096
	ds_read_b128 v[208:211], v149 offset:5120
	ds_read_b128 v[212:215], v149 offset:6144
	ds_read_b128 v[216:219], v149 offset:7168
	global_load_lds_dwordx4 v136, s[22:23]
	s_add_i32 m0, s21, 0xe000
	s_nop 0
	global_load_lds_dwordx4 v138, s[22:23]
	s_waitcnt vmcnt(16)
	s_waitcnt lgkmcnt(0)
	s_barrier
	s_setprio 1
	v_mfma_f32_16x16x32_bf16 v[124:127], v[150:153], v[182:185], 0
	v_mfma_f32_16x16x32_bf16 v[120:123], v[158:161], v[182:185], 0
	v_mfma_f32_16x16x32_bf16 v[108:111], v[150:153], v[196:199], 0
	v_mfma_f32_16x16x32_bf16 v[104:107], v[158:161], v[196:199], 0
	v_mfma_f32_16x16x32_bf16 v[92:95], v[150:153], v[204:207], 0
	v_mfma_f32_16x16x32_bf16 v[88:91], v[158:161], v[204:207], 0
	v_mfma_f32_16x16x32_bf16 v[76:79], v[150:153], v[212:215], 0
	v_mfma_f32_16x16x32_bf16 v[72:75], v[158:161], v[212:215], 0
	v_mfma_f32_16x16x32_bf16 v[124:127], v[154:157], v[192:195], v[124:127]
	v_mfma_f32_16x16x32_bf16 v[120:123], v[162:165], v[192:195], v[120:123]
	v_mfma_f32_16x16x32_bf16 v[108:111], v[154:157], v[200:203], v[108:111]
	v_mfma_f32_16x16x32_bf16 v[104:107], v[162:165], v[200:203], v[104:107]
	v_mfma_f32_16x16x32_bf16 v[92:95], v[154:157], v[208:211], v[92:95]
	v_mfma_f32_16x16x32_bf16 v[88:91], v[162:165], v[208:211], v[88:91]
	v_mfma_f32_16x16x32_bf16 v[76:79], v[154:157], v[216:219], v[76:79]
	v_mfma_f32_16x16x32_bf16 v[72:75], v[162:165], v[216:219], v[72:75]
	v_mfma_f32_16x16x32_bf16 v[116:119], v[166:169], v[182:185], 0
	v_mfma_f32_16x16x32_bf16 v[112:115], v[174:177], v[182:185], 0
	v_mfma_f32_16x16x32_bf16 v[100:103], v[166:169], v[196:199], 0
	v_mfma_f32_16x16x32_bf16 v[96:99], v[174:177], v[196:199], 0
	v_mfma_f32_16x16x32_bf16 v[84:87], v[166:169], v[204:207], 0
	v_mfma_f32_16x16x32_bf16 v[80:83], v[174:177], v[204:207], 0
	v_mfma_f32_16x16x32_bf16 v[68:71], v[166:169], v[212:215], 0
	v_mfma_f32_16x16x32_bf16 v[64:67], v[174:177], v[212:215], 0
	v_mfma_f32_16x16x32_bf16 v[116:119], v[170:173], v[192:195], v[116:119]
	v_mfma_f32_16x16x32_bf16 v[112:115], v[178:181], v[192:195], v[112:115]
	v_mfma_f32_16x16x32_bf16 v[100:103], v[170:173], v[200:203], v[100:103]
	v_mfma_f32_16x16x32_bf16 v[96:99], v[178:181], v[200:203], v[96:99]
	v_mfma_f32_16x16x32_bf16 v[84:87], v[170:173], v[208:211], v[84:87]
	v_mfma_f32_16x16x32_bf16 v[80:83], v[178:181], v[208:211], v[80:83]
	v_mfma_f32_16x16x32_bf16 v[68:71], v[170:173], v[216:219], v[68:71]
	v_mfma_f32_16x16x32_bf16 v[64:67], v[178:181], v[216:219], v[64:67]
	s_setprio 0
	s_barrier
; #define PG8_STAGE(bufoff, gbase, voff) do { _Pragma("unroll") for (int _i = 0; _i < 2; ++_i) \
;         __builtin_amdgcn_global_load_lds((const unsigned*)((const char*)(gbase) + (voff)[_i]), (PG8_LAS unsigned*)(lds + (bufoff) + ldsw + _i * 8192), 16, 0, 0); } while (0)
; #define PG8_LDA(dst, b, h) do { _Pragma("unroll") for (int m = 0; m < 4; ++m) _Pragma("unroll") for (int k = 0; k < 2; ++k) dst[m][k] = *(const PG8_LAS bf16x8*)(lds + PG8_SA(b, h) + aoff + m * 2048 + k * 1024); } while (0)
; #define PG8_LDB(dst, b, h) do { _Pragma("unroll") for (int n = 0; n < 2; ++n) _Pragma("unroll") for (int k = 0; k < 2; ++k) dst[n][k] = *(const PG8_LAS bf16x8*)(lds + PG8_SB(b, h) + boff + n * 2048 + k * 1024); } while (0)
; #define PG8_MMA(ai, bj, At, Bt) do { __builtin_amdgcn_s_setprio(1); _Pragma("unroll") for (int m = 0; m < 4; ++m) _Pragma("unroll") for (int n = 0; n < 2; ++n) _Pragma("unroll") for (int k = 0; k < 2; ++k) \
;         acc[ai][bj][m][n] = __builtin_amdgcn_mfma_f32_16x16x32_bf16(Bt[n][k], At[m][k], acc[ai][bj][m][n], 0, 0, 0); __builtin_amdgcn_s_setprio(0); } while (0)
; #define PG8_WAIT_V(n) asm volatile("s_waitcnt vmcnt(" #n ")" ::: "memory")
; #define PG8_WAIT_L(n) asm volatile("s_waitcnt lgkmcnt(" #n ")" ::: "memory")
; #define PG8_BAR __builtin_amdgcn_s_barrier()
; #define PG8_SCHED __builtin_amdgcn_sched_barrier(0)
; template <class Epi, class Sched, bool ALIGN_EPI = false, bool SP2 = false>
; __device__ __forceinline__ void gemm_phase(PG8_LAS unsigned char* lds, const Gemm g, const Sched& S, const Epi& E) {
;     ...
;             PG8_LDA(At, 0, 1); PG8_STAGE(PG8_SB(0, 0), b2, voffB); PG8_STAGE(PG8_SB(0, 1), b2 + hstep, voffB); PG8_STAGE(PG8_SA(0, 0), a2, voffA);
;             PG8_WAIT_V(8); PG8_WAIT_L(0); PG8_BAR; PG8_MMA(1, 0, At, B0); PG8_MMA(1, 1, At, B1); PG8_BAR; PG8_SCHED;
;             PG8_LDB(B0, 1, 0); PG8_LDB(B1, 1, 1); PG8_SCHED; PG8_LDA(At, 1, 0); PG8_STAGE(PG8_SA(0, 1), a2 + hstep, voffA);
;             PG8_WAIT_V(8); PG8_WAIT_L(0); PG8_BAR; PG8_MMA(0, 0, At, B0); PG8_MMA(0, 1, At, B1); PG8_BAR; PG8_SCHED;
	s_add_i32 s55, s46, s35
	v_lshl_add_u64 v[186:187], s[24:25], 0, v[132:133]
	s_mov_b32 m0, s55
	ds_read_b128 v[182:185], v149 offset:16384
	ds_read_b128 v[192:195], v149 offset:17408
	ds_read_b128 v[196:199], v149 offset:18432
	ds_read_b128 v[200:203], v149 offset:19456
	ds_read_b128 v[204:207], v149 offset:20480
	ds_read_b128 v[208:211], v149 offset:21504
	ds_read_b128 v[212:215], v149 offset:22528
	ds_read_b128 v[216:219], v149 offset:23552
	global_load_lds_dwordx4 v[186:187], off
	s_add_i32 m0, s55, 0x2000
	s_add_u32 s56, s24, 0x40000
	v_lshl_add_u64 v[220:221], s[24:25], 0, v[128:129]
	s_addc_u32 s57, s25, 0
	s_add_i32 s55, s47, s35
	global_load_lds_dwordx4 v[220:221], off
	s_mov_b32 m0, s55
	v_lshl_add_u64 v[224:225], s[30:31], 0, v[130:131]
	global_load_lds_dwordx4 v132, s[56:57]
	s_add_i32 m0, s55, 0x2000
	s_nop 0
	global_load_lds_dwordx4 v128, s[56:57]
	v_lshl_add_u64 v[222:223], s[30:31], 0, v[134:135]
	s_mov_b32 m0, s21
	s_nop 0
	global_load_lds_dwordx4 v[222:223], off
	s_mov_b32 m0, s38
	s_nop 0
	global_load_lds_dwordx4 v[224:225], off
	s_waitcnt vmcnt(16)
	s_waitcnt lgkmcnt(0)
	s_barrier
	s_setprio 1
	v_mfma_f32_16x16x32_bf16 v[60:63], v[150:153], v[182:185], 0
	v_mfma_f32_16x16x32_bf16 v[56:59], v[158:161], v[182:185], 0
	v_mfma_f32_16x16x32_bf16 v[44:47], v[150:153], v[196:199], 0
	v_mfma_f32_16x16x32_bf16 v[40:43], v[158:161], v[196:199], 0
	v_mfma_f32_16x16x32_bf16 v[28:31], v[150:153], v[204:207], 0
	v_mfma_f32_16x16x32_bf16 v[24:27], v[158:161], v[204:207], 0
	v_mfma_f32_16x16x32_bf16 v[12:15], v[150:153], v[212:215], 0
	v_mfma_f32_16x16x32_bf16 v[8:11], v[158:161], v[212:215], 0
	v_mfma_f32_16x16x32_bf16 v[60:63], v[154:157], v[192:195], v[60:63]
	v_mfma_f32_16x16x32_bf16 v[56:59], v[162:165], v[192:195], v[56:59]
	v_mfma_f32_16x16x32_bf16 v[44:47], v[154:157], v[200:203], v[44:47]
	v_mfma_f32_16x16x32_bf16 v[40:43], v[162:165], v[200:203], v[40:43]
	v_mfma_f32_16x16x32_bf16 v[28:31], v[154:157], v[208:211], v[28:31]
	v_mfma_f32_16x16x32_bf16 v[24:27], v[162:165], v[208:211], v[24:27]
	v_mfma_f32_16x16x32_bf16 v[12:15], v[154:157], v[216:219], v[12:15]
	v_mfma_f32_16x16x32_bf16 v[8:11], v[162:165], v[216:219], v[8:11]
	v_mfma_f32_16x16x32_bf16 v[52:55], v[166:169], v[182:185], 0
	v_mfma_f32_16x16x32_bf16 v[48:51], v[174:177], v[182:185], 0
	v_mfma_f32_16x16x32_bf16 v[36:39], v[166:169], v[196:199], 0
	v_mfma_f32_16x16x32_bf16 v[32:35], v[174:177], v[196:199], 0
	v_mfma_f32_16x16x32_bf16 v[20:23], v[166:169], v[204:207], 0
	v_mfma_f32_16x16x32_bf16 v[16:19], v[174:177], v[204:207], 0
	v_mfma_f32_16x16x32_bf16 v[4:7], v[166:169], v[212:215], 0
	v_mfma_f32_16x16x32_bf16 v[0:3], v[174:177], v[212:215], 0
	v_mfma_f32_16x16x32_bf16 v[52:55], v[170:173], v[192:195], v[52:55]
	v_mfma_f32_16x16x32_bf16 v[48:51], v[178:181], v[192:195], v[48:51]
	v_mfma_f32_16x16x32_bf16 v[36:39], v[170:173], v[200:203], v[36:39]
	v_mfma_f32_16x16x32_bf16 v[32:35], v[178:181], v[200:203], v[32:35]
	v_mfma_f32_16x16x32_bf16 v[20:23], v[170:173], v[208:211], v[20:23]
	v_mfma_f32_16x16x32_bf16 v[16:19], v[178:181], v[208:211], v[16:19]
	v_mfma_f32_16x16x32_bf16 v[4:7], v[170:173], v[216:219], v[4:7]
	v_mfma_f32_16x16x32_bf16 v[0:3], v[178:181], v[216:219], v[0:3]
	s_setprio 0
	s_barrier
	s_add_i32 s55, 0, 0x18000
	s_add_i32 s56, 0, 0x1c000
	v_add_u32_e32 v162, s55, v145
	v_add_u32_e32 v178, s56, v145
	ds_read_b128 v[150:153], v162
	ds_read_b128 v[154:157], v162 offset:1024
	ds_read_b128 v[158:161], v162 offset:2048
	ds_read_b128 v[162:165], v162 offset:3072
	ds_read_b128 v[166:169], v178
	ds_read_b128 v[170:173], v178 offset:1024
	ds_read_b128 v[174:177], v178 offset:2048
	ds_read_b128 v[178:181], v178 offset:3072
	s_add_u32 s30, s30, 0x40000
	s_addc_u32 s31, s31, 0
	s_mov_b32 m0, s39
	ds_read_b128 v[182:185], v149 offset:32768
	ds_read_b128 v[192:195], v149 offset:33792
	ds_read_b128 v[196:199], v149 offset:34816
	ds_read_b128 v[200:203], v149 offset:35840
	ds_read_b128 v[204:207], v149 offset:36864
	ds_read_b128 v[208:211], v149 offset:37888
	ds_read_b128 v[212:215], v149 offset:38912
	ds_read_b128 v[216:219], v149 offset:39936
	global_load_lds_dwordx4 v134, s[30:31]
	v_lshl_add_u64 v[226:227], s[30:31], 0, v[130:131]
	s_mov_b32 m0, s40
	s_nop 0
	global_load_lds_dwordx4 v[226:227], off
	s_waitcnt vmcnt(8)
	s_waitcnt lgkmcnt(0)
	s_barrier
	s_setprio 1
	v_mfma_f32_16x16x32_bf16 v[124:127], v[150:153], v[182:185], v[124:127]
	v_mfma_f32_16x16x32_bf16 v[120:123], v[158:161], v[182:185], v[120:123]
	v_mfma_f32_16x16x32_bf16 v[108:111], v[150:153], v[196:199], v[108:111]
	v_mfma_f32_16x16x32_bf16 v[104:107], v[158:161], v[196:199], v[104:107]
	v_mfma_f32_16x16x32_bf16 v[92:95], v[150:153], v[204:207], v[92:95]
	v_mfma_f32_16x16x32_bf16 v[88:91], v[158:161], v[204:207], v[88:91]
	v_mfma_f32_16x16x32_bf16 v[76:79], v[150:153], v[212:215], v[76:79]
	v_mfma_f32_16x16x32_bf16 v[72:75], v[158:161], v[212:215], v[72:75]
	v_mfma_f32_16x16x32_bf16 v[124:127], v[154:157], v[192:195], v[124:127]
	v_mfma_f32_16x16x32_bf16 v[120:123], v[162:165], v[192:195], v[120:123]
	v_mfma_f32_16x16x32_bf16 v[108:111], v[154:157], v[200:203], v[108:111]
	v_mfma_f32_16x16x32_bf16 v[104:107], v[162:165], v[200:203], v[104:107]
	v_mfma_f32_16x16x32_bf16 v[92:95], v[154:157], v[208:211], v[92:95]
	v_mfma_f32_16x16x32_bf16 v[88:91], v[162:165], v[208:211], v[88:91]
	v_mfma_f32_16x16x32_bf16 v[76:79], v[154:157], v[216:219], v[76:79]
	v_mfma_f32_16x16x32_bf16 v[72:75], v[162:165], v[216:219], v[72:75]
	v_mfma_f32_16x16x32_bf16 v[116:119], v[166:169], v[182:185], v[116:119]
	v_mfma_f32_16x16x32_bf16 v[112:115], v[174:177], v[182:185], v[112:115]
	v_mfma_f32_16x16x32_bf16 v[100:103], v[166:169], v[196:199], v[100:103]
	v_mfma_f32_16x16x32_bf16 v[96:99], v[174:177], v[196:199], v[96:99]
	v_mfma_f32_16x16x32_bf16 v[84:87], v[166:169], v[204:207], v[84:87]
	v_mfma_f32_16x16x32_bf16 v[80:83], v[174:177], v[204:207], v[80:83]
	v_mfma_f32_16x16x32_bf16 v[68:71], v[166:169], v[212:215], v[68:71]
	v_mfma_f32_16x16x32_bf16 v[64:67], v[174:177], v[212:215], v[64:67]
	v_mfma_f32_16x16x32_bf16 v[116:119], v[170:173], v[192:195], v[116:119]
	v_mfma_f32_16x16x32_bf16 v[112:115], v[178:181], v[192:195], v[112:115]
	v_mfma_f32_16x16x32_bf16 v[100:103], v[170:173], v[200:203], v[100:103]
	v_mfma_f32_16x16x32_bf16 v[96:99], v[178:181], v[200:203], v[96:99]
	v_mfma_f32_16x16x32_bf16 v[84:87], v[170:173], v[208:211], v[84:87]
	v_mfma_f32_16x16x32_bf16 v[80:83], v[178:181], v[208:211], v[80:83]
	v_mfma_f32_16x16x32_bf16 v[68:71], v[170:173], v[216:219], v[68:71]
	v_mfma_f32_16x16x32_bf16 v[64:67], v[178:181], v[216:219], v[64:67]
	s_setprio 0
	s_barrier
; #define PG8_STAGE(bufoff, gbase, voff) do { _Pragma("unroll") for (int _i = 0; _i < 2; ++_i) \
;         __builtin_amdgcn_global_load_lds((const unsigned*)((const char*)(gbase) + (voff)[_i]), (PG8_LAS unsigned*)(lds + (bufoff) + ldsw + _i * 8192), 16, 0, 0); } while (0)
; #define PG8_LDA(dst, b, h) do { _Pragma("unroll") for (int m = 0; m < 4; ++m) _Pragma("unroll") for (int k = 0; k < 2; ++k) dst[m][k] = *(const PG8_LAS bf16x8*)(lds + PG8_SA(b, h) + aoff + m * 2048 + k * 1024); } while (0)
; #define PG8_LDB(dst, b, h) do { _Pragma("unroll") for (int n = 0; n < 2; ++n) _Pragma("unroll") for (int k = 0; k < 2; ++k) dst[n][k] = *(const PG8_LAS bf16x8*)(lds + PG8_SB(b, h) + boff + n * 2048 + k * 1024); } while (0)
; template <class Epi, class Sched, bool ALIGN_EPI = false, bool SP2 = false>
; __device__ __forceinline__ void gemm_phase(PG8_LAS unsigned char* lds, const Gemm g, const Sched& S, const Epi& E) {
;     ...
;         for (int t = 0; t < nt; t += 2) {
;             const bool last = (t == nt - 2);
;             const char* a1 = cA + (size_t)(t + 1) * kstep;
;             const char* a2 = last ? nA : cA + (size_t)(t + 2) * kstep; const char* b2 = last ? nB : cB + (size_t)(t + 2) * kstep;
;             const char* a3 = a2 + kstep; const char* b3 = b2 + kstep;
;             if (last && has_next) S.a_ready(nxt);
;             if constexpr (SP2) {
;             PG8_LDB(B0, 0, 0); PG8_LDB(B1, 0, 1); PG8_SCHED; PG8_LDA(At, 0, 0); PG8_STAGE(PG8_SA(1, 1), a1 + hstep, voffA);
;             PG8_WAIT_V(8); PG8_WAIT_L(0); PG8_BAR; PG8_MMA(0, 0, At, B0); PG8_MMA(0, 1, At, B1); PG8_BAR; PG8_SCHED;
;             PG8_LDA(At, 0, 1); PG8_STAGE(PG8_SB(0, 0), b2, voffB); PG8_STAGE(PG8_SB(0, 1), b2 + hstep, voffB); PG8_STAGE(PG8_SA(0, 0), a2, voffA);
;             PG8_WAIT_V(8); PG8_WAIT_L(0); PG8_BAR; PG8_MMA(1, 0, At, B0); PG8_MMA(1, 1, At, B1); PG8_BAR; PG8_SCHED;
;             PG8_LDB(B0, 1, 0); PG8_LDB(B1, 1, 1); PG8_SCHED; PG8_LDA(At, 1, 0); PG8_STAGE(PG8_SA(0, 1), a2 + hstep, voffA);
;             PG8_WAIT_V(8); PG8_WAIT_L(0); PG8_BAR; PG8_MMA(0, 0, At, B0); PG8_MMA(0, 1, At, B1); PG8_BAR; PG8_SCHED;
;             PG8_LDA(At, 1, 1); PG8_STAGE(PG8_SB(1, 0), b3, voffB); PG8_STAGE(PG8_SB(1, 1), b3 + hstep, voffB); PG8_STAGE(PG8_SA(1, 0), a3, voffA);
;             PG8_WAIT_V(8); PG8_WAIT_L(0); PG8_BAR; PG8_MMA(1, 0, At, B0); PG8_MMA(1, 1, At, B1); PG8_BAR; PG8_SCHED;
	s_add_i32 s30, s55, s35
	v_lshl_add_u64 v[186:187], v[186:187], 0, s[4:5]
	s_mov_b32 m0, s30
	ds_read_b128 v[182:185], v149 offset:49152
	ds_read_b128 v[192:195], v149 offset:50176
	ds_read_b128 v[196:199], v149 offset:51200
	ds_read_b128 v[200:203], v149 offset:52224
	ds_read_b128 v[204:207], v149 offset:53248
	ds_read_b128 v[208:211], v149 offset:54272
	ds_read_b128 v[212:215], v149 offset:55296
	ds_read_b128 v[216:219], v149 offset:56320
	global_load_lds_dwordx4 v[186:187], off
	s_add_i32 m0, s30, 0x2000
	s_add_u32 s24, s24, 0x40080
	v_lshl_add_u64 v[186:187], v[220:221], 0, s[4:5]
	s_addc_u32 s25, s25, 0
	s_add_i32 s30, s56, s35
	global_load_lds_dwordx4 v[186:187], off
	s_mov_b32 m0, s30
	s_nop 0
	global_load_lds_dwordx4 v132, s[24:25]
	s_add_i32 m0, s30, 0x2000
	s_nop 0
	global_load_lds_dwordx4 v128, s[24:25]
	v_lshl_add_u64 v[186:187], v[222:223], 0, s[4:5]
	s_mov_b32 m0, s42
	s_nop 0
	global_load_lds_dwordx4 v[186:187], off
	v_lshl_add_u64 v[186:187], v[224:225], 0, s[4:5]
	s_mov_b32 m0, s43
	s_nop 0
	global_load_lds_dwordx4 v[186:187], off
	s_waitcnt vmcnt(8)
	s_waitcnt lgkmcnt(0)
	s_barrier
	s_setprio 1
	v_mfma_f32_16x16x32_bf16 v[60:63], v[150:153], v[182:185], v[60:63]
	v_mfma_f32_16x16x32_bf16 v[56:59], v[158:161], v[182:185], v[56:59]
	v_mfma_f32_16x16x32_bf16 v[44:47], v[150:153], v[196:199], v[44:47]
	v_mfma_f32_16x16x32_bf16 v[40:43], v[158:161], v[196:199], v[40:43]
	v_mfma_f32_16x16x32_bf16 v[28:31], v[150:153], v[204:207], v[28:31]
	v_mfma_f32_16x16x32_bf16 v[24:27], v[158:161], v[204:207], v[24:27]
	v_mfma_f32_16x16x32_bf16 v[12:15], v[150:153], v[212:215], v[12:15]
	v_mfma_f32_16x16x32_bf16 v[8:11], v[158:161], v[212:215], v[8:11]
	v_mfma_f32_16x16x32_bf16 v[60:63], v[154:157], v[192:195], v[60:63]
	v_mfma_f32_16x16x32_bf16 v[56:59], v[162:165], v[192:195], v[56:59]
	v_mfma_f32_16x16x32_bf16 v[44:47], v[154:157], v[200:203], v[44:47]
	v_mfma_f32_16x16x32_bf16 v[40:43], v[162:165], v[200:203], v[40:43]
	v_mfma_f32_16x16x32_bf16 v[28:31], v[154:157], v[208:211], v[28:31]
	v_mfma_f32_16x16x32_bf16 v[24:27], v[162:165], v[208:211], v[24:27]
	v_mfma_f32_16x16x32_bf16 v[12:15], v[154:157], v[216:219], v[12:15]
	v_mfma_f32_16x16x32_bf16 v[8:11], v[162:165], v[216:219], v[8:11]
	v_mfma_f32_16x16x32_bf16 v[52:55], v[166:169], v[182:185], v[52:55]
	v_mfma_f32_16x16x32_bf16 v[48:51], v[174:177], v[182:185], v[48:51]
	v_mfma_f32_16x16x32_bf16 v[36:39], v[166:169], v[196:199], v[36:39]
	v_mfma_f32_16x16x32_bf16 v[32:35], v[174:177], v[196:199], v[32:35]
	v_mfma_f32_16x16x32_bf16 v[20:23], v[166:169], v[204:207], v[20:23]
	v_mfma_f32_16x16x32_bf16 v[16:19], v[174:177], v[204:207], v[16:19]
	v_mfma_f32_16x16x32_bf16 v[4:7], v[166:169], v[212:215], v[4:7]
	v_mfma_f32_16x16x32_bf16 v[0:3], v[174:177], v[212:215], v[0:3]
	v_mfma_f32_16x16x32_bf16 v[52:55], v[170:173], v[192:195], v[52:55]
	v_mfma_f32_16x16x32_bf16 v[48:51], v[178:181], v[192:195], v[48:51]
	v_mfma_f32_16x16x32_bf16 v[36:39], v[170:173], v[200:203], v[36:39]
	v_mfma_f32_16x16x32_bf16 v[32:35], v[178:181], v[200:203], v[32:35]
	v_mfma_f32_16x16x32_bf16 v[20:23], v[170:173], v[208:211], v[20:23]
	v_mfma_f32_16x16x32_bf16 v[16:19], v[178:181], v[208:211], v[16:19]
	v_mfma_f32_16x16x32_bf16 v[4:7], v[170:173], v[216:219], v[4:7]
	v_mfma_f32_16x16x32_bf16 v[0:3], v[178:181], v[216:219], v[0:3]
	s_setprio 0
	s_barrier
	s_add_i32 s54, s54, 2
	s_add_u32 s22, s22, 0x100
	s_addc_u32 s23, s23, 0
	s_add_u32 s52, s52, 0x100
	s_addc_u32 s53, s53, 0
.LBB0_192:
	ds_read_b128 v[150:153], v147
	ds_read_b128 v[154:157], v147 offset:1024
	ds_read_b128 v[158:161], v147 offset:2048
	ds_read_b128 v[162:165], v147 offset:3072
	ds_read_b128 v[166:169], v148
	ds_read_b128 v[170:173], v148 offset:1024
	ds_read_b128 v[174:177], v148 offset:2048
	ds_read_b128 v[178:181], v148 offset:3072
	s_add_u32 s24, s22, 0xfffc0080
	s_addc_u32 s25, s23, -1
	s_cmp_eq_u32 s54, 12
	s_cselect_b32 s31, s15, s25
	s_cselect_b32 s30, s50, s24
	s_cselect_b32 s25, s9, s53
	s_cselect_b32 s24, s51, s52
	s_add_i32 m0, s21, 0xc000
	ds_read_b128 v[182:185], v149
	ds_read_b128 v[192:195], v149 offset:1024
	ds_read_b128 v[196:199], v149 offset:2048
	ds_read_b128 v[200:203], v149 offset:3072
	ds_read_b128 v[204:207], v149 offset:4096
	ds_read_b128 v[208:211], v149 offset:5120
	ds_read_b128 v[212:215], v149 offset:6144
	ds_read_b128 v[216:219], v149 offset:7168
	global_load_lds_dwordx4 v136, s[22:23]
	s_add_i32 m0, s21, 0xe000
	s_nop 0
	global_load_lds_dwordx4 v138, s[22:23]
	s_waitcnt vmcnt(8)
	s_waitcnt lgkmcnt(0)
	s_barrier
; #define PG8_STAGE(bufoff, gbase, voff) do { _Pragma("unroll") for (int _i = 0; _i < 2; ++_i) \
;         __builtin_amdgcn_global_load_lds((const unsigned*)((const char*)(gbase) + (voff)[_i]), (PG8_LAS unsigned*)(lds + (bufoff) + ldsw + _i * 8192), 16, 0, 0); } while (0)
; #define PG8_LDA(dst, b, h) do { _Pragma("unroll") for (int m = 0; m < 4; ++m) _Pragma("unroll") for (int k = 0; k < 2; ++k) dst[m][k] = *(const PG8_LAS bf16x8*)(lds + PG8_SA(b, h) + aoff + m * 2048 + k * 1024); } while (0)
; #define PG8_MMA(ai, bj, At, Bt) do { __builtin_amdgcn_s_setprio(1); _Pragma("unroll") for (int m = 0; m < 4; ++m) _Pragma("unroll") for (int n = 0; n < 2; ++n) _Pragma("unroll") for (int k = 0; k < 2; ++k) \
;         acc[ai][bj][m][n] = __builtin_amdgcn_mfma_f32_16x16x32_bf16(Bt[n][k], At[m][k], acc[ai][bj][m][n], 0, 0, 0); __builtin_amdgcn_s_setprio(0); } while (0)
; #define PG8_WAIT_V(n) asm volatile("s_waitcnt vmcnt(" #n ")" ::: "memory")
; #define PG8_WAIT_L(n) asm volatile("s_waitcnt lgkmcnt(" #n ")" ::: "memory")
; #define PG8_BAR __builtin_amdgcn_s_barrier()
; #define PG8_SCHED __builtin_amdgcn_sched_barrier(0)
; template <class Epi, class Sched, bool ALIGN_EPI = false, bool SP2 = false>
; __device__ __forceinline__ void gemm_phase(PG8_LAS unsigned char* lds, const Gemm g, const Sched& S, const Epi& E) {
;     ...
;             PG8_WAIT_V(8); PG8_WAIT_L(0); PG8_BAR; PG8_MMA(0, 0, At, B0); PG8_MMA(0, 1, At, B1); PG8_BAR; PG8_SCHED;
;             PG8_LDA(At, 0, 1); PG8_STAGE(PG8_SB(0, 0), b2, voffB); PG8_STAGE(PG8_SB(0, 1), b2 + hstep, voffB); PG8_STAGE(PG8_SA(0, 0), a2, voffA);
;             PG8_WAIT_V(8); PG8_WAIT_L(0); PG8_BAR; PG8_MMA(1, 0, At, B0); PG8_MMA(1, 1, At, B1); PG8_BAR; PG8_SCHED;
	s_setprio 1
	v_mfma_f32_16x16x32_bf16 v[124:127], v[150:153], v[182:185], v[124:127]
	v_mfma_f32_16x16x32_bf16 v[120:123], v[158:161], v[182:185], v[120:123]
	v_mfma_f32_16x16x32_bf16 v[108:111], v[150:153], v[196:199], v[108:111]
	v_mfma_f32_16x16x32_bf16 v[104:107], v[158:161], v[196:199], v[104:107]
	v_mfma_f32_16x16x32_bf16 v[92:95], v[150:153], v[204:207], v[92:95]
	v_mfma_f32_16x16x32_bf16 v[88:91], v[158:161], v[204:207], v[88:91]
	v_mfma_f32_16x16x32_bf16 v[76:79], v[150:153], v[212:215], v[76:79]
	v_mfma_f32_16x16x32_bf16 v[72:75], v[158:161], v[212:215], v[72:75]
	v_mfma_f32_16x16x32_bf16 v[124:127], v[154:157], v[192:195], v[124:127]
	v_mfma_f32_16x16x32_bf16 v[120:123], v[162:165], v[192:195], v[120:123]
	v_mfma_f32_16x16x32_bf16 v[108:111], v[154:157], v[200:203], v[108:111]
	v_mfma_f32_16x16x32_bf16 v[104:107], v[162:165], v[200:203], v[104:107]
	v_mfma_f32_16x16x32_bf16 v[92:95], v[154:157], v[208:211], v[92:95]
	v_mfma_f32_16x16x32_bf16 v[88:91], v[162:165], v[208:211], v[88:91]
	v_mfma_f32_16x16x32_bf16 v[76:79], v[154:157], v[216:219], v[76:79]
	v_mfma_f32_16x16x32_bf16 v[72:75], v[162:165], v[216:219], v[72:75]
	v_mfma_f32_16x16x32_bf16 v[116:119], v[166:169], v[182:185], v[116:119]
	v_mfma_f32_16x16x32_bf16 v[112:115], v[174:177], v[182:185], v[112:115]
	v_mfma_f32_16x16x32_bf16 v[100:103], v[166:169], v[196:199], v[100:103]
	v_mfma_f32_16x16x32_bf16 v[96:99], v[174:177], v[196:199], v[96:99]
	v_mfma_f32_16x16x32_bf16 v[84:87], v[166:169], v[204:207], v[84:87]
	v_mfma_f32_16x16x32_bf16 v[80:83], v[174:177], v[204:207], v[80:83]
	v_mfma_f32_16x16x32_bf16 v[68:71], v[166:169], v[212:215], v[68:71]
	v_mfma_f32_16x16x32_bf16 v[64:67], v[174:177], v[212:215], v[64:67]
	v_mfma_f32_16x16x32_bf16 v[116:119], v[170:173], v[192:195], v[116:119]
	v_mfma_f32_16x16x32_bf16 v[112:115], v[178:181], v[192:195], v[112:115]
	v_mfma_f32_16x16x32_bf16 v[100:103], v[170:173], v[200:203], v[100:103]
	v_mfma_f32_16x16x32_bf16 v[96:99], v[178:181], v[200:203], v[96:99]
	v_mfma_f32_16x16x32_bf16 v[84:87], v[170:173], v[208:211], v[84:87]
	v_mfma_f32_16x16x32_bf16 v[80:83], v[178:181], v[208:211], v[80:83]
	v_mfma_f32_16x16x32_bf16 v[68:71], v[170:173], v[216:219], v[68:71]
	v_mfma_f32_16x16x32_bf16 v[64:67], v[178:181], v[216:219], v[64:67]
	s_setprio 0
	s_barrier
	s_add_i32 s55, s46, s35
	v_lshl_add_u64 v[186:187], s[24:25], 0, v[132:133]
	s_mov_b32 m0, s55
	ds_read_b128 v[182:185], v149 offset:16384
	ds_read_b128 v[192:195], v149 offset:17408
	ds_read_b128 v[196:199], v149 offset:18432
	ds_read_b128 v[200:203], v149 offset:19456
	ds_read_b128 v[204:207], v149 offset:20480
	ds_read_b128 v[208:211], v149 offset:21504
	ds_read_b128 v[212:215], v149 offset:22528
	ds_read_b128 v[216:219], v149 offset:23552
	global_load_lds_dwordx4 v[186:187], off
	s_add_i32 m0, s55, 0x2000
	s_add_u32 s56, s24, 0x40000
	v_lshl_add_u64 v[220:221], s[24:25], 0, v[128:129]
	s_addc_u32 s57, s25, 0
	s_add_i32 s55, s47, s35
	global_load_lds_dwordx4 v[220:221], off
	s_mov_b32 m0, s55
	v_lshl_add_u64 v[224:225], s[30:31], 0, v[130:131]
	global_load_lds_dwordx4 v132, s[56:57]
	s_add_i32 m0, s55, 0x2000
	s_nop 0
	global_load_lds_dwordx4 v128, s[56:57]
	v_lshl_add_u64 v[222:223], s[30:31], 0, v[134:135]
	s_mov_b32 m0, s21
	s_nop 0
	global_load_lds_dwordx4 v[222:223], off
	s_mov_b32 m0, s38
	s_nop 0
	global_load_lds_dwordx4 v[224:225], off
	s_waitcnt vmcnt(8)
	s_waitcnt lgkmcnt(0)
	s_barrier
	s_setprio 1
	v_mfma_f32_16x16x32_bf16 v[60:63], v[150:153], v[182:185], v[60:63]
	v_mfma_f32_16x16x32_bf16 v[56:59], v[158:161], v[182:185], v[56:59]
	v_mfma_f32_16x16x32_bf16 v[44:47], v[150:153], v[196:199], v[44:47]
	v_mfma_f32_16x16x32_bf16 v[40:43], v[158:161], v[196:199], v[40:43]
	v_mfma_f32_16x16x32_bf16 v[28:31], v[150:153], v[204:207], v[28:31]
	v_mfma_f32_16x16x32_bf16 v[24:27], v[158:161], v[204:207], v[24:27]
	v_mfma_f32_16x16x32_bf16 v[12:15], v[150:153], v[212:215], v[12:15]
	v_mfma_f32_16x16x32_bf16 v[8:11], v[158:161], v[212:215], v[8:11]
	v_mfma_f32_16x16x32_bf16 v[60:63], v[154:157], v[192:195], v[60:63]
	v_mfma_f32_16x16x32_bf16 v[56:59], v[162:165], v[192:195], v[56:59]
	v_mfma_f32_16x16x32_bf16 v[44:47], v[154:157], v[200:203], v[44:47]
	v_mfma_f32_16x16x32_bf16 v[40:43], v[162:165], v[200:203], v[40:43]
	v_mfma_f32_16x16x32_bf16 v[28:31], v[154:157], v[208:211], v[28:31]
	v_mfma_f32_16x16x32_bf16 v[24:27], v[162:165], v[208:211], v[24:27]
	v_mfma_f32_16x16x32_bf16 v[12:15], v[154:157], v[216:219], v[12:15]
	v_mfma_f32_16x16x32_bf16 v[8:11], v[162:165], v[216:219], v[8:11]
	v_mfma_f32_16x16x32_bf16 v[52:55], v[166:169], v[182:185], v[52:55]
	v_mfma_f32_16x16x32_bf16 v[48:51], v[174:177], v[182:185], v[48:51]
	v_mfma_f32_16x16x32_bf16 v[36:39], v[166:169], v[196:199], v[36:39]
	v_mfma_f32_16x16x32_bf16 v[32:35], v[174:177], v[196:199], v[32:35]
	v_mfma_f32_16x16x32_bf16 v[20:23], v[166:169], v[204:207], v[20:23]
	v_mfma_f32_16x16x32_bf16 v[16:19], v[174:177], v[204:207], v[16:19]
	v_mfma_f32_16x16x32_bf16 v[4:7], v[166:169], v[212:215], v[4:7]
	v_mfma_f32_16x16x32_bf16 v[0:3], v[174:177], v[212:215], v[0:3]
	v_mfma_f32_16x16x32_bf16 v[52:55], v[170:173], v[192:195], v[52:55]
	v_mfma_f32_16x16x32_bf16 v[48:51], v[178:181], v[192:195], v[48:51]
	v_mfma_f32_16x16x32_bf16 v[36:39], v[170:173], v[200:203], v[36:39]
	v_mfma_f32_16x16x32_bf16 v[32:35], v[178:181], v[200:203], v[32:35]
	v_mfma_f32_16x16x32_bf16 v[20:23], v[170:173], v[208:211], v[20:23]
	v_mfma_f32_16x16x32_bf16 v[16:19], v[178:181], v[208:211], v[16:19]
	v_mfma_f32_16x16x32_bf16 v[4:7], v[170:173], v[216:219], v[4:7]
	v_mfma_f32_16x16x32_bf16 v[0:3], v[178:181], v[216:219], v[0:3]
	s_setprio 0
	s_barrier
; #define PG8_STAGE(bufoff, gbase, voff) do { _Pragma("unroll") for (int _i = 0; _i < 2; ++_i) \
;         __builtin_amdgcn_global_load_lds((const unsigned*)((const char*)(gbase) + (voff)[_i]), (PG8_LAS unsigned*)(lds + (bufoff) + ldsw + _i * 8192), 16, 0, 0); } while (0)
; #define PG8_LDA(dst, b, h) do { _Pragma("unroll") for (int m = 0; m < 4; ++m) _Pragma("unroll") for (int k = 0; k < 2; ++k) dst[m][k] = *(const PG8_LAS bf16x8*)(lds + PG8_SA(b, h) + aoff + m * 2048 + k * 1024); } while (0)
; #define PG8_LDB(dst, b, h) do { _Pragma("unroll") for (int n = 0; n < 2; ++n) _Pragma("unroll") for (int k = 0; k < 2; ++k) dst[n][k] = *(const PG8_LAS bf16x8*)(lds + PG8_SB(b, h) + boff + n * 2048 + k * 1024); } while (0)
; #define PG8_MMA(ai, bj, At, Bt) do { __builtin_amdgcn_s_setprio(1); _Pragma("unroll") for (int m = 0; m < 4; ++m) _Pragma("unroll") for (int n = 0; n < 2; ++n) _Pragma("unroll") for (int k = 0; k < 2; ++k) \
;         acc[ai][bj][m][n] = __builtin_amdgcn_mfma_f32_16x16x32_bf16(Bt[n][k], At[m][k], acc[ai][bj][m][n], 0, 0, 0); __builtin_amdgcn_s_setprio(0); } while (0)
; #define PG8_WAIT_V(n) asm volatile("s_waitcnt vmcnt(" #n ")" ::: "memory")
; #define PG8_WAIT_L(n) asm volatile("s_waitcnt lgkmcnt(" #n ")" ::: "memory")
; #define PG8_BAR __builtin_amdgcn_s_barrier()
; #define PG8_SCHED __builtin_amdgcn_sched_barrier(0)
; template <class Epi, class Sched, bool ALIGN_EPI = false, bool SP2 = false>
; __device__ __forceinline__ void gemm_phase(PG8_LAS unsigned char* lds, const Gemm g, const Sched& S, const Epi& E) {
;     ...
;             PG8_LDB(B0, 1, 0); PG8_LDB(B1, 1, 1); PG8_SCHED; PG8_LDA(At, 1, 0); PG8_STAGE(PG8_SA(0, 1), a2 + hstep, voffA);
;             PG8_WAIT_V(8); PG8_WAIT_L(0); PG8_BAR; PG8_MMA(0, 0, At, B0); PG8_MMA(0, 1, At, B1); PG8_BAR; PG8_SCHED;
;             PG8_LDA(At, 1, 1); PG8_STAGE(PG8_SB(1, 0), b3, voffB); PG8_STAGE(PG8_SB(1, 1), b3 + hstep, voffB); PG8_STAGE(PG8_SA(1, 0), a3, voffA);
;             PG8_WAIT_V(8); PG8_WAIT_L(0); PG8_BAR; PG8_MMA(1, 0, At, B0); PG8_MMA(1, 1, At, B1); PG8_BAR; PG8_SCHED;
	s_add_i32 s55, 0, 0x18000
	s_add_i32 s56, 0, 0x1c000
	v_add_u32_e32 v162, s55, v145
	v_add_u32_e32 v178, s56, v145
	ds_read_b128 v[150:153], v162
	ds_read_b128 v[154:157], v162 offset:1024
	ds_read_b128 v[158:161], v162 offset:2048
	ds_read_b128 v[162:165], v162 offset:3072
	ds_read_b128 v[166:169], v178
	ds_read_b128 v[170:173], v178 offset:1024
	ds_read_b128 v[174:177], v178 offset:2048
	ds_read_b128 v[178:181], v178 offset:3072
	s_add_u32 s30, s30, 0x40000
	s_addc_u32 s31, s31, 0
	s_mov_b32 m0, s39
	ds_read_b128 v[182:185], v149 offset:32768
	ds_read_b128 v[192:195], v149 offset:33792
	ds_read_b128 v[196:199], v149 offset:34816
	ds_read_b128 v[200:203], v149 offset:35840
	ds_read_b128 v[204:207], v149 offset:36864
	ds_read_b128 v[208:211], v149 offset:37888
	ds_read_b128 v[212:215], v149 offset:38912
	ds_read_b128 v[216:219], v149 offset:39936
	global_load_lds_dwordx4 v134, s[30:31]
	v_lshl_add_u64 v[226:227], s[30:31], 0, v[130:131]
	s_mov_b32 m0, s40
	s_nop 0
	global_load_lds_dwordx4 v[226:227], off
	s_waitcnt vmcnt(8)
	s_waitcnt lgkmcnt(0)
	s_barrier
	s_setprio 1
	v_mfma_f32_16x16x32_bf16 v[124:127], v[150:153], v[182:185], v[124:127]
	v_mfma_f32_16x16x32_bf16 v[120:123], v[158:161], v[182:185], v[120:123]
	v_mfma_f32_16x16x32_bf16 v[108:111], v[150:153], v[196:199], v[108:111]
	v_mfma_f32_16x16x32_bf16 v[104:107], v[158:161], v[196:199], v[104:107]
	v_mfma_f32_16x16x32_bf16 v[92:95], v[150:153], v[204:207], v[92:95]
	v_mfma_f32_16x16x32_bf16 v[88:91], v[158:161], v[204:207], v[88:91]
	v_mfma_f32_16x16x32_bf16 v[76:79], v[150:153], v[212:215], v[76:79]
	v_mfma_f32_16x16x32_bf16 v[72:75], v[158:161], v[212:215], v[72:75]
	v_mfma_f32_16x16x32_bf16 v[124:127], v[154:157], v[192:195], v[124:127]
	v_mfma_f32_16x16x32_bf16 v[120:123], v[162:165], v[192:195], v[120:123]
	v_mfma_f32_16x16x32_bf16 v[108:111], v[154:157], v[200:203], v[108:111]
	v_mfma_f32_16x16x32_bf16 v[104:107], v[162:165], v[200:203], v[104:107]
	v_mfma_f32_16x16x32_bf16 v[92:95], v[154:157], v[208:211], v[92:95]
	v_mfma_f32_16x16x32_bf16 v[88:91], v[162:165], v[208:211], v[88:91]
	v_mfma_f32_16x16x32_bf16 v[76:79], v[154:157], v[216:219], v[76:79]
	v_mfma_f32_16x16x32_bf16 v[72:75], v[162:165], v[216:219], v[72:75]
	v_mfma_f32_16x16x32_bf16 v[116:119], v[166:169], v[182:185], v[116:119]
	v_mfma_f32_16x16x32_bf16 v[112:115], v[174:177], v[182:185], v[112:115]
	v_mfma_f32_16x16x32_bf16 v[100:103], v[166:169], v[196:199], v[100:103]
	v_mfma_f32_16x16x32_bf16 v[96:99], v[174:177], v[196:199], v[96:99]
	v_mfma_f32_16x16x32_bf16 v[84:87], v[166:169], v[204:207], v[84:87]
	v_mfma_f32_16x16x32_bf16 v[80:83], v[174:177], v[204:207], v[80:83]
	v_mfma_f32_16x16x32_bf16 v[68:71], v[166:169], v[212:215], v[68:71]
	v_mfma_f32_16x16x32_bf16 v[64:67], v[174:177], v[212:215], v[64:67]
	v_mfma_f32_16x16x32_bf16 v[116:119], v[170:173], v[192:195], v[116:119]
	v_mfma_f32_16x16x32_bf16 v[112:115], v[178:181], v[192:195], v[112:115]
	v_mfma_f32_16x16x32_bf16 v[100:103], v[170:173], v[200:203], v[100:103]
	v_mfma_f32_16x16x32_bf16 v[96:99], v[178:181], v[200:203], v[96:99]
	v_mfma_f32_16x16x32_bf16 v[84:87], v[170:173], v[208:211], v[84:87]
	v_mfma_f32_16x16x32_bf16 v[80:83], v[178:181], v[208:211], v[80:83]
	v_mfma_f32_16x16x32_bf16 v[68:71], v[170:173], v[216:219], v[68:71]
	v_mfma_f32_16x16x32_bf16 v[64:67], v[178:181], v[216:219], v[64:67]
	s_setprio 0
	s_barrier
	s_add_i32 s30, s55, s35
	v_lshl_add_u64 v[186:187], v[186:187], 0, s[4:5]
	s_mov_b32 m0, s30
	ds_read_b128 v[182:185], v149 offset:49152
	ds_read_b128 v[192:195], v149 offset:50176
	ds_read_b128 v[196:199], v149 offset:51200
	ds_read_b128 v[200:203], v149 offset:52224
	ds_read_b128 v[204:207], v149 offset:53248
	ds_read_b128 v[208:211], v149 offset:54272
	ds_read_b128 v[212:215], v149 offset:55296
	ds_read_b128 v[216:219], v149 offset:56320
	global_load_lds_dwordx4 v[186:187], off
	s_add_i32 m0, s30, 0x2000
	s_add_u32 s24, s24, 0x40080
	v_lshl_add_u64 v[186:187], v[220:221], 0, s[4:5]
	s_addc_u32 s25, s25, 0
	s_add_i32 s30, s56, s35
	global_load_lds_dwordx4 v[186:187], off
	s_mov_b32 m0, s30
	s_nop 0
	global_load_lds_dwordx4 v132, s[24:25]
	s_add_i32 m0, s30, 0x2000
	s_nop 0
	global_load_lds_dwordx4 v128, s[24:25]
	v_lshl_add_u64 v[186:187], v[222:223], 0, s[4:5]
	s_mov_b32 m0, s42
	s_nop 0
	global_load_lds_dwordx4 v[186:187], off
	v_lshl_add_u64 v[186:187], v[224:225], 0, s[4:5]
	s_mov_b32 m0, s43
	s_nop 0
	global_load_lds_dwordx4 v[186:187], off
	s_waitcnt vmcnt(8)
	s_waitcnt lgkmcnt(0)
	s_barrier
	s_setprio 1
	v_mfma_f32_16x16x32_bf16 v[60:63], v[150:153], v[182:185], v[60:63]
	v_mfma_f32_16x16x32_bf16 v[56:59], v[158:161], v[182:185], v[56:59]
	v_mfma_f32_16x16x32_bf16 v[44:47], v[150:153], v[196:199], v[44:47]
	v_mfma_f32_16x16x32_bf16 v[40:43], v[158:161], v[196:199], v[40:43]
	v_mfma_f32_16x16x32_bf16 v[28:31], v[150:153], v[204:207], v[28:31]
	v_mfma_f32_16x16x32_bf16 v[24:27], v[158:161], v[204:207], v[24:27]
	v_mfma_f32_16x16x32_bf16 v[12:15], v[150:153], v[212:215], v[12:15]
	v_mfma_f32_16x16x32_bf16 v[8:11], v[158:161], v[212:215], v[8:11]
	v_mfma_f32_16x16x32_bf16 v[60:63], v[154:157], v[192:195], v[60:63]
	v_mfma_f32_16x16x32_bf16 v[56:59], v[162:165], v[192:195], v[56:59]
	v_mfma_f32_16x16x32_bf16 v[44:47], v[154:157], v[200:203], v[44:47]
	v_mfma_f32_16x16x32_bf16 v[40:43], v[162:165], v[200:203], v[40:43]
	v_mfma_f32_16x16x32_bf16 v[28:31], v[154:157], v[208:211], v[28:31]
	v_mfma_f32_16x16x32_bf16 v[24:27], v[162:165], v[208:211], v[24:27]
	v_mfma_f32_16x16x32_bf16 v[12:15], v[154:157], v[216:219], v[12:15]
	v_mfma_f32_16x16x32_bf16 v[8:11], v[162:165], v[216:219], v[8:11]
	v_mfma_f32_16x16x32_bf16 v[52:55], v[166:169], v[182:185], v[52:55]
	v_mfma_f32_16x16x32_bf16 v[48:51], v[174:177], v[182:185], v[48:51]
	v_mfma_f32_16x16x32_bf16 v[36:39], v[166:169], v[196:199], v[36:39]
	v_mfma_f32_16x16x32_bf16 v[32:35], v[174:177], v[196:199], v[32:35]
	v_mfma_f32_16x16x32_bf16 v[20:23], v[166:169], v[204:207], v[20:23]
	v_mfma_f32_16x16x32_bf16 v[16:19], v[174:177], v[204:207], v[16:19]
	v_mfma_f32_16x16x32_bf16 v[4:7], v[166:169], v[212:215], v[4:7]
	v_mfma_f32_16x16x32_bf16 v[0:3], v[174:177], v[212:215], v[0:3]
	v_mfma_f32_16x16x32_bf16 v[52:55], v[170:173], v[192:195], v[52:55]
	v_mfma_f32_16x16x32_bf16 v[48:51], v[178:181], v[192:195], v[48:51]
	v_mfma_f32_16x16x32_bf16 v[36:39], v[170:173], v[200:203], v[36:39]
	v_mfma_f32_16x16x32_bf16 v[32:35], v[178:181], v[200:203], v[32:35]
	v_mfma_f32_16x16x32_bf16 v[20:23], v[170:173], v[208:211], v[20:23]
	v_mfma_f32_16x16x32_bf16 v[16:19], v[178:181], v[208:211], v[16:19]
	v_mfma_f32_16x16x32_bf16 v[4:7], v[170:173], v[216:219], v[4:7]
	v_mfma_f32_16x16x32_bf16 v[0:3], v[178:181], v[216:219], v[0:3]
	s_setprio 0
	s_barrier
	s_add_i32 s54, s54, 2
	s_add_u32 s22, s22, 0x100
	s_addc_u32 s23, s23, 0
	s_add_u32 s52, s52, 0x100
	s_addc_u32 s53, s53, 0
	s_cmp_gt_u32 s54, 13
	s_cbranch_scc0 .LBB0_192
	s_and_b64 vcc, exec, s[6:7]
	s_cbranch_vccz .LBB0_195
	s_barrier

; #define PG8_STAGE(bufoff, gbase, voff) do { _Pragma("unroll") for (int _i = 0; _i < 2; ++_i) \
;         __builtin_amdgcn_global_load_lds((const unsigned*)((const char*)(gbase) + (voff)[_i]), (PG8_LAS unsigned*)(lds + (bufoff) + ldsw + _i * 8192), 16, 0, 0); } while (0)
; #define PG8_LDA(dst, b, h) do { _Pragma("unroll") for (int m = 0; m < 4; ++m) _Pragma("unroll") for (int k = 0; k < 2; ++k) dst[m][k] = *(const PG8_LAS bf16x8*)(lds + PG8_SA(b, h) + aoff + m * 2048 + k * 1024); } while (0)
; #define PG8_LDB(dst, b, h) do { _Pragma("unroll") for (int n = 0; n < 2; ++n) _Pragma("unroll") for (int k = 0; k < 2; ++k) dst[n][k] = *(const PG8_LAS bf16x8*)(lds + PG8_SB(b, h) + boff + n * 2048 + k * 1024); } while (0)
; #define PG8_MMA(ai, bj, At, Bt) do { __builtin_amdgcn_s_setprio(1); _Pragma("unroll") for (int m = 0; m < 4; ++m) _Pragma("unroll") for (int n = 0; n < 2; ++n) _Pragma("unroll") for (int k = 0; k < 2; ++k) \
;         acc[ai][bj][m][n] = __builtin_amdgcn_mfma_f32_16x16x32_bf16(Bt[n][k], At[m][k], acc[ai][bj][m][n], 0, 0, 0); __builtin_amdgcn_s_setprio(0); } while (0)
; #define PG8_BAR __builtin_amdgcn_s_barrier()
; template <class Epi, class Sched, bool ALIGN_EPI = false, bool SP2 = false>
; __device__ __forceinline__ void gemm_phase(PG8_LAS unsigned char* lds, const Gemm g, const Sched& S, const Epi& E) {
;     ...
;         const bool has_next = S.next(ui + 1, nxt);
;         const char* nA = has_next ? (const char*)g.A + (size_t)nxt.pm * tstep : cA; const char* nB = has_next ? (const char*)g.Bt + (size_t)nxt.pn * tstep : cB;
;         for (int t = 0; t < nt; t += 2) {
;             const bool last = (t == nt - 2);
;             const char* a1 = cA + (size_t)(t + 1) * kstep;
;             const char* a2 = last ? nA : cA + (size_t)(t + 2) * kstep; const char* b2 = last ? nB : cB + (size_t)(t + 2) * kstep;
;             const char* a3 = a2 + kstep; const char* b3 = b2 + kstep;
;             if (last && has_next) S.a_ready(nxt);
;             if constexpr (SP2) {
;             PG8_LDB(B0, 0, 0); PG8_LDB(B1, 0, 1); PG8_SCHED; PG8_LDA(At, 0, 0); PG8_STAGE(PG8_SA(1, 1), a1 + hstep, voffA);
;             PG8_WAIT_V(8); PG8_WAIT_L(0); PG8_BAR; PG8_MMA(0, 0, At, B0); PG8_MMA(0, 1, At, B1); PG8_BAR; PG8_SCHED;
;             PG8_LDA(At, 0, 1); PG8_STAGE(PG8_SB(0, 0), b2, voffB); PG8_STAGE(PG8_SB(0, 1), b2 + hstep, voffB); PG8_STAGE(PG8_SA(0, 0), a2, voffA);
.LBB0_373:
	s_ashr_i32 s31, s30, 31
	s_lshl_b64 s[34:35], s[30:31], 19
	v_readlane_b32 s36, v235, 31
	v_readlane_b32 s37, v235, 32
	s_add_u32 s34, s36, s34
	s_addc_u32 s35, s37, s35
	s_and_b64 s[36:37], s[6:7], exec
	s_cselect_b32 s1, s35, s3
	s_cselect_b32 s25, s34, s2
	s_ashr_i32 s29, s28, 31
	s_lshl_b64 s[36:37], s[28:29], 19
	s_add_u32 s36, s10, s36
	s_addc_u32 s37, s11, s37
	s_and_b64 s[40:41], s[6:7], exec
	s_cselect_b32 s29, s37, s39
	s_cselect_b32 s31, s36, s38
	s_add_u32 s2, s2, 0x40080
	s_addc_u32 s3, s3, 0
	s_add_u32 s58, s38, 0x100
	s_addc_u32 s59, s39, 0
	s_mov_b32 s60, -2
	ds_read_b128 v[128:131], v171
	ds_read_b128 v[132:135], v171 offset:1024
	ds_read_b128 v[136:139], v171 offset:2048
	ds_read_b128 v[140:143], v171 offset:3072
	ds_read_b128 v[164:167], v172
	ds_read_b128 v[178:181], v172 offset:1024
	ds_read_b128 v[182:185], v172 offset:2048
	ds_read_b128 v[192:195], v172 offset:3072
	s_add_u32 s38, s2, 0xfffc0080
	s_addc_u32 s39, s3, -1
	s_cmp_eq_u32 s60, 12
	s_cselect_b32 s41, s1, s39
	s_cselect_b32 s40, s25, s38
	s_cselect_b32 s39, s29, s59
	s_cselect_b32 s38, s31, s58
	s_add_i32 m0, s44, 0xc000
	ds_read_b128 v[196:199], v173
	ds_read_b128 v[200:203], v173 offset:1024
	ds_read_b128 v[204:207], v173 offset:2048
	ds_read_b128 v[208:211], v173 offset:3072
	ds_read_b128 v[212:215], v173 offset:4096
	ds_read_b128 v[216:219], v173 offset:5120
	ds_read_b128 v[220:223], v173 offset:6144
	ds_read_b128 v[224:227], v173 offset:7168
	global_load_lds_dwordx4 v156, s[2:3]
	s_add_i32 m0, s44, 0xe000
	s_nop 0
	global_load_lds_dwordx4 v158, s[2:3]
	s_waitcnt vmcnt(8)
	s_waitcnt lgkmcnt(0)
	s_barrier
	s_setprio 1
	v_mfma_f32_16x16x32_bf16 v[124:127], v[128:131], v[196:199], 0
	v_mfma_f32_16x16x32_bf16 v[120:123], v[136:139], v[196:199], 0
	v_mfma_f32_16x16x32_bf16 v[108:111], v[128:131], v[204:207], 0
	v_mfma_f32_16x16x32_bf16 v[104:107], v[136:139], v[204:207], 0
	v_mfma_f32_16x16x32_bf16 v[92:95], v[128:131], v[212:215], 0
	v_mfma_f32_16x16x32_bf16 v[88:91], v[136:139], v[212:215], 0
	v_mfma_f32_16x16x32_bf16 v[76:79], v[128:131], v[220:223], 0
	v_mfma_f32_16x16x32_bf16 v[72:75], v[136:139], v[220:223], 0
	v_mfma_f32_16x16x32_bf16 v[124:127], v[132:135], v[200:203], v[124:127]
	v_mfma_f32_16x16x32_bf16 v[120:123], v[140:143], v[200:203], v[120:123]
	v_mfma_f32_16x16x32_bf16 v[108:111], v[132:135], v[208:211], v[108:111]
	v_mfma_f32_16x16x32_bf16 v[104:107], v[140:143], v[208:211], v[104:107]
	v_mfma_f32_16x16x32_bf16 v[92:95], v[132:135], v[216:219], v[92:95]
	v_mfma_f32_16x16x32_bf16 v[88:91], v[140:143], v[216:219], v[88:91]
	v_mfma_f32_16x16x32_bf16 v[76:79], v[132:135], v[224:227], v[76:79]
	v_mfma_f32_16x16x32_bf16 v[72:75], v[140:143], v[224:227], v[72:75]
	v_mfma_f32_16x16x32_bf16 v[116:119], v[164:167], v[196:199], 0
	v_mfma_f32_16x16x32_bf16 v[112:115], v[182:185], v[196:199], 0
	v_mfma_f32_16x16x32_bf16 v[100:103], v[164:167], v[204:207], 0
	v_mfma_f32_16x16x32_bf16 v[96:99], v[182:185], v[204:207], 0
	v_mfma_f32_16x16x32_bf16 v[84:87], v[164:167], v[212:215], 0
	v_mfma_f32_16x16x32_bf16 v[80:83], v[182:185], v[212:215], 0
	v_mfma_f32_16x16x32_bf16 v[68:71], v[164:167], v[220:223], 0
	v_mfma_f32_16x16x32_bf16 v[64:67], v[182:185], v[220:223], 0
	v_mfma_f32_16x16x32_bf16 v[116:119], v[178:181], v[200:203], v[116:119]
	v_mfma_f32_16x16x32_bf16 v[112:115], v[192:195], v[200:203], v[112:115]
	v_mfma_f32_16x16x32_bf16 v[100:103], v[178:181], v[208:211], v[100:103]
	v_mfma_f32_16x16x32_bf16 v[96:99], v[192:195], v[208:211], v[96:99]
	v_mfma_f32_16x16x32_bf16 v[84:87], v[178:181], v[216:219], v[84:87]
	v_mfma_f32_16x16x32_bf16 v[80:83], v[192:195], v[216:219], v[80:83]
	v_mfma_f32_16x16x32_bf16 v[68:71], v[178:181], v[224:227], v[68:71]
	v_mfma_f32_16x16x32_bf16 v[64:67], v[192:195], v[224:227], v[64:67]
	s_setprio 0
	s_barrier
	s_add_i32 s61, s52, s33
	v_lshl_add_u64 v[168:169], s[38:39], 0, v[148:149]
	s_mov_b32 m0, s61
	ds_read_b128 v[196:199], v173 offset:16384
	ds_read_b128 v[200:203], v173 offset:17408
	ds_read_b128 v[204:207], v173 offset:18432
	ds_read_b128 v[208:211], v173 offset:19456
	ds_read_b128 v[212:215], v173 offset:20480
	ds_read_b128 v[216:219], v173 offset:21504
	ds_read_b128 v[220:223], v173 offset:22528
	ds_read_b128 v[224:227], v173 offset:23552
	global_load_lds_dwordx4 v[168:169], off
	s_add_i32 m0, s61, 0x2000
	s_add_u32 s62, s38, 0x40000
	v_lshl_add_u64 v[186:187], s[38:39], 0, v[144:145]
	s_addc_u32 s63, s39, 0
	s_add_i32 s61, s53, s33
	global_load_lds_dwordx4 v[186:187], off
	s_mov_b32 m0, s61
	v_lshl_add_u64 v[230:231], s[40:41], 0, v[146:147]
	global_load_lds_dwordx4 v148, s[62:63]
	s_add_i32 m0, s61, 0x2000
	s_nop 0
	global_load_lds_dwordx4 v144, s[62:63]
	v_lshl_add_u64 v[228:229], s[40:41], 0, v[150:151]
	s_mov_b32 m0, s44
	s_nop 0
	global_load_lds_dwordx4 v[228:229], off
	s_mov_b32 m0, s45
	s_nop 0
	global_load_lds_dwordx4 v[230:231], off
	s_waitcnt vmcnt(8)
	s_waitcnt lgkmcnt(0)
	s_barrier
; #define PG8_STAGE(bufoff, gbase, voff) do { _Pragma("unroll") for (int _i = 0; _i < 2; ++_i) \
;         __builtin_amdgcn_global_load_lds((const unsigned*)((const char*)(gbase) + (voff)[_i]), (PG8_LAS unsigned*)(lds + (bufoff) + ldsw + _i * 8192), 16, 0, 0); } while (0)
; #define PG8_LDA(dst, b, h) do { _Pragma("unroll") for (int m = 0; m < 4; ++m) _Pragma("unroll") for (int k = 0; k < 2; ++k) dst[m][k] = *(const PG8_LAS bf16x8*)(lds + PG8_SA(b, h) + aoff + m * 2048 + k * 1024); } while (0)
; #define PG8_LDB(dst, b, h) do { _Pragma("unroll") for (int n = 0; n < 2; ++n) _Pragma("unroll") for (int k = 0; k < 2; ++k) dst[n][k] = *(const PG8_LAS bf16x8*)(lds + PG8_SB(b, h) + boff + n * 2048 + k * 1024); } while (0)
; #define PG8_MMA(ai, bj, At, Bt) do { __builtin_amdgcn_s_setprio(1); _Pragma("unroll") for (int m = 0; m < 4; ++m) _Pragma("unroll") for (int n = 0; n < 2; ++n) _Pragma("unroll") for (int k = 0; k < 2; ++k) \
;         acc[ai][bj][m][n] = __builtin_amdgcn_mfma_f32_16x16x32_bf16(Bt[n][k], At[m][k], acc[ai][bj][m][n], 0, 0, 0); __builtin_amdgcn_s_setprio(0); } while (0)
; #define PG8_WAIT_V(n) asm volatile("s_waitcnt vmcnt(" #n ")" ::: "memory")
; #define PG8_WAIT_L(n) asm volatile("s_waitcnt lgkmcnt(" #n ")" ::: "memory")
; #define PG8_BAR __builtin_amdgcn_s_barrier()
; #define PG8_SCHED __builtin_amdgcn_sched_barrier(0)
; template <class Epi, class Sched, bool ALIGN_EPI = false, bool SP2 = false>
; __device__ __forceinline__ void gemm_phase(PG8_LAS unsigned char* lds, const Gemm g, const Sched& S, const Epi& E) {
;     ...
;             PG8_WAIT_V(8); PG8_WAIT_L(0); PG8_BAR; PG8_MMA(1, 0, At, B0); PG8_MMA(1, 1, At, B1); PG8_BAR; PG8_SCHED;
;             PG8_LDB(B0, 1, 0); PG8_LDB(B1, 1, 1); PG8_SCHED; PG8_LDA(At, 1, 0); PG8_STAGE(PG8_SA(0, 1), a2 + hstep, voffA);
;             PG8_WAIT_V(8); PG8_WAIT_L(0); PG8_BAR; PG8_MMA(0, 0, At, B0); PG8_MMA(0, 1, At, B1); PG8_BAR; PG8_SCHED;
	s_setprio 1
	v_mfma_f32_16x16x32_bf16 v[60:63], v[128:131], v[196:199], 0
	v_mfma_f32_16x16x32_bf16 v[56:59], v[136:139], v[196:199], 0
	v_mfma_f32_16x16x32_bf16 v[44:47], v[128:131], v[204:207], 0
	v_mfma_f32_16x16x32_bf16 v[40:43], v[136:139], v[204:207], 0
	v_mfma_f32_16x16x32_bf16 v[28:31], v[128:131], v[212:215], 0
	v_mfma_f32_16x16x32_bf16 v[24:27], v[136:139], v[212:215], 0
	v_mfma_f32_16x16x32_bf16 v[12:15], v[128:131], v[220:223], 0
	v_mfma_f32_16x16x32_bf16 v[8:11], v[136:139], v[220:223], 0
	v_mfma_f32_16x16x32_bf16 v[60:63], v[132:135], v[200:203], v[60:63]
	v_mfma_f32_16x16x32_bf16 v[56:59], v[140:143], v[200:203], v[56:59]
	v_mfma_f32_16x16x32_bf16 v[44:47], v[132:135], v[208:211], v[44:47]
	v_mfma_f32_16x16x32_bf16 v[40:43], v[140:143], v[208:211], v[40:43]
	v_mfma_f32_16x16x32_bf16 v[28:31], v[132:135], v[216:219], v[28:31]
	v_mfma_f32_16x16x32_bf16 v[24:27], v[140:143], v[216:219], v[24:27]
	v_mfma_f32_16x16x32_bf16 v[12:15], v[132:135], v[224:227], v[12:15]
	v_mfma_f32_16x16x32_bf16 v[8:11], v[140:143], v[224:227], v[8:11]
	v_mfma_f32_16x16x32_bf16 v[52:55], v[164:167], v[196:199], 0
	v_mfma_f32_16x16x32_bf16 v[48:51], v[182:185], v[196:199], 0
	v_mfma_f32_16x16x32_bf16 v[36:39], v[164:167], v[204:207], 0
	v_mfma_f32_16x16x32_bf16 v[32:35], v[182:185], v[204:207], 0
	v_mfma_f32_16x16x32_bf16 v[20:23], v[164:167], v[212:215], 0
	v_mfma_f32_16x16x32_bf16 v[16:19], v[182:185], v[212:215], 0
	v_mfma_f32_16x16x32_bf16 v[4:7], v[164:167], v[220:223], 0
	v_mfma_f32_16x16x32_bf16 v[0:3], v[182:185], v[220:223], 0
	v_mfma_f32_16x16x32_bf16 v[52:55], v[178:181], v[200:203], v[52:55]
	v_mfma_f32_16x16x32_bf16 v[48:51], v[192:195], v[200:203], v[48:51]
	v_mfma_f32_16x16x32_bf16 v[36:39], v[178:181], v[208:211], v[36:39]
	v_mfma_f32_16x16x32_bf16 v[32:35], v[192:195], v[208:211], v[32:35]
	v_mfma_f32_16x16x32_bf16 v[20:23], v[178:181], v[216:219], v[20:23]
	v_mfma_f32_16x16x32_bf16 v[16:19], v[192:195], v[216:219], v[16:19]
	v_mfma_f32_16x16x32_bf16 v[4:7], v[178:181], v[224:227], v[4:7]
	v_mfma_f32_16x16x32_bf16 v[0:3], v[192:195], v[224:227], v[0:3]
	s_setprio 0
	s_barrier
	s_add_i32 s61, 0, 0x18000
	s_add_i32 s62, 0, 0x1c000
	v_add_u32_e32 v140, s61, v170
	v_add_u32_e32 v152, s62, v170
	ds_read_b128 v[128:131], v140
	ds_read_b128 v[132:135], v140 offset:1024
	ds_read_b128 v[136:139], v140 offset:2048
	ds_read_b128 v[140:143], v140 offset:3072
	ds_read_b128 v[164:167], v152
	ds_read_b128 v[178:181], v152 offset:1024
	ds_read_b128 v[182:185], v152 offset:2048
	ds_read_b128 v[192:195], v152 offset:3072
	s_add_u32 s40, s40, 0x40000
	s_addc_u32 s41, s41, 0
	s_mov_b32 m0, s46
	ds_read_b128 v[196:199], v173 offset:32768
	ds_read_b128 v[200:203], v173 offset:33792
	ds_read_b128 v[204:207], v173 offset:34816
	ds_read_b128 v[208:211], v173 offset:35840
	ds_read_b128 v[212:215], v173 offset:36864
	ds_read_b128 v[216:219], v173 offset:37888
	ds_read_b128 v[220:223], v173 offset:38912
	ds_read_b128 v[224:227], v173 offset:39936
	global_load_lds_dwordx4 v150, s[40:41]
	v_lshl_add_u64 v[232:233], s[40:41], 0, v[146:147]
	s_mov_b32 m0, s47
	s_nop 0
	global_load_lds_dwordx4 v[232:233], off
	s_waitcnt vmcnt(8)
	s_waitcnt lgkmcnt(0)
	s_barrier
	s_setprio 1
	v_mfma_f32_16x16x32_bf16 v[124:127], v[128:131], v[196:199], v[124:127]
	v_mfma_f32_16x16x32_bf16 v[120:123], v[136:139], v[196:199], v[120:123]
	v_mfma_f32_16x16x32_bf16 v[108:111], v[128:131], v[204:207], v[108:111]
	v_mfma_f32_16x16x32_bf16 v[104:107], v[136:139], v[204:207], v[104:107]
	v_mfma_f32_16x16x32_bf16 v[92:95], v[128:131], v[212:215], v[92:95]
	v_mfma_f32_16x16x32_bf16 v[88:91], v[136:139], v[212:215], v[88:91]
	v_mfma_f32_16x16x32_bf16 v[76:79], v[128:131], v[220:223], v[76:79]
	v_mfma_f32_16x16x32_bf16 v[72:75], v[136:139], v[220:223], v[72:75]
	v_mfma_f32_16x16x32_bf16 v[124:127], v[132:135], v[200:203], v[124:127]
	v_mfma_f32_16x16x32_bf16 v[120:123], v[140:143], v[200:203], v[120:123]
	v_mfma_f32_16x16x32_bf16 v[108:111], v[132:135], v[208:211], v[108:111]
	v_mfma_f32_16x16x32_bf16 v[104:107], v[140:143], v[208:211], v[104:107]
	v_mfma_f32_16x16x32_bf16 v[92:95], v[132:135], v[216:219], v[92:95]
	v_mfma_f32_16x16x32_bf16 v[88:91], v[140:143], v[216:219], v[88:91]
	v_mfma_f32_16x16x32_bf16 v[76:79], v[132:135], v[224:227], v[76:79]
	v_mfma_f32_16x16x32_bf16 v[72:75], v[140:143], v[224:227], v[72:75]
	v_mfma_f32_16x16x32_bf16 v[116:119], v[164:167], v[196:199], v[116:119]
	v_mfma_f32_16x16x32_bf16 v[112:115], v[182:185], v[196:199], v[112:115]
	v_mfma_f32_16x16x32_bf16 v[100:103], v[164:167], v[204:207], v[100:103]
	v_mfma_f32_16x16x32_bf16 v[96:99], v[182:185], v[204:207], v[96:99]
	v_mfma_f32_16x16x32_bf16 v[84:87], v[164:167], v[212:215], v[84:87]
	v_mfma_f32_16x16x32_bf16 v[80:83], v[182:185], v[212:215], v[80:83]
	v_mfma_f32_16x16x32_bf16 v[68:71], v[164:167], v[220:223], v[68:71]
	v_mfma_f32_16x16x32_bf16 v[64:67], v[182:185], v[220:223], v[64:67]
	v_mfma_f32_16x16x32_bf16 v[116:119], v[178:181], v[200:203], v[116:119]
	v_mfma_f32_16x16x32_bf16 v[112:115], v[192:195], v[200:203], v[112:115]
	v_mfma_f32_16x16x32_bf16 v[100:103], v[178:181], v[208:211], v[100:103]
	v_mfma_f32_16x16x32_bf16 v[96:99], v[192:195], v[208:211], v[96:99]
	v_mfma_f32_16x16x32_bf16 v[84:87], v[178:181], v[216:219], v[84:87]
	v_mfma_f32_16x16x32_bf16 v[80:83], v[192:195], v[216:219], v[80:83]
	v_mfma_f32_16x16x32_bf16 v[68:71], v[178:181], v[224:227], v[68:71]
	v_mfma_f32_16x16x32_bf16 v[64:67], v[192:195], v[224:227], v[64:67]
	s_setprio 0
	s_barrier
; #define PG8_STAGE(bufoff, gbase, voff) do { _Pragma("unroll") for (int _i = 0; _i < 2; ++_i) \
;         __builtin_amdgcn_global_load_lds((const unsigned*)((const char*)(gbase) + (voff)[_i]), (PG8_LAS unsigned*)(lds + (bufoff) + ldsw + _i * 8192), 16, 0, 0); } while (0)
; #define PG8_LDA(dst, b, h) do { _Pragma("unroll") for (int m = 0; m < 4; ++m) _Pragma("unroll") for (int k = 0; k < 2; ++k) dst[m][k] = *(const PG8_LAS bf16x8*)(lds + PG8_SA(b, h) + aoff + m * 2048 + k * 1024); } while (0)
; #define PG8_LDB(dst, b, h) do { _Pragma("unroll") for (int n = 0; n < 2; ++n) _Pragma("unroll") for (int k = 0; k < 2; ++k) dst[n][k] = *(const PG8_LAS bf16x8*)(lds + PG8_SB(b, h) + boff + n * 2048 + k * 1024); } while (0)
; template <class Epi, class Sched, bool ALIGN_EPI = false, bool SP2 = false>
; __device__ __forceinline__ void gemm_phase(PG8_LAS unsigned char* lds, const Gemm g, const Sched& S, const Epi& E) {
;     ...
;         for (int t = 0; t < nt; t += 2) {
;             const bool last = (t == nt - 2);
;             const char* a1 = cA + (size_t)(t + 1) * kstep;
;             const char* a2 = last ? nA : cA + (size_t)(t + 2) * kstep; const char* b2 = last ? nB : cB + (size_t)(t + 2) * kstep;
;             const char* a3 = a2 + kstep; const char* b3 = b2 + kstep;
;             if (last && has_next) S.a_ready(nxt);
;             if constexpr (SP2) {
;             PG8_LDB(B0, 0, 0); PG8_LDB(B1, 0, 1); PG8_SCHED; PG8_LDA(At, 0, 0); PG8_STAGE(PG8_SA(1, 1), a1 + hstep, voffA);
;             PG8_WAIT_V(8); PG8_WAIT_L(0); PG8_BAR; PG8_MMA(0, 0, At, B0); PG8_MMA(0, 1, At, B1); PG8_BAR; PG8_SCHED;
;             PG8_LDA(At, 0, 1); PG8_STAGE(PG8_SB(0, 0), b2, voffB); PG8_STAGE(PG8_SB(0, 1), b2 + hstep, voffB); PG8_STAGE(PG8_SA(0, 0), a2, voffA);
;             PG8_WAIT_V(8); PG8_WAIT_L(0); PG8_BAR; PG8_MMA(1, 0, At, B0); PG8_MMA(1, 1, At, B1); PG8_BAR; PG8_SCHED;
;             PG8_LDB(B0, 1, 0); PG8_LDB(B1, 1, 1); PG8_SCHED; PG8_LDA(At, 1, 0); PG8_STAGE(PG8_SA(0, 1), a2 + hstep, voffA);
;             PG8_WAIT_V(8); PG8_WAIT_L(0); PG8_BAR; PG8_MMA(0, 0, At, B0); PG8_MMA(0, 1, At, B1); PG8_BAR; PG8_SCHED;
;             PG8_LDA(At, 1, 1); PG8_STAGE(PG8_SB(1, 0), b3, voffB); PG8_STAGE(PG8_SB(1, 1), b3 + hstep, voffB); PG8_STAGE(PG8_SA(1, 0), a3, voffA);
;             PG8_WAIT_V(8); PG8_WAIT_L(0); PG8_BAR; PG8_MMA(1, 0, At, B0); PG8_MMA(1, 1, At, B1); PG8_BAR; PG8_SCHED;
	s_add_i32 s40, s61, s33
	v_lshl_add_u64 v[168:169], v[168:169], 0, s[16:17]
	s_mov_b32 m0, s40
	ds_read_b128 v[196:199], v173 offset:49152
	ds_read_b128 v[200:203], v173 offset:50176
	ds_read_b128 v[204:207], v173 offset:51200
	ds_read_b128 v[208:211], v173 offset:52224
	ds_read_b128 v[212:215], v173 offset:53248
	ds_read_b128 v[216:219], v173 offset:54272
	ds_read_b128 v[220:223], v173 offset:55296
	ds_read_b128 v[224:227], v173 offset:56320
	global_load_lds_dwordx4 v[168:169], off
	s_add_i32 m0, s40, 0x2000
	s_add_u32 s38, s38, 0x40080
	v_lshl_add_u64 v[168:169], v[186:187], 0, s[16:17]
	s_addc_u32 s39, s39, 0
	s_add_i32 s40, s62, s33
	global_load_lds_dwordx4 v[168:169], off
	s_mov_b32 m0, s40
	s_nop 0
	global_load_lds_dwordx4 v148, s[38:39]
	s_add_i32 m0, s40, 0x2000
	s_nop 0
	global_load_lds_dwordx4 v144, s[38:39]
	v_lshl_add_u64 v[168:169], v[228:229], 0, s[16:17]
	s_mov_b32 m0, s48
	s_nop 0
	global_load_lds_dwordx4 v[168:169], off
	v_lshl_add_u64 v[168:169], v[230:231], 0, s[16:17]
	s_mov_b32 m0, s49
	s_nop 0
	global_load_lds_dwordx4 v[168:169], off
	s_waitcnt vmcnt(8)
	s_waitcnt lgkmcnt(0)
	s_barrier
	s_setprio 1
	v_mfma_f32_16x16x32_bf16 v[60:63], v[128:131], v[196:199], v[60:63]
	v_mfma_f32_16x16x32_bf16 v[56:59], v[136:139], v[196:199], v[56:59]
	v_mfma_f32_16x16x32_bf16 v[44:47], v[128:131], v[204:207], v[44:47]
	v_mfma_f32_16x16x32_bf16 v[40:43], v[136:139], v[204:207], v[40:43]
	v_mfma_f32_16x16x32_bf16 v[28:31], v[128:131], v[212:215], v[28:31]
	v_mfma_f32_16x16x32_bf16 v[24:27], v[136:139], v[212:215], v[24:27]
	v_mfma_f32_16x16x32_bf16 v[12:15], v[128:131], v[220:223], v[12:15]
	v_mfma_f32_16x16x32_bf16 v[8:11], v[136:139], v[220:223], v[8:11]
	v_mfma_f32_16x16x32_bf16 v[60:63], v[132:135], v[200:203], v[60:63]
	v_mfma_f32_16x16x32_bf16 v[56:59], v[140:143], v[200:203], v[56:59]
	v_mfma_f32_16x16x32_bf16 v[44:47], v[132:135], v[208:211], v[44:47]
	v_mfma_f32_16x16x32_bf16 v[40:43], v[140:143], v[208:211], v[40:43]
	v_mfma_f32_16x16x32_bf16 v[28:31], v[132:135], v[216:219], v[28:31]
	v_mfma_f32_16x16x32_bf16 v[24:27], v[140:143], v[216:219], v[24:27]
	v_mfma_f32_16x16x32_bf16 v[12:15], v[132:135], v[224:227], v[12:15]
	v_mfma_f32_16x16x32_bf16 v[8:11], v[140:143], v[224:227], v[8:11]
	v_mfma_f32_16x16x32_bf16 v[52:55], v[164:167], v[196:199], v[52:55]
	v_mfma_f32_16x16x32_bf16 v[48:51], v[182:185], v[196:199], v[48:51]
	v_mfma_f32_16x16x32_bf16 v[36:39], v[164:167], v[204:207], v[36:39]
	v_mfma_f32_16x16x32_bf16 v[32:35], v[182:185], v[204:207], v[32:35]
	v_mfma_f32_16x16x32_bf16 v[20:23], v[164:167], v[212:215], v[20:23]
	v_mfma_f32_16x16x32_bf16 v[16:19], v[182:185], v[212:215], v[16:19]
	v_mfma_f32_16x16x32_bf16 v[4:7], v[164:167], v[220:223], v[4:7]
	v_mfma_f32_16x16x32_bf16 v[0:3], v[182:185], v[220:223], v[0:3]
	v_mfma_f32_16x16x32_bf16 v[52:55], v[178:181], v[200:203], v[52:55]
	v_mfma_f32_16x16x32_bf16 v[48:51], v[192:195], v[200:203], v[48:51]
	v_mfma_f32_16x16x32_bf16 v[36:39], v[178:181], v[208:211], v[36:39]
	v_mfma_f32_16x16x32_bf16 v[32:35], v[192:195], v[208:211], v[32:35]
	v_mfma_f32_16x16x32_bf16 v[20:23], v[178:181], v[216:219], v[20:23]
	v_mfma_f32_16x16x32_bf16 v[16:19], v[192:195], v[216:219], v[16:19]
	v_mfma_f32_16x16x32_bf16 v[4:7], v[178:181], v[224:227], v[4:7]
	v_mfma_f32_16x16x32_bf16 v[0:3], v[192:195], v[224:227], v[0:3]
	s_setprio 0
	s_barrier
	s_add_i32 s60, s60, 2
	s_add_u32 s2, s2, 0x100
	s_addc_u32 s3, s3, 0
	s_add_u32 s58, s58, 0x100
	s_addc_u32 s59, s59, 0
.LBB0_374:
	ds_read_b128 v[128:131], v171
	ds_read_b128 v[132:135], v171 offset:1024
	ds_read_b128 v[136:139], v171 offset:2048
	ds_read_b128 v[140:143], v171 offset:3072
	ds_read_b128 v[164:167], v172
	ds_read_b128 v[178:181], v172 offset:1024
	ds_read_b128 v[182:185], v172 offset:2048
	ds_read_b128 v[192:195], v172 offset:3072
	s_add_u32 s38, s2, 0xfffc0080
	s_addc_u32 s39, s3, -1
	s_cmp_eq_u32 s60, 12
	s_cselect_b32 s41, s1, s39
	s_cselect_b32 s40, s25, s38
	s_cselect_b32 s39, s29, s59
	s_cselect_b32 s38, s31, s58
	s_add_i32 m0, s44, 0xc000
	ds_read_b128 v[196:199], v173
	ds_read_b128 v[200:203], v173 offset:1024
	ds_read_b128 v[204:207], v173 offset:2048
	ds_read_b128 v[208:211], v173 offset:3072
	ds_read_b128 v[212:215], v173 offset:4096
	ds_read_b128 v[216:219], v173 offset:5120
	ds_read_b128 v[220:223], v173 offset:6144
	ds_read_b128 v[224:227], v173 offset:7168
	global_load_lds_dwordx4 v156, s[2:3]
	s_add_i32 m0, s44, 0xe000
	s_nop 0
	global_load_lds_dwordx4 v158, s[2:3]
	s_waitcnt vmcnt(8)
	s_waitcnt lgkmcnt(0)
	s_barrier
; #define PG8_STAGE(bufoff, gbase, voff) do { _Pragma("unroll") for (int _i = 0; _i < 2; ++_i) \
;         __builtin_amdgcn_global_load_lds((const unsigned*)((const char*)(gbase) + (voff)[_i]), (PG8_LAS unsigned*)(lds + (bufoff) + ldsw + _i * 8192), 16, 0, 0); } while (0)
; #define PG8_LDA(dst, b, h) do { _Pragma("unroll") for (int m = 0; m < 4; ++m) _Pragma("unroll") for (int k = 0; k < 2; ++k) dst[m][k] = *(const PG8_LAS bf16x8*)(lds + PG8_SA(b, h) + aoff + m * 2048 + k * 1024); } while (0)
; #define PG8_MMA(ai, bj, At, Bt) do { __builtin_amdgcn_s_setprio(1); _Pragma("unroll") for (int m = 0; m < 4; ++m) _Pragma("unroll") for (int n = 0; n < 2; ++n) _Pragma("unroll") for (int k = 0; k < 2; ++k) \
;         acc[ai][bj][m][n] = __builtin_amdgcn_mfma_f32_16x16x32_bf16(Bt[n][k], At[m][k], acc[ai][bj][m][n], 0, 0, 0); __builtin_amdgcn_s_setprio(0); } while (0)
; #define PG8_WAIT_V(n) asm volatile("s_waitcnt vmcnt(" #n ")" ::: "memory")
; #define PG8_WAIT_L(n) asm volatile("s_waitcnt lgkmcnt(" #n ")" ::: "memory")
; #define PG8_BAR __builtin_amdgcn_s_barrier()
; #define PG8_SCHED __builtin_amdgcn_sched_barrier(0)
; template <class Epi, class Sched, bool ALIGN_EPI = false, bool SP2 = false>
; __device__ __forceinline__ void gemm_phase(PG8_LAS unsigned char* lds, const Gemm g, const Sched& S, const Epi& E) {
;     ...
;             PG8_WAIT_V(8); PG8_WAIT_L(0); PG8_BAR; PG8_MMA(0, 0, At, B0); PG8_MMA(0, 1, At, B1); PG8_BAR; PG8_SCHED;
;             PG8_LDA(At, 0, 1); PG8_STAGE(PG8_SB(0, 0), b2, voffB); PG8_STAGE(PG8_SB(0, 1), b2 + hstep, voffB); PG8_STAGE(PG8_SA(0, 0), a2, voffA);
;             PG8_WAIT_V(8); PG8_WAIT_L(0); PG8_BAR; PG8_MMA(1, 0, At, B0); PG8_MMA(1, 1, At, B1); PG8_BAR; PG8_SCHED;
	s_setprio 1
	v_mfma_f32_16x16x32_bf16 v[124:127], v[128:131], v[196:199], v[124:127]
	v_mfma_f32_16x16x32_bf16 v[120:123], v[136:139], v[196:199], v[120:123]
	v_mfma_f32_16x16x32_bf16 v[108:111], v[128:131], v[204:207], v[108:111]
	v_mfma_f32_16x16x32_bf16 v[104:107], v[136:139], v[204:207], v[104:107]
	v_mfma_f32_16x16x32_bf16 v[92:95], v[128:131], v[212:215], v[92:95]
	v_mfma_f32_16x16x32_bf16 v[88:91], v[136:139], v[212:215], v[88:91]
	v_mfma_f32_16x16x32_bf16 v[76:79], v[128:131], v[220:223], v[76:79]
	v_mfma_f32_16x16x32_bf16 v[72:75], v[136:139], v[220:223], v[72:75]
	v_mfma_f32_16x16x32_bf16 v[124:127], v[132:135], v[200:203], v[124:127]
	v_mfma_f32_16x16x32_bf16 v[120:123], v[140:143], v[200:203], v[120:123]
	v_mfma_f32_16x16x32_bf16 v[108:111], v[132:135], v[208:211], v[108:111]
	v_mfma_f32_16x16x32_bf16 v[104:107], v[140:143], v[208:211], v[104:107]
	v_mfma_f32_16x16x32_bf16 v[92:95], v[132:135], v[216:219], v[92:95]
	v_mfma_f32_16x16x32_bf16 v[88:91], v[140:143], v[216:219], v[88:91]
	v_mfma_f32_16x16x32_bf16 v[76:79], v[132:135], v[224:227], v[76:79]
	v_mfma_f32_16x16x32_bf16 v[72:75], v[140:143], v[224:227], v[72:75]
	v_mfma_f32_16x16x32_bf16 v[116:119], v[164:167], v[196:199], v[116:119]
	v_mfma_f32_16x16x32_bf16 v[112:115], v[182:185], v[196:199], v[112:115]
	v_mfma_f32_16x16x32_bf16 v[100:103], v[164:167], v[204:207], v[100:103]
	v_mfma_f32_16x16x32_bf16 v[96:99], v[182:185], v[204:207], v[96:99]
	v_mfma_f32_16x16x32_bf16 v[84:87], v[164:167], v[212:215], v[84:87]
	v_mfma_f32_16x16x32_bf16 v[80:83], v[182:185], v[212:215], v[80:83]
	v_mfma_f32_16x16x32_bf16 v[68:71], v[164:167], v[220:223], v[68:71]
	v_mfma_f32_16x16x32_bf16 v[64:67], v[182:185], v[220:223], v[64:67]
	v_mfma_f32_16x16x32_bf16 v[116:119], v[178:181], v[200:203], v[116:119]
	v_mfma_f32_16x16x32_bf16 v[112:115], v[192:195], v[200:203], v[112:115]
	v_mfma_f32_16x16x32_bf16 v[100:103], v[178:181], v[208:211], v[100:103]
	v_mfma_f32_16x16x32_bf16 v[96:99], v[192:195], v[208:211], v[96:99]
	v_mfma_f32_16x16x32_bf16 v[84:87], v[178:181], v[216:219], v[84:87]
	v_mfma_f32_16x16x32_bf16 v[80:83], v[192:195], v[216:219], v[80:83]
	v_mfma_f32_16x16x32_bf16 v[68:71], v[178:181], v[224:227], v[68:71]
	v_mfma_f32_16x16x32_bf16 v[64:67], v[192:195], v[224:227], v[64:67]
	s_setprio 0
	s_barrier
	s_add_i32 s61, s52, s33
	v_lshl_add_u64 v[168:169], s[38:39], 0, v[148:149]
	s_mov_b32 m0, s61
	ds_read_b128 v[196:199], v173 offset:16384
	ds_read_b128 v[200:203], v173 offset:17408
	ds_read_b128 v[204:207], v173 offset:18432
	ds_read_b128 v[208:211], v173 offset:19456
	ds_read_b128 v[212:215], v173 offset:20480
	ds_read_b128 v[216:219], v173 offset:21504
	ds_read_b128 v[220:223], v173 offset:22528
	ds_read_b128 v[224:227], v173 offset:23552
	global_load_lds_dwordx4 v[168:169], off
	s_add_i32 m0, s61, 0x2000
	s_add_u32 s62, s38, 0x40000
	v_lshl_add_u64 v[186:187], s[38:39], 0, v[144:145]
	s_addc_u32 s63, s39, 0
	s_add_i32 s61, s53, s33
	global_load_lds_dwordx4 v[186:187], off
	s_mov_b32 m0, s61
	v_lshl_add_u64 v[230:231], s[40:41], 0, v[146:147]
	global_load_lds_dwordx4 v148, s[62:63]
	s_add_i32 m0, s61, 0x2000
	s_nop 0
	global_load_lds_dwordx4 v144, s[62:63]
	v_lshl_add_u64 v[228:229], s[40:41], 0, v[150:151]
	s_mov_b32 m0, s44
	s_nop 0
	global_load_lds_dwordx4 v[228:229], off
	s_mov_b32 m0, s45
	s_nop 0
	global_load_lds_dwordx4 v[230:231], off
	s_waitcnt vmcnt(8)
	s_waitcnt lgkmcnt(0)
	s_barrier
	s_setprio 1
	v_mfma_f32_16x16x32_bf16 v[60:63], v[128:131], v[196:199], v[60:63]
	v_mfma_f32_16x16x32_bf16 v[56:59], v[136:139], v[196:199], v[56:59]
	v_mfma_f32_16x16x32_bf16 v[44:47], v[128:131], v[204:207], v[44:47]
	v_mfma_f32_16x16x32_bf16 v[40:43], v[136:139], v[204:207], v[40:43]
	v_mfma_f32_16x16x32_bf16 v[28:31], v[128:131], v[212:215], v[28:31]
	v_mfma_f32_16x16x32_bf16 v[24:27], v[136:139], v[212:215], v[24:27]
	v_mfma_f32_16x16x32_bf16 v[12:15], v[128:131], v[220:223], v[12:15]
	v_mfma_f32_16x16x32_bf16 v[8:11], v[136:139], v[220:223], v[8:11]
	v_mfma_f32_16x16x32_bf16 v[60:63], v[132:135], v[200:203], v[60:63]
	v_mfma_f32_16x16x32_bf16 v[56:59], v[140:143], v[200:203], v[56:59]
	v_mfma_f32_16x16x32_bf16 v[44:47], v[132:135], v[208:211], v[44:47]
	v_mfma_f32_16x16x32_bf16 v[40:43], v[140:143], v[208:211], v[40:43]
	v_mfma_f32_16x16x32_bf16 v[28:31], v[132:135], v[216:219], v[28:31]
	v_mfma_f32_16x16x32_bf16 v[24:27], v[140:143], v[216:219], v[24:27]
	v_mfma_f32_16x16x32_bf16 v[12:15], v[132:135], v[224:227], v[12:15]
	v_mfma_f32_16x16x32_bf16 v[8:11], v[140:143], v[224:227], v[8:11]
	v_mfma_f32_16x16x32_bf16 v[52:55], v[164:167], v[196:199], v[52:55]
	v_mfma_f32_16x16x32_bf16 v[48:51], v[182:185], v[196:199], v[48:51]
	v_mfma_f32_16x16x32_bf16 v[36:39], v[164:167], v[204:207], v[36:39]
	v_mfma_f32_16x16x32_bf16 v[32:35], v[182:185], v[204:207], v[32:35]
	v_mfma_f32_16x16x32_bf16 v[20:23], v[164:167], v[212:215], v[20:23]
	v_mfma_f32_16x16x32_bf16 v[16:19], v[182:185], v[212:215], v[16:19]
	v_mfma_f32_16x16x32_bf16 v[4:7], v[164:167], v[220:223], v[4:7]
	v_mfma_f32_16x16x32_bf16 v[0:3], v[182:185], v[220:223], v[0:3]
	v_mfma_f32_16x16x32_bf16 v[52:55], v[178:181], v[200:203], v[52:55]
	v_mfma_f32_16x16x32_bf16 v[48:51], v[192:195], v[200:203], v[48:51]
	v_mfma_f32_16x16x32_bf16 v[36:39], v[178:181], v[208:211], v[36:39]
	v_mfma_f32_16x16x32_bf16 v[32:35], v[192:195], v[208:211], v[32:35]
	v_mfma_f32_16x16x32_bf16 v[20:23], v[178:181], v[216:219], v[20:23]
	v_mfma_f32_16x16x32_bf16 v[16:19], v[192:195], v[216:219], v[16:19]
	v_mfma_f32_16x16x32_bf16 v[4:7], v[178:181], v[224:227], v[4:7]
	v_mfma_f32_16x16x32_bf16 v[0:3], v[192:195], v[224:227], v[0:3]
	s_setprio 0
	s_barrier
; #define PG8_STAGE(bufoff, gbase, voff) do { _Pragma("unroll") for (int _i = 0; _i < 2; ++_i) \
;         __builtin_amdgcn_global_load_lds((const unsigned*)((const char*)(gbase) + (voff)[_i]), (PG8_LAS unsigned*)(lds + (bufoff) + ldsw + _i * 8192), 16, 0, 0); } while (0)
; #define PG8_LDA(dst, b, h) do { _Pragma("unroll") for (int m = 0; m < 4; ++m) _Pragma("unroll") for (int k = 0; k < 2; ++k) dst[m][k] = *(const PG8_LAS bf16x8*)(lds + PG8_SA(b, h) + aoff + m * 2048 + k * 1024); } while (0)
; #define PG8_LDB(dst, b, h) do { _Pragma("unroll") for (int n = 0; n < 2; ++n) _Pragma("unroll") for (int k = 0; k < 2; ++k) dst[n][k] = *(const PG8_LAS bf16x8*)(lds + PG8_SB(b, h) + boff + n * 2048 + k * 1024); } while (0)
; #define PG8_MMA(ai, bj, At, Bt) do { __builtin_amdgcn_s_setprio(1); _Pragma("unroll") for (int m = 0; m < 4; ++m) _Pragma("unroll") for (int n = 0; n < 2; ++n) _Pragma("unroll") for (int k = 0; k < 2; ++k) \
;         acc[ai][bj][m][n] = __builtin_amdgcn_mfma_f32_16x16x32_bf16(Bt[n][k], At[m][k], acc[ai][bj][m][n], 0, 0, 0); __builtin_amdgcn_s_setprio(0); } while (0)
; #define PG8_WAIT_V(n) asm volatile("s_waitcnt vmcnt(" #n ")" ::: "memory")
; #define PG8_WAIT_L(n) asm volatile("s_waitcnt lgkmcnt(" #n ")" ::: "memory")
; #define PG8_BAR __builtin_amdgcn_s_barrier()
; #define PG8_SCHED __builtin_amdgcn_sched_barrier(0)
; template <class Epi, class Sched, bool ALIGN_EPI = false, bool SP2 = false>
; __device__ __forceinline__ void gemm_phase(PG8_LAS unsigned char* lds, const Gemm g, const Sched& S, const Epi& E) {
;     ...
;             PG8_LDB(B0, 1, 0); PG8_LDB(B1, 1, 1); PG8_SCHED; PG8_LDA(At, 1, 0); PG8_STAGE(PG8_SA(0, 1), a2 + hstep, voffA);
;             PG8_WAIT_V(8); PG8_WAIT_L(0); PG8_BAR; PG8_MMA(0, 0, At, B0); PG8_MMA(0, 1, At, B1); PG8_BAR; PG8_SCHED;
	s_add_i32 s61, 0, 0x18000
	s_add_i32 s62, 0, 0x1c000
	v_add_u32_e32 v140, s61, v170
	v_add_u32_e32 v152, s62, v170
	ds_read_b128 v[128:131], v140
	ds_read_b128 v[132:135], v140 offset:1024
	ds_read_b128 v[136:139], v140 offset:2048
	ds_read_b128 v[140:143], v140 offset:3072
	ds_read_b128 v[164:167], v152
	ds_read_b128 v[178:181], v152 offset:1024
	ds_read_b128 v[182:185], v152 offset:2048
	ds_read_b128 v[192:195], v152 offset:3072
	s_add_u32 s40, s40, 0x40000
	s_addc_u32 s41, s41, 0
	s_mov_b32 m0, s46
	ds_read_b128 v[196:199], v173 offset:32768
	ds_read_b128 v[200:203], v173 offset:33792
	ds_read_b128 v[204:207], v173 offset:34816
	ds_read_b128 v[208:211], v173 offset:35840
	ds_read_b128 v[212:215], v173 offset:36864
	ds_read_b128 v[216:219], v173 offset:37888
	ds_read_b128 v[220:223], v173 offset:38912
	ds_read_b128 v[224:227], v173 offset:39936
	global_load_lds_dwordx4 v150, s[40:41]
	v_lshl_add_u64 v[232:233], s[40:41], 0, v[146:147]
	s_mov_b32 m0, s47
	s_nop 0
	global_load_lds_dwordx4 v[232:233], off
	s_waitcnt vmcnt(8)
	s_waitcnt lgkmcnt(0)
	s_barrier
	s_setprio 1
	v_mfma_f32_16x16x32_bf16 v[124:127], v[128:131], v[196:199], v[124:127]
	v_mfma_f32_16x16x32_bf16 v[120:123], v[136:139], v[196:199], v[120:123]
	v_mfma_f32_16x16x32_bf16 v[108:111], v[128:131], v[204:207], v[108:111]
	v_mfma_f32_16x16x32_bf16 v[104:107], v[136:139], v[204:207], v[104:107]
	v_mfma_f32_16x16x32_bf16 v[92:95], v[128:131], v[212:215], v[92:95]
	v_mfma_f32_16x16x32_bf16 v[88:91], v[136:139], v[212:215], v[88:91]
	v_mfma_f32_16x16x32_bf16 v[76:79], v[128:131], v[220:223], v[76:79]
	v_mfma_f32_16x16x32_bf16 v[72:75], v[136:139], v[220:223], v[72:75]
	v_mfma_f32_16x16x32_bf16 v[124:127], v[132:135], v[200:203], v[124:127]
	v_mfma_f32_16x16x32_bf16 v[120:123], v[140:143], v[200:203], v[120:123]
	v_mfma_f32_16x16x32_bf16 v[108:111], v[132:135], v[208:211], v[108:111]
	v_mfma_f32_16x16x32_bf16 v[104:107], v[140:143], v[208:211], v[104:107]
	v_mfma_f32_16x16x32_bf16 v[92:95], v[132:135], v[216:219], v[92:95]
	v_mfma_f32_16x16x32_bf16 v[88:91], v[140:143], v[216:219], v[88:91]
	v_mfma_f32_16x16x32_bf16 v[76:79], v[132:135], v[224:227], v[76:79]
	v_mfma_f32_16x16x32_bf16 v[72:75], v[140:143], v[224:227], v[72:75]
	v_mfma_f32_16x16x32_bf16 v[116:119], v[164:167], v[196:199], v[116:119]
	v_mfma_f32_16x16x32_bf16 v[112:115], v[182:185], v[196:199], v[112:115]
	v_mfma_f32_16x16x32_bf16 v[100:103], v[164:167], v[204:207], v[100:103]
	v_mfma_f32_16x16x32_bf16 v[96:99], v[182:185], v[204:207], v[96:99]
	v_mfma_f32_16x16x32_bf16 v[84:87], v[164:167], v[212:215], v[84:87]
	v_mfma_f32_16x16x32_bf16 v[80:83], v[182:185], v[212:215], v[80:83]
	v_mfma_f32_16x16x32_bf16 v[68:71], v[164:167], v[220:223], v[68:71]
	v_mfma_f32_16x16x32_bf16 v[64:67], v[182:185], v[220:223], v[64:67]
	v_mfma_f32_16x16x32_bf16 v[116:119], v[178:181], v[200:203], v[116:119]
	v_mfma_f32_16x16x32_bf16 v[112:115], v[192:195], v[200:203], v[112:115]
	v_mfma_f32_16x16x32_bf16 v[100:103], v[178:181], v[208:211], v[100:103]
	v_mfma_f32_16x16x32_bf16 v[96:99], v[192:195], v[208:211], v[96:99]
	v_mfma_f32_16x16x32_bf16 v[84:87], v[178:181], v[216:219], v[84:87]
	v_mfma_f32_16x16x32_bf16 v[80:83], v[192:195], v[216:219], v[80:83]
	v_mfma_f32_16x16x32_bf16 v[68:71], v[178:181], v[224:227], v[68:71]
	v_mfma_f32_16x16x32_bf16 v[64:67], v[192:195], v[224:227], v[64:67]
	s_setprio 0
	s_barrier
; #define PG8_STAGE(bufoff, gbase, voff) do { _Pragma("unroll") for (int _i = 0; _i < 2; ++_i) \
;         __builtin_amdgcn_global_load_lds((const unsigned*)((const char*)(gbase) + (voff)[_i]), (PG8_LAS unsigned*)(lds + (bufoff) + ldsw + _i * 8192), 16, 0, 0); } while (0)
; #define PG8_LDA(dst, b, h) do { _Pragma("unroll") for (int m = 0; m < 4; ++m) _Pragma("unroll") for (int k = 0; k < 2; ++k) dst[m][k] = *(const PG8_LAS bf16x8*)(lds + PG8_SA(b, h) + aoff + m * 2048 + k * 1024); } while (0)
; #define PG8_MMA(ai, bj, At, Bt) do { __builtin_amdgcn_s_setprio(1); _Pragma("unroll") for (int m = 0; m < 4; ++m) _Pragma("unroll") for (int n = 0; n < 2; ++n) _Pragma("unroll") for (int k = 0; k < 2; ++k) \
;         acc[ai][bj][m][n] = __builtin_amdgcn_mfma_f32_16x16x32_bf16(Bt[n][k], At[m][k], acc[ai][bj][m][n], 0, 0, 0); __builtin_amdgcn_s_setprio(0); } while (0)
; #define PG8_WAIT_V(n) asm volatile("s_waitcnt vmcnt(" #n ")" ::: "memory")
; #define PG8_WAIT_L(n) asm volatile("s_waitcnt lgkmcnt(" #n ")" ::: "memory")
; #define PG8_BAR __builtin_amdgcn_s_barrier()
; #define PG8_SCHED __builtin_amdgcn_sched_barrier(0)
; template <class Epi, class Sched, bool ALIGN_EPI = false, bool SP2 = false>
; __device__ __forceinline__ void gemm_phase(PG8_LAS unsigned char* lds, const Gemm g, const Sched& S, const Epi& E) {
;     ...
;             PG8_LDA(At, 1, 1); PG8_STAGE(PG8_SB(1, 0), b3, voffB); PG8_STAGE(PG8_SB(1, 1), b3 + hstep, voffB); PG8_STAGE(PG8_SA(1, 0), a3, voffA);
;             PG8_WAIT_V(8); PG8_WAIT_L(0); PG8_BAR; PG8_MMA(1, 0, At, B0); PG8_MMA(1, 1, At, B1); PG8_BAR; PG8_SCHED;
	s_add_i32 s40, s61, s33
	v_lshl_add_u64 v[168:169], v[168:169], 0, s[16:17]
	s_mov_b32 m0, s40
	ds_read_b128 v[196:199], v173 offset:49152
	ds_read_b128 v[200:203], v173 offset:50176
	ds_read_b128 v[204:207], v173 offset:51200
	ds_read_b128 v[208:211], v173 offset:52224
	ds_read_b128 v[212:215], v173 offset:53248
	ds_read_b128 v[216:219], v173 offset:54272
	ds_read_b128 v[220:223], v173 offset:55296
	ds_read_b128 v[224:227], v173 offset:56320
	global_load_lds_dwordx4 v[168:169], off
	s_add_i32 m0, s40, 0x2000
	s_add_u32 s38, s38, 0x40080
	v_lshl_add_u64 v[168:169], v[186:187], 0, s[16:17]
	s_addc_u32 s39, s39, 0
	s_add_i32 s40, s62, s33
	global_load_lds_dwordx4 v[168:169], off
	s_mov_b32 m0, s40
	s_nop 0
	global_load_lds_dwordx4 v148, s[38:39]
	s_add_i32 m0, s40, 0x2000
	s_nop 0
	global_load_lds_dwordx4 v144, s[38:39]
	v_lshl_add_u64 v[168:169], v[228:229], 0, s[16:17]
	s_mov_b32 m0, s48
	s_nop 0
	global_load_lds_dwordx4 v[168:169], off
	v_lshl_add_u64 v[168:169], v[230:231], 0, s[16:17]
	s_mov_b32 m0, s49
	s_nop 0
	global_load_lds_dwordx4 v[168:169], off
	s_waitcnt vmcnt(8)
	s_waitcnt lgkmcnt(0)
	s_barrier
	s_setprio 1
	v_mfma_f32_16x16x32_bf16 v[60:63], v[128:131], v[196:199], v[60:63]
	v_mfma_f32_16x16x32_bf16 v[56:59], v[136:139], v[196:199], v[56:59]
	v_mfma_f32_16x16x32_bf16 v[44:47], v[128:131], v[204:207], v[44:47]
	v_mfma_f32_16x16x32_bf16 v[40:43], v[136:139], v[204:207], v[40:43]
	v_mfma_f32_16x16x32_bf16 v[28:31], v[128:131], v[212:215], v[28:31]
	v_mfma_f32_16x16x32_bf16 v[24:27], v[136:139], v[212:215], v[24:27]
	v_mfma_f32_16x16x32_bf16 v[12:15], v[128:131], v[220:223], v[12:15]
	v_mfma_f32_16x16x32_bf16 v[8:11], v[136:139], v[220:223], v[8:11]
	v_mfma_f32_16x16x32_bf16 v[60:63], v[132:135], v[200:203], v[60:63]
	v_mfma_f32_16x16x32_bf16 v[56:59], v[140:143], v[200:203], v[56:59]
	v_mfma_f32_16x16x32_bf16 v[44:47], v[132:135], v[208:211], v[44:47]
	v_mfma_f32_16x16x32_bf16 v[40:43], v[140:143], v[208:211], v[40:43]
	v_mfma_f32_16x16x32_bf16 v[28:31], v[132:135], v[216:219], v[28:31]
	v_mfma_f32_16x16x32_bf16 v[24:27], v[140:143], v[216:219], v[24:27]
	v_mfma_f32_16x16x32_bf16 v[12:15], v[132:135], v[224:227], v[12:15]
	v_mfma_f32_16x16x32_bf16 v[8:11], v[140:143], v[224:227], v[8:11]
	v_mfma_f32_16x16x32_bf16 v[52:55], v[164:167], v[196:199], v[52:55]
	v_mfma_f32_16x16x32_bf16 v[48:51], v[182:185], v[196:199], v[48:51]
	v_mfma_f32_16x16x32_bf16 v[36:39], v[164:167], v[204:207], v[36:39]
	v_mfma_f32_16x16x32_bf16 v[32:35], v[182:185], v[204:207], v[32:35]
	v_mfma_f32_16x16x32_bf16 v[20:23], v[164:167], v[212:215], v[20:23]
	v_mfma_f32_16x16x32_bf16 v[16:19], v[182:185], v[212:215], v[16:19]
	v_mfma_f32_16x16x32_bf16 v[4:7], v[164:167], v[220:223], v[4:7]
	v_mfma_f32_16x16x32_bf16 v[0:3], v[182:185], v[220:223], v[0:3]
	v_mfma_f32_16x16x32_bf16 v[52:55], v[178:181], v[200:203], v[52:55]
	v_mfma_f32_16x16x32_bf16 v[48:51], v[192:195], v[200:203], v[48:51]
	v_mfma_f32_16x16x32_bf16 v[36:39], v[178:181], v[208:211], v[36:39]
	v_mfma_f32_16x16x32_bf16 v[32:35], v[192:195], v[208:211], v[32:35]
	v_mfma_f32_16x16x32_bf16 v[20:23], v[178:181], v[216:219], v[20:23]
	v_mfma_f32_16x16x32_bf16 v[16:19], v[192:195], v[216:219], v[16:19]
	v_mfma_f32_16x16x32_bf16 v[4:7], v[178:181], v[224:227], v[4:7]
	v_mfma_f32_16x16x32_bf16 v[0:3], v[192:195], v[224:227], v[0:3]
	s_setprio 0
	s_barrier
	s_add_i32 s60, s60, 2
	s_add_u32 s2, s2, 0x100
	s_addc_u32 s3, s3, 0
	s_add_u32 s58, s58, 0x100
	s_addc_u32 s59, s59, 0
	s_cmp_gt_u32 s60, 13
	s_cbranch_scc0 .LBB0_374
	s_and_b64 vcc, exec, s[18:19]
	s_cbranch_vccnz .LBB0_379
	v_lshl_add_u32 v164, s0, 8, v155
	s_cmp_gt_i32 s57, 3
	s_mov_b64 s[0:1], -1
	s_cbranch_scc1 .LBB0_380

; #define PG8_STAGE(bufoff, gbase, voff) do { _Pragma("unroll") for (int _i = 0; _i < 2; ++_i) \
;         __builtin_amdgcn_global_load_lds((const unsigned*)((const char*)(gbase) + (voff)[_i]), (PG8_LAS unsigned*)(lds + (bufoff) + ldsw + _i * 8192), 16, 0, 0); } while (0)
; #define PG8_LDA(dst, b, h) do { _Pragma("unroll") for (int m = 0; m < 4; ++m) _Pragma("unroll") for (int k = 0; k < 2; ++k) dst[m][k] = *(const PG8_LAS bf16x8*)(lds + PG8_SA(b, h) + aoff + m * 2048 + k * 1024); } while (0)
; #define PG8_LDB(dst, b, h) do { _Pragma("unroll") for (int n = 0; n < 2; ++n) _Pragma("unroll") for (int k = 0; k < 2; ++k) dst[n][k] = *(const PG8_LAS bf16x8*)(lds + PG8_SB(b, h) + boff + n * 2048 + k * 1024); } while (0)
; #define PG8_MMA(ai, bj, At, Bt) do { __builtin_amdgcn_s_setprio(1); _Pragma("unroll") for (int m = 0; m < 4; ++m) _Pragma("unroll") for (int n = 0; n < 2; ++n) _Pragma("unroll") for (int k = 0; k < 2; ++k) \
;         acc[ai][bj][m][n] = __builtin_amdgcn_mfma_f32_16x16x32_bf16(Bt[n][k], At[m][k], acc[ai][bj][m][n], 0, 0, 0); __builtin_amdgcn_s_setprio(0); } while (0)
; #define PG8_BAR __builtin_amdgcn_s_barrier()
; template <class Epi, class Sched, bool ALIGN_EPI = false, bool SP2 = false>
; __device__ __forceinline__ void gemm_phase(PG8_LAS unsigned char* lds, const Gemm g, const Sched& S, const Epi& E) {
;     ...
;         const bool has_next = S.next(ui + 1, nxt);
;         const char* nA = has_next ? (const char*)g.A + (size_t)nxt.pm * tstep : cA; const char* nB = has_next ? (const char*)g.Bt + (size_t)nxt.pn * tstep : cB;
;         for (int t = 0; t < nt; t += 2) {
;             const bool last = (t == nt - 2);
;             const char* a1 = cA + (size_t)(t + 1) * kstep;
;             const char* a2 = last ? nA : cA + (size_t)(t + 2) * kstep; const char* b2 = last ? nB : cB + (size_t)(t + 2) * kstep;
;             const char* a3 = a2 + kstep; const char* b3 = b2 + kstep;
;             if (last && has_next) S.a_ready(nxt);
;             if constexpr (SP2) {
;             PG8_LDB(B0, 0, 0); PG8_LDB(B1, 0, 1); PG8_SCHED; PG8_LDA(At, 0, 0); PG8_STAGE(PG8_SA(1, 1), a1 + hstep, voffA);
;             PG8_WAIT_V(8); PG8_WAIT_L(0); PG8_BAR; PG8_MMA(0, 0, At, B0); PG8_MMA(0, 1, At, B1); PG8_BAR; PG8_SCHED;
;             PG8_LDA(At, 0, 1); PG8_STAGE(PG8_SB(0, 0), b2, voffB); PG8_STAGE(PG8_SB(0, 1), b2 + hstep, voffB); PG8_STAGE(PG8_SA(0, 0), a2, voffA);
.LBB0_697:
	s_ashr_i32 s17, s16, 31
	s_lshl_b64 s[18:19], s[16:17], 19
	v_readlane_b32 s48, v235, 2
	v_readlane_b32 s49, v235, 3
	s_add_u32 s18, s48, s18
	s_addc_u32 s19, s49, s19
	s_and_b64 s[20:21], s[6:7], exec
	s_cselect_b32 s17, s19, s27
	s_cselect_b32 s23, s18, s26
	s_ashr_i32 s15, s14, 31
	s_lshl_b64 s[20:21], s[14:15], 19
	s_add_u32 s20, s33, s20
	s_addc_u32 s21, s34, s21
	s_and_b64 s[30:31], s[6:7], exec
	s_cselect_b32 s15, s21, s29
	s_cselect_b32 s47, s20, s28
	s_add_u32 s26, s26, 0x40080
	s_addc_u32 s27, s27, 0
	v_readlane_b32 s50, v235, 4
	s_add_u32 s48, s28, 0x100
	s_addc_u32 s49, s29, 0
	s_mov_b32 s50, -2
	s_waitcnt lgkmcnt(0)
	v_readlane_b32 s51, v235, 5
	ds_read_b128 v[144:147], v151
	ds_read_b128 v[156:159], v151 offset:1024
	ds_read_b128 v[160:163], v151 offset:2048
	ds_read_b128 v[164:167], v151 offset:3072
	ds_read_b128 v[168:171], v152
	ds_read_b128 v[172:175], v152 offset:1024
	ds_read_b128 v[176:179], v152 offset:2048
	ds_read_b128 v[180:183], v152 offset:3072
	s_add_u32 s28, s26, 0xfffc0080
	s_addc_u32 s29, s27, -1
	s_cmp_eq_u32 s50, 12
	s_cselect_b32 s31, s17, s29
	s_cselect_b32 s30, s23, s28
	s_cselect_b32 s29, s15, s49
	s_cselect_b32 s28, s47, s48
	s_add_i32 m0, s25, 0xc000
	ds_read_b128 v[184:187], v153
	ds_read_b128 v[190:193], v153 offset:1024
	ds_read_b128 v[194:197], v153 offset:2048
	ds_read_b128 v[198:201], v153 offset:3072
	ds_read_b128 v[202:205], v153 offset:4096
	ds_read_b128 v[206:209], v153 offset:5120
	ds_read_b128 v[210:213], v153 offset:6144
	ds_read_b128 v[214:217], v153 offset:7168
	global_load_lds_dwordx4 v136, s[26:27]
	s_add_i32 m0, s25, 0xe000
	s_nop 0
	global_load_lds_dwordx4 v138, s[26:27]
	s_waitcnt vmcnt(8)
	s_waitcnt lgkmcnt(0)
	s_barrier
	s_setprio 1
	v_mfma_f32_16x16x32_bf16 v[124:127], v[144:147], v[184:187], 0
	v_mfma_f32_16x16x32_bf16 v[120:123], v[160:163], v[184:187], 0
	v_mfma_f32_16x16x32_bf16 v[108:111], v[144:147], v[194:197], 0
	v_mfma_f32_16x16x32_bf16 v[104:107], v[160:163], v[194:197], 0
	v_mfma_f32_16x16x32_bf16 v[92:95], v[144:147], v[202:205], 0
	v_mfma_f32_16x16x32_bf16 v[88:91], v[160:163], v[202:205], 0
	v_mfma_f32_16x16x32_bf16 v[76:79], v[144:147], v[210:213], 0
	v_mfma_f32_16x16x32_bf16 v[72:75], v[160:163], v[210:213], 0
	v_mfma_f32_16x16x32_bf16 v[124:127], v[156:159], v[190:193], v[124:127]
	v_mfma_f32_16x16x32_bf16 v[120:123], v[164:167], v[190:193], v[120:123]
	v_mfma_f32_16x16x32_bf16 v[108:111], v[156:159], v[198:201], v[108:111]
	v_mfma_f32_16x16x32_bf16 v[104:107], v[164:167], v[198:201], v[104:107]
	v_mfma_f32_16x16x32_bf16 v[92:95], v[156:159], v[206:209], v[92:95]
	v_mfma_f32_16x16x32_bf16 v[88:91], v[164:167], v[206:209], v[88:91]
	v_mfma_f32_16x16x32_bf16 v[76:79], v[156:159], v[214:217], v[76:79]
	v_mfma_f32_16x16x32_bf16 v[72:75], v[164:167], v[214:217], v[72:75]
	v_mfma_f32_16x16x32_bf16 v[116:119], v[168:171], v[184:187], 0
	v_mfma_f32_16x16x32_bf16 v[112:115], v[176:179], v[184:187], 0
	v_mfma_f32_16x16x32_bf16 v[100:103], v[168:171], v[194:197], 0
	v_mfma_f32_16x16x32_bf16 v[96:99], v[176:179], v[194:197], 0
	v_mfma_f32_16x16x32_bf16 v[84:87], v[168:171], v[202:205], 0
	v_mfma_f32_16x16x32_bf16 v[80:83], v[176:179], v[202:205], 0
	v_mfma_f32_16x16x32_bf16 v[68:71], v[168:171], v[210:213], 0
	v_mfma_f32_16x16x32_bf16 v[64:67], v[176:179], v[210:213], 0
	v_mfma_f32_16x16x32_bf16 v[116:119], v[172:175], v[190:193], v[116:119]
	v_mfma_f32_16x16x32_bf16 v[112:115], v[180:183], v[190:193], v[112:115]
	v_mfma_f32_16x16x32_bf16 v[100:103], v[172:175], v[198:201], v[100:103]
	v_mfma_f32_16x16x32_bf16 v[96:99], v[180:183], v[198:201], v[96:99]
	v_mfma_f32_16x16x32_bf16 v[84:87], v[172:175], v[206:209], v[84:87]
	v_mfma_f32_16x16x32_bf16 v[80:83], v[180:183], v[206:209], v[80:83]
	v_mfma_f32_16x16x32_bf16 v[68:71], v[172:175], v[214:217], v[68:71]
	v_mfma_f32_16x16x32_bf16 v[64:67], v[180:183], v[214:217], v[64:67]
	s_setprio 0
	s_barrier
	s_add_i32 s51, s45, s35
	v_lshl_add_u64 v[218:219], s[28:29], 0, v[130:131]
	s_mov_b32 m0, s51
	ds_read_b128 v[184:187], v153 offset:16384
	ds_read_b128 v[190:193], v153 offset:17408
	ds_read_b128 v[194:197], v153 offset:18432
	ds_read_b128 v[198:201], v153 offset:19456
	ds_read_b128 v[202:205], v153 offset:20480
	ds_read_b128 v[206:209], v153 offset:21504
	ds_read_b128 v[210:213], v153 offset:22528
	ds_read_b128 v[214:217], v153 offset:23552
	global_load_lds_dwordx4 v[218:219], off
	s_add_i32 m0, s51, 0x2000
	s_add_u32 s52, s28, 0x40000
	v_lshl_add_u64 v[220:221], s[28:29], 0, v[134:135]
	s_addc_u32 s53, s29, 0
	s_add_i32 s51, s46, s35
	global_load_lds_dwordx4 v[220:221], off
	s_mov_b32 m0, s51
	v_lshl_add_u64 v[224:225], s[30:31], 0, v[132:133]
	global_load_lds_dwordx4 v130, s[52:53]
	s_add_i32 m0, s51, 0x2000
	s_nop 0
	global_load_lds_dwordx4 v134, s[52:53]
	v_lshl_add_u64 v[222:223], s[30:31], 0, v[128:129]
	s_mov_b32 m0, s25
	s_nop 0
	global_load_lds_dwordx4 v[222:223], off
	s_mov_b32 m0, s36
	s_nop 0
	global_load_lds_dwordx4 v[224:225], off
	s_waitcnt vmcnt(8)
	s_waitcnt lgkmcnt(0)
	s_barrier
; #define PG8_STAGE(bufoff, gbase, voff) do { _Pragma("unroll") for (int _i = 0; _i < 2; ++_i) \
;         __builtin_amdgcn_global_load_lds((const unsigned*)((const char*)(gbase) + (voff)[_i]), (PG8_LAS unsigned*)(lds + (bufoff) + ldsw + _i * 8192), 16, 0, 0); } while (0)
; #define PG8_LDA(dst, b, h) do { _Pragma("unroll") for (int m = 0; m < 4; ++m) _Pragma("unroll") for (int k = 0; k < 2; ++k) dst[m][k] = *(const PG8_LAS bf16x8*)(lds + PG8_SA(b, h) + aoff + m * 2048 + k * 1024); } while (0)
; #define PG8_LDB(dst, b, h) do { _Pragma("unroll") for (int n = 0; n < 2; ++n) _Pragma("unroll") for (int k = 0; k < 2; ++k) dst[n][k] = *(const PG8_LAS bf16x8*)(lds + PG8_SB(b, h) + boff + n * 2048 + k * 1024); } while (0)
; #define PG8_MMA(ai, bj, At, Bt) do { __builtin_amdgcn_s_setprio(1); _Pragma("unroll") for (int m = 0; m < 4; ++m) _Pragma("unroll") for (int n = 0; n < 2; ++n) _Pragma("unroll") for (int k = 0; k < 2; ++k) \
;         acc[ai][bj][m][n] = __builtin_amdgcn_mfma_f32_16x16x32_bf16(Bt[n][k], At[m][k], acc[ai][bj][m][n], 0, 0, 0); __builtin_amdgcn_s_setprio(0); } while (0)
; #define PG8_WAIT_V(n) asm volatile("s_waitcnt vmcnt(" #n ")" ::: "memory")
; #define PG8_WAIT_L(n) asm volatile("s_waitcnt lgkmcnt(" #n ")" ::: "memory")
; #define PG8_BAR __builtin_amdgcn_s_barrier()
; #define PG8_SCHED __builtin_amdgcn_sched_barrier(0)
; template <class Epi, class Sched, bool ALIGN_EPI = false, bool SP2 = false>
; __device__ __forceinline__ void gemm_phase(PG8_LAS unsigned char* lds, const Gemm g, const Sched& S, const Epi& E) {
;     ...
;             PG8_WAIT_V(8); PG8_WAIT_L(0); PG8_BAR; PG8_MMA(1, 0, At, B0); PG8_MMA(1, 1, At, B1); PG8_BAR; PG8_SCHED;
;             PG8_LDB(B0, 1, 0); PG8_LDB(B1, 1, 1); PG8_SCHED; PG8_LDA(At, 1, 0); PG8_STAGE(PG8_SA(0, 1), a2 + hstep, voffA);
;             PG8_WAIT_V(8); PG8_WAIT_L(0); PG8_BAR; PG8_MMA(0, 0, At, B0); PG8_MMA(0, 1, At, B1); PG8_BAR; PG8_SCHED;
	s_setprio 1
	v_mfma_f32_16x16x32_bf16 v[60:63], v[144:147], v[184:187], 0
	v_mfma_f32_16x16x32_bf16 v[56:59], v[160:163], v[184:187], 0
	v_mfma_f32_16x16x32_bf16 v[44:47], v[144:147], v[194:197], 0
	v_mfma_f32_16x16x32_bf16 v[40:43], v[160:163], v[194:197], 0
	v_mfma_f32_16x16x32_bf16 v[28:31], v[144:147], v[202:205], 0
	v_mfma_f32_16x16x32_bf16 v[24:27], v[160:163], v[202:205], 0
	v_mfma_f32_16x16x32_bf16 v[12:15], v[144:147], v[210:213], 0
	v_mfma_f32_16x16x32_bf16 v[8:11], v[160:163], v[210:213], 0
	v_mfma_f32_16x16x32_bf16 v[60:63], v[156:159], v[190:193], v[60:63]
	v_mfma_f32_16x16x32_bf16 v[56:59], v[164:167], v[190:193], v[56:59]
	v_mfma_f32_16x16x32_bf16 v[44:47], v[156:159], v[198:201], v[44:47]
	v_mfma_f32_16x16x32_bf16 v[40:43], v[164:167], v[198:201], v[40:43]
	v_mfma_f32_16x16x32_bf16 v[28:31], v[156:159], v[206:209], v[28:31]
	v_mfma_f32_16x16x32_bf16 v[24:27], v[164:167], v[206:209], v[24:27]
	v_mfma_f32_16x16x32_bf16 v[12:15], v[156:159], v[214:217], v[12:15]
	v_mfma_f32_16x16x32_bf16 v[8:11], v[164:167], v[214:217], v[8:11]
	v_mfma_f32_16x16x32_bf16 v[52:55], v[168:171], v[184:187], 0
	v_mfma_f32_16x16x32_bf16 v[48:51], v[176:179], v[184:187], 0
	v_mfma_f32_16x16x32_bf16 v[36:39], v[168:171], v[194:197], 0
	v_mfma_f32_16x16x32_bf16 v[32:35], v[176:179], v[194:197], 0
	v_mfma_f32_16x16x32_bf16 v[20:23], v[168:171], v[202:205], 0
	v_mfma_f32_16x16x32_bf16 v[16:19], v[176:179], v[202:205], 0
	v_mfma_f32_16x16x32_bf16 v[4:7], v[168:171], v[210:213], 0
	v_mfma_f32_16x16x32_bf16 v[0:3], v[176:179], v[210:213], 0
	v_mfma_f32_16x16x32_bf16 v[52:55], v[172:175], v[190:193], v[52:55]
	v_mfma_f32_16x16x32_bf16 v[48:51], v[180:183], v[190:193], v[48:51]
	v_mfma_f32_16x16x32_bf16 v[36:39], v[172:175], v[198:201], v[36:39]
	v_mfma_f32_16x16x32_bf16 v[32:35], v[180:183], v[198:201], v[32:35]
	v_mfma_f32_16x16x32_bf16 v[20:23], v[172:175], v[206:209], v[20:23]
	v_mfma_f32_16x16x32_bf16 v[16:19], v[180:183], v[206:209], v[16:19]
	v_mfma_f32_16x16x32_bf16 v[4:7], v[172:175], v[214:217], v[4:7]
	v_mfma_f32_16x16x32_bf16 v[0:3], v[180:183], v[214:217], v[0:3]
	s_setprio 0
	s_barrier
	s_add_i32 s51, 0, 0x18000
	v_add_u32_e32 v155, s51, v149
	s_add_i32 s52, 0, 0x1c000
	ds_read_b128 v[144:147], v155
	ds_read_b128 v[156:159], v155 offset:1024
	ds_read_b128 v[160:163], v155 offset:2048
	ds_read_b128 v[164:167], v155 offset:3072
	v_add_u32_e32 v155, s52, v149
	ds_read_b128 v[168:171], v155
	ds_read_b128 v[172:175], v155 offset:1024
	ds_read_b128 v[176:179], v155 offset:2048
	ds_read_b128 v[180:183], v155 offset:3072
	s_add_u32 s30, s30, 0x40000
	s_addc_u32 s31, s31, 0
	s_mov_b32 m0, s37
	ds_read_b128 v[184:187], v153 offset:32768
	ds_read_b128 v[190:193], v153 offset:33792
	ds_read_b128 v[194:197], v153 offset:34816
	ds_read_b128 v[198:201], v153 offset:35840
	ds_read_b128 v[202:205], v153 offset:36864
	ds_read_b128 v[206:209], v153 offset:37888
	ds_read_b128 v[210:213], v153 offset:38912
	ds_read_b128 v[214:217], v153 offset:39936
	global_load_lds_dwordx4 v128, s[30:31]
	v_lshl_add_u64 v[226:227], s[30:31], 0, v[132:133]
	s_mov_b32 m0, s38
	s_nop 0
	global_load_lds_dwordx4 v[226:227], off
	s_waitcnt vmcnt(8)
	s_waitcnt lgkmcnt(0)
	s_barrier
	s_setprio 1
	v_mfma_f32_16x16x32_bf16 v[124:127], v[144:147], v[184:187], v[124:127]
	v_mfma_f32_16x16x32_bf16 v[120:123], v[160:163], v[184:187], v[120:123]
	v_mfma_f32_16x16x32_bf16 v[108:111], v[144:147], v[194:197], v[108:111]
	v_mfma_f32_16x16x32_bf16 v[104:107], v[160:163], v[194:197], v[104:107]
	v_mfma_f32_16x16x32_bf16 v[92:95], v[144:147], v[202:205], v[92:95]
	v_mfma_f32_16x16x32_bf16 v[88:91], v[160:163], v[202:205], v[88:91]
	v_mfma_f32_16x16x32_bf16 v[76:79], v[144:147], v[210:213], v[76:79]
	v_mfma_f32_16x16x32_bf16 v[72:75], v[160:163], v[210:213], v[72:75]
	v_mfma_f32_16x16x32_bf16 v[124:127], v[156:159], v[190:193], v[124:127]
	v_mfma_f32_16x16x32_bf16 v[120:123], v[164:167], v[190:193], v[120:123]
	v_mfma_f32_16x16x32_bf16 v[108:111], v[156:159], v[198:201], v[108:111]
	v_mfma_f32_16x16x32_bf16 v[104:107], v[164:167], v[198:201], v[104:107]
	v_mfma_f32_16x16x32_bf16 v[92:95], v[156:159], v[206:209], v[92:95]
	v_mfma_f32_16x16x32_bf16 v[88:91], v[164:167], v[206:209], v[88:91]
	v_mfma_f32_16x16x32_bf16 v[76:79], v[156:159], v[214:217], v[76:79]
	v_mfma_f32_16x16x32_bf16 v[72:75], v[164:167], v[214:217], v[72:75]
	v_mfma_f32_16x16x32_bf16 v[116:119], v[168:171], v[184:187], v[116:119]
	v_mfma_f32_16x16x32_bf16 v[112:115], v[176:179], v[184:187], v[112:115]
	v_mfma_f32_16x16x32_bf16 v[100:103], v[168:171], v[194:197], v[100:103]
	v_mfma_f32_16x16x32_bf16 v[96:99], v[176:179], v[194:197], v[96:99]
	v_mfma_f32_16x16x32_bf16 v[84:87], v[168:171], v[202:205], v[84:87]
	v_mfma_f32_16x16x32_bf16 v[80:83], v[176:179], v[202:205], v[80:83]
	v_mfma_f32_16x16x32_bf16 v[68:71], v[168:171], v[210:213], v[68:71]
	v_mfma_f32_16x16x32_bf16 v[64:67], v[176:179], v[210:213], v[64:67]
	v_mfma_f32_16x16x32_bf16 v[116:119], v[172:175], v[190:193], v[116:119]
	v_mfma_f32_16x16x32_bf16 v[112:115], v[180:183], v[190:193], v[112:115]
	v_mfma_f32_16x16x32_bf16 v[100:103], v[172:175], v[198:201], v[100:103]
	v_mfma_f32_16x16x32_bf16 v[96:99], v[180:183], v[198:201], v[96:99]
	v_mfma_f32_16x16x32_bf16 v[84:87], v[172:175], v[206:209], v[84:87]
	v_mfma_f32_16x16x32_bf16 v[80:83], v[180:183], v[206:209], v[80:83]
	v_mfma_f32_16x16x32_bf16 v[68:71], v[172:175], v[214:217], v[68:71]
	v_mfma_f32_16x16x32_bf16 v[64:67], v[180:183], v[214:217], v[64:67]
	s_setprio 0
	s_barrier
; #define PG8_STAGE(bufoff, gbase, voff) do { _Pragma("unroll") for (int _i = 0; _i < 2; ++_i) \
;         __builtin_amdgcn_global_load_lds((const unsigned*)((const char*)(gbase) + (voff)[_i]), (PG8_LAS unsigned*)(lds + (bufoff) + ldsw + _i * 8192), 16, 0, 0); } while (0)
; #define PG8_LDA(dst, b, h) do { _Pragma("unroll") for (int m = 0; m < 4; ++m) _Pragma("unroll") for (int k = 0; k < 2; ++k) dst[m][k] = *(const PG8_LAS bf16x8*)(lds + PG8_SA(b, h) + aoff + m * 2048 + k * 1024); } while (0)
; #define PG8_LDB(dst, b, h) do { _Pragma("unroll") for (int n = 0; n < 2; ++n) _Pragma("unroll") for (int k = 0; k < 2; ++k) dst[n][k] = *(const PG8_LAS bf16x8*)(lds + PG8_SB(b, h) + boff + n * 2048 + k * 1024); } while (0)
; template <class Epi, class Sched, bool ALIGN_EPI = false, bool SP2 = false>
; __device__ __forceinline__ void gemm_phase(PG8_LAS unsigned char* lds, const Gemm g, const Sched& S, const Epi& E) {
;     ...
;         for (int t = 0; t < nt; t += 2) {
;             const bool last = (t == nt - 2);
;             const char* a1 = cA + (size_t)(t + 1) * kstep;
;             const char* a2 = last ? nA : cA + (size_t)(t + 2) * kstep; const char* b2 = last ? nB : cB + (size_t)(t + 2) * kstep;
;             const char* a3 = a2 + kstep; const char* b3 = b2 + kstep;
;             if (last && has_next) S.a_ready(nxt);
;             if constexpr (SP2) {
;             PG8_LDB(B0, 0, 0); PG8_LDB(B1, 0, 1); PG8_SCHED; PG8_LDA(At, 0, 0); PG8_STAGE(PG8_SA(1, 1), a1 + hstep, voffA);
;             PG8_WAIT_V(8); PG8_WAIT_L(0); PG8_BAR; PG8_MMA(0, 0, At, B0); PG8_MMA(0, 1, At, B1); PG8_BAR; PG8_SCHED;
;             PG8_LDA(At, 0, 1); PG8_STAGE(PG8_SB(0, 0), b2, voffB); PG8_STAGE(PG8_SB(0, 1), b2 + hstep, voffB); PG8_STAGE(PG8_SA(0, 0), a2, voffA);
;             PG8_WAIT_V(8); PG8_WAIT_L(0); PG8_BAR; PG8_MMA(1, 0, At, B0); PG8_MMA(1, 1, At, B1); PG8_BAR; PG8_SCHED;
;             PG8_LDB(B0, 1, 0); PG8_LDB(B1, 1, 1); PG8_SCHED; PG8_LDA(At, 1, 0); PG8_STAGE(PG8_SA(0, 1), a2 + hstep, voffA);
;             PG8_WAIT_V(8); PG8_WAIT_L(0); PG8_BAR; PG8_MMA(0, 0, At, B0); PG8_MMA(0, 1, At, B1); PG8_BAR; PG8_SCHED;
;             PG8_LDA(At, 1, 1); PG8_STAGE(PG8_SB(1, 0), b3, voffB); PG8_STAGE(PG8_SB(1, 1), b3 + hstep, voffB); PG8_STAGE(PG8_SA(1, 0), a3, voffA);
;             PG8_WAIT_V(8); PG8_WAIT_L(0); PG8_BAR; PG8_MMA(1, 0, At, B0); PG8_MMA(1, 1, At, B1); PG8_BAR; PG8_SCHED;
	s_add_i32 s30, s51, s35
	v_lshl_add_u64 v[218:219], v[218:219], 0, s[2:3]
	s_mov_b32 m0, s30
	ds_read_b128 v[184:187], v153 offset:49152
	ds_read_b128 v[190:193], v153 offset:50176
	ds_read_b128 v[194:197], v153 offset:51200
	ds_read_b128 v[198:201], v153 offset:52224
	ds_read_b128 v[202:205], v153 offset:53248
	ds_read_b128 v[206:209], v153 offset:54272
	ds_read_b128 v[210:213], v153 offset:55296
	ds_read_b128 v[214:217], v153 offset:56320
	global_load_lds_dwordx4 v[218:219], off
	s_add_i32 m0, s30, 0x2000
	s_add_u32 s28, s28, 0x40080
	v_lshl_add_u64 v[218:219], v[220:221], 0, s[2:3]
	s_addc_u32 s29, s29, 0
	s_add_i32 s30, s52, s35
	global_load_lds_dwordx4 v[218:219], off
	s_mov_b32 m0, s30
	s_nop 0
	global_load_lds_dwordx4 v130, s[28:29]
	s_add_i32 m0, s30, 0x2000
	s_nop 0
	global_load_lds_dwordx4 v134, s[28:29]
	v_lshl_add_u64 v[218:219], v[222:223], 0, s[2:3]
	s_mov_b32 m0, s40
	s_nop 0
	global_load_lds_dwordx4 v[218:219], off
	v_lshl_add_u64 v[218:219], v[224:225], 0, s[2:3]
	s_mov_b32 m0, s41
	s_nop 0
	global_load_lds_dwordx4 v[218:219], off
	s_waitcnt vmcnt(8)
	s_waitcnt lgkmcnt(0)
	s_barrier
	s_setprio 1
	v_mfma_f32_16x16x32_bf16 v[60:63], v[144:147], v[184:187], v[60:63]
	v_mfma_f32_16x16x32_bf16 v[56:59], v[160:163], v[184:187], v[56:59]
	v_mfma_f32_16x16x32_bf16 v[44:47], v[144:147], v[194:197], v[44:47]
	v_mfma_f32_16x16x32_bf16 v[40:43], v[160:163], v[194:197], v[40:43]
	v_mfma_f32_16x16x32_bf16 v[28:31], v[144:147], v[202:205], v[28:31]
	v_mfma_f32_16x16x32_bf16 v[24:27], v[160:163], v[202:205], v[24:27]
	v_mfma_f32_16x16x32_bf16 v[12:15], v[144:147], v[210:213], v[12:15]
	v_mfma_f32_16x16x32_bf16 v[8:11], v[160:163], v[210:213], v[8:11]
	v_mfma_f32_16x16x32_bf16 v[60:63], v[156:159], v[190:193], v[60:63]
	v_mfma_f32_16x16x32_bf16 v[56:59], v[164:167], v[190:193], v[56:59]
	v_mfma_f32_16x16x32_bf16 v[44:47], v[156:159], v[198:201], v[44:47]
	v_mfma_f32_16x16x32_bf16 v[40:43], v[164:167], v[198:201], v[40:43]
	v_mfma_f32_16x16x32_bf16 v[28:31], v[156:159], v[206:209], v[28:31]
	v_mfma_f32_16x16x32_bf16 v[24:27], v[164:167], v[206:209], v[24:27]
	v_mfma_f32_16x16x32_bf16 v[12:15], v[156:159], v[214:217], v[12:15]
	v_mfma_f32_16x16x32_bf16 v[8:11], v[164:167], v[214:217], v[8:11]
	v_mfma_f32_16x16x32_bf16 v[52:55], v[168:171], v[184:187], v[52:55]
	v_mfma_f32_16x16x32_bf16 v[48:51], v[176:179], v[184:187], v[48:51]
	v_mfma_f32_16x16x32_bf16 v[36:39], v[168:171], v[194:197], v[36:39]
	v_mfma_f32_16x16x32_bf16 v[32:35], v[176:179], v[194:197], v[32:35]
	v_mfma_f32_16x16x32_bf16 v[20:23], v[168:171], v[202:205], v[20:23]
	v_mfma_f32_16x16x32_bf16 v[16:19], v[176:179], v[202:205], v[16:19]
	v_mfma_f32_16x16x32_bf16 v[4:7], v[168:171], v[210:213], v[4:7]
	v_mfma_f32_16x16x32_bf16 v[0:3], v[176:179], v[210:213], v[0:3]
	v_mfma_f32_16x16x32_bf16 v[52:55], v[172:175], v[190:193], v[52:55]
	v_mfma_f32_16x16x32_bf16 v[48:51], v[180:183], v[190:193], v[48:51]
	v_mfma_f32_16x16x32_bf16 v[36:39], v[172:175], v[198:201], v[36:39]
	v_mfma_f32_16x16x32_bf16 v[32:35], v[180:183], v[198:201], v[32:35]
	v_mfma_f32_16x16x32_bf16 v[20:23], v[172:175], v[206:209], v[20:23]
	v_mfma_f32_16x16x32_bf16 v[16:19], v[180:183], v[206:209], v[16:19]
	v_mfma_f32_16x16x32_bf16 v[4:7], v[172:175], v[214:217], v[4:7]
	v_mfma_f32_16x16x32_bf16 v[0:3], v[180:183], v[214:217], v[0:3]
	s_setprio 0
	s_barrier
	s_add_i32 s50, s50, 2
	s_add_u32 s26, s26, 0x100
	s_addc_u32 s27, s27, 0
	s_add_u32 s48, s48, 0x100
	s_addc_u32 s49, s49, 0
.LBB0_698:
	ds_read_b128 v[144:147], v151
	ds_read_b128 v[156:159], v151 offset:1024
	ds_read_b128 v[160:163], v151 offset:2048
	ds_read_b128 v[164:167], v151 offset:3072
	ds_read_b128 v[168:171], v152
	ds_read_b128 v[172:175], v152 offset:1024
	ds_read_b128 v[176:179], v152 offset:2048
	ds_read_b128 v[180:183], v152 offset:3072
	s_add_u32 s28, s26, 0xfffc0080
	s_addc_u32 s29, s27, -1
	s_cmp_eq_u32 s50, 12
	s_cselect_b32 s31, s17, s29
	s_cselect_b32 s30, s23, s28
	s_cselect_b32 s29, s15, s49
	s_cselect_b32 s28, s47, s48
	s_add_i32 m0, s25, 0xc000
	ds_read_b128 v[184:187], v153
	ds_read_b128 v[190:193], v153 offset:1024
	ds_read_b128 v[194:197], v153 offset:2048
	ds_read_b128 v[198:201], v153 offset:3072
	ds_read_b128 v[202:205], v153 offset:4096
	ds_read_b128 v[206:209], v153 offset:5120
	ds_read_b128 v[210:213], v153 offset:6144
	ds_read_b128 v[214:217], v153 offset:7168
	global_load_lds_dwordx4 v136, s[26:27]
	s_add_i32 m0, s25, 0xe000
	s_nop 0
	global_load_lds_dwordx4 v138, s[26:27]
	s_waitcnt vmcnt(8)
	s_waitcnt lgkmcnt(0)
	s_barrier
; #define PG8_STAGE(bufoff, gbase, voff) do { _Pragma("unroll") for (int _i = 0; _i < 2; ++_i) \
;         __builtin_amdgcn_global_load_lds((const unsigned*)((const char*)(gbase) + (voff)[_i]), (PG8_LAS unsigned*)(lds + (bufoff) + ldsw + _i * 8192), 16, 0, 0); } while (0)
; #define PG8_LDA(dst, b, h) do { _Pragma("unroll") for (int m = 0; m < 4; ++m) _Pragma("unroll") for (int k = 0; k < 2; ++k) dst[m][k] = *(const PG8_LAS bf16x8*)(lds + PG8_SA(b, h) + aoff + m * 2048 + k * 1024); } while (0)
; #define PG8_MMA(ai, bj, At, Bt) do { __builtin_amdgcn_s_setprio(1); _Pragma("unroll") for (int m = 0; m < 4; ++m) _Pragma("unroll") for (int n = 0; n < 2; ++n) _Pragma("unroll") for (int k = 0; k < 2; ++k) \
;         acc[ai][bj][m][n] = __builtin_amdgcn_mfma_f32_16x16x32_bf16(Bt[n][k], At[m][k], acc[ai][bj][m][n], 0, 0, 0); __builtin_amdgcn_s_setprio(0); } while (0)
; #define PG8_WAIT_V(n) asm volatile("s_waitcnt vmcnt(" #n ")" ::: "memory")
; #define PG8_WAIT_L(n) asm volatile("s_waitcnt lgkmcnt(" #n ")" ::: "memory")
; #define PG8_BAR __builtin_amdgcn_s_barrier()
; #define PG8_SCHED __builtin_amdgcn_sched_barrier(0)
; template <class Epi, class Sched, bool ALIGN_EPI = false, bool SP2 = false>
; __device__ __forceinline__ void gemm_phase(PG8_LAS unsigned char* lds, const Gemm g, const Sched& S, const Epi& E) {
;     ...
;             PG8_WAIT_V(8); PG8_WAIT_L(0); PG8_BAR; PG8_MMA(0, 0, At, B0); PG8_MMA(0, 1, At, B1); PG8_BAR; PG8_SCHED;
;             PG8_LDA(At, 0, 1); PG8_STAGE(PG8_SB(0, 0), b2, voffB); PG8_STAGE(PG8_SB(0, 1), b2 + hstep, voffB); PG8_STAGE(PG8_SA(0, 0), a2, voffA);
;             PG8_WAIT_V(8); PG8_WAIT_L(0); PG8_BAR; PG8_MMA(1, 0, At, B0); PG8_MMA(1, 1, At, B1); PG8_BAR; PG8_SCHED;
	s_setprio 1
	v_mfma_f32_16x16x32_bf16 v[124:127], v[144:147], v[184:187], v[124:127]
	v_mfma_f32_16x16x32_bf16 v[120:123], v[160:163], v[184:187], v[120:123]
	v_mfma_f32_16x16x32_bf16 v[108:111], v[144:147], v[194:197], v[108:111]
	v_mfma_f32_16x16x32_bf16 v[104:107], v[160:163], v[194:197], v[104:107]
	v_mfma_f32_16x16x32_bf16 v[92:95], v[144:147], v[202:205], v[92:95]
	v_mfma_f32_16x16x32_bf16 v[88:91], v[160:163], v[202:205], v[88:91]
	v_mfma_f32_16x16x32_bf16 v[76:79], v[144:147], v[210:213], v[76:79]
	v_mfma_f32_16x16x32_bf16 v[72:75], v[160:163], v[210:213], v[72:75]
	v_mfma_f32_16x16x32_bf16 v[124:127], v[156:159], v[190:193], v[124:127]
	v_mfma_f32_16x16x32_bf16 v[120:123], v[164:167], v[190:193], v[120:123]
	v_mfma_f32_16x16x32_bf16 v[108:111], v[156:159], v[198:201], v[108:111]
	v_mfma_f32_16x16x32_bf16 v[104:107], v[164:167], v[198:201], v[104:107]
	v_mfma_f32_16x16x32_bf16 v[92:95], v[156:159], v[206:209], v[92:95]
	v_mfma_f32_16x16x32_bf16 v[88:91], v[164:167], v[206:209], v[88:91]
	v_mfma_f32_16x16x32_bf16 v[76:79], v[156:159], v[214:217], v[76:79]
	v_mfma_f32_16x16x32_bf16 v[72:75], v[164:167], v[214:217], v[72:75]
	v_mfma_f32_16x16x32_bf16 v[116:119], v[168:171], v[184:187], v[116:119]
	v_mfma_f32_16x16x32_bf16 v[112:115], v[176:179], v[184:187], v[112:115]
	v_mfma_f32_16x16x32_bf16 v[100:103], v[168:171], v[194:197], v[100:103]
	v_mfma_f32_16x16x32_bf16 v[96:99], v[176:179], v[194:197], v[96:99]
	v_mfma_f32_16x16x32_bf16 v[84:87], v[168:171], v[202:205], v[84:87]
	v_mfma_f32_16x16x32_bf16 v[80:83], v[176:179], v[202:205], v[80:83]
	v_mfma_f32_16x16x32_bf16 v[68:71], v[168:171], v[210:213], v[68:71]
	v_mfma_f32_16x16x32_bf16 v[64:67], v[176:179], v[210:213], v[64:67]
	v_mfma_f32_16x16x32_bf16 v[116:119], v[172:175], v[190:193], v[116:119]
	v_mfma_f32_16x16x32_bf16 v[112:115], v[180:183], v[190:193], v[112:115]
	v_mfma_f32_16x16x32_bf16 v[100:103], v[172:175], v[198:201], v[100:103]
	v_mfma_f32_16x16x32_bf16 v[96:99], v[180:183], v[198:201], v[96:99]
	v_mfma_f32_16x16x32_bf16 v[84:87], v[172:175], v[206:209], v[84:87]
	v_mfma_f32_16x16x32_bf16 v[80:83], v[180:183], v[206:209], v[80:83]
	v_mfma_f32_16x16x32_bf16 v[68:71], v[172:175], v[214:217], v[68:71]
	v_mfma_f32_16x16x32_bf16 v[64:67], v[180:183], v[214:217], v[64:67]
	s_setprio 0
	s_barrier
	s_add_i32 s51, s45, s35
	v_lshl_add_u64 v[218:219], s[28:29], 0, v[130:131]
	s_mov_b32 m0, s51
	ds_read_b128 v[184:187], v153 offset:16384
	ds_read_b128 v[190:193], v153 offset:17408
	ds_read_b128 v[194:197], v153 offset:18432
	ds_read_b128 v[198:201], v153 offset:19456
	ds_read_b128 v[202:205], v153 offset:20480
	ds_read_b128 v[206:209], v153 offset:21504
	ds_read_b128 v[210:213], v153 offset:22528
	ds_read_b128 v[214:217], v153 offset:23552
	global_load_lds_dwordx4 v[218:219], off
	s_add_i32 m0, s51, 0x2000
	s_add_u32 s52, s28, 0x40000
	v_lshl_add_u64 v[220:221], s[28:29], 0, v[134:135]
	s_addc_u32 s53, s29, 0
	s_add_i32 s51, s46, s35
	global_load_lds_dwordx4 v[220:221], off
	s_mov_b32 m0, s51
	v_lshl_add_u64 v[224:225], s[30:31], 0, v[132:133]
	global_load_lds_dwordx4 v130, s[52:53]
	s_add_i32 m0, s51, 0x2000
	s_nop 0
	global_load_lds_dwordx4 v134, s[52:53]
	v_lshl_add_u64 v[222:223], s[30:31], 0, v[128:129]
	s_mov_b32 m0, s25
	s_nop 0
	global_load_lds_dwordx4 v[222:223], off
	s_mov_b32 m0, s36
	s_nop 0
	global_load_lds_dwordx4 v[224:225], off
	s_waitcnt vmcnt(8)
	s_waitcnt lgkmcnt(0)
	s_barrier
	s_setprio 1
	v_mfma_f32_16x16x32_bf16 v[60:63], v[144:147], v[184:187], v[60:63]
	v_mfma_f32_16x16x32_bf16 v[56:59], v[160:163], v[184:187], v[56:59]
	v_mfma_f32_16x16x32_bf16 v[44:47], v[144:147], v[194:197], v[44:47]
	v_mfma_f32_16x16x32_bf16 v[40:43], v[160:163], v[194:197], v[40:43]
	v_mfma_f32_16x16x32_bf16 v[28:31], v[144:147], v[202:205], v[28:31]
	v_mfma_f32_16x16x32_bf16 v[24:27], v[160:163], v[202:205], v[24:27]
	v_mfma_f32_16x16x32_bf16 v[12:15], v[144:147], v[210:213], v[12:15]
	v_mfma_f32_16x16x32_bf16 v[8:11], v[160:163], v[210:213], v[8:11]
	v_mfma_f32_16x16x32_bf16 v[60:63], v[156:159], v[190:193], v[60:63]
	v_mfma_f32_16x16x32_bf16 v[56:59], v[164:167], v[190:193], v[56:59]
	v_mfma_f32_16x16x32_bf16 v[44:47], v[156:159], v[198:201], v[44:47]
	v_mfma_f32_16x16x32_bf16 v[40:43], v[164:167], v[198:201], v[40:43]
	v_mfma_f32_16x16x32_bf16 v[28:31], v[156:159], v[206:209], v[28:31]
	v_mfma_f32_16x16x32_bf16 v[24:27], v[164:167], v[206:209], v[24:27]
	v_mfma_f32_16x16x32_bf16 v[12:15], v[156:159], v[214:217], v[12:15]
	v_mfma_f32_16x16x32_bf16 v[8:11], v[164:167], v[214:217], v[8:11]
	v_mfma_f32_16x16x32_bf16 v[52:55], v[168:171], v[184:187], v[52:55]
	v_mfma_f32_16x16x32_bf16 v[48:51], v[176:179], v[184:187], v[48:51]
	v_mfma_f32_16x16x32_bf16 v[36:39], v[168:171], v[194:197], v[36:39]
	v_mfma_f32_16x16x32_bf16 v[32:35], v[176:179], v[194:197], v[32:35]
	v_mfma_f32_16x16x32_bf16 v[20:23], v[168:171], v[202:205], v[20:23]
	v_mfma_f32_16x16x32_bf16 v[16:19], v[176:179], v[202:205], v[16:19]
	v_mfma_f32_16x16x32_bf16 v[4:7], v[168:171], v[210:213], v[4:7]
	v_mfma_f32_16x16x32_bf16 v[0:3], v[176:179], v[210:213], v[0:3]
	v_mfma_f32_16x16x32_bf16 v[52:55], v[172:175], v[190:193], v[52:55]
	v_mfma_f32_16x16x32_bf16 v[48:51], v[180:183], v[190:193], v[48:51]
	v_mfma_f32_16x16x32_bf16 v[36:39], v[172:175], v[198:201], v[36:39]
	v_mfma_f32_16x16x32_bf16 v[32:35], v[180:183], v[198:201], v[32:35]
	v_mfma_f32_16x16x32_bf16 v[20:23], v[172:175], v[206:209], v[20:23]
	v_mfma_f32_16x16x32_bf16 v[16:19], v[180:183], v[206:209], v[16:19]
	v_mfma_f32_16x16x32_bf16 v[4:7], v[172:175], v[214:217], v[4:7]
	v_mfma_f32_16x16x32_bf16 v[0:3], v[180:183], v[214:217], v[0:3]
	s_setprio 0
	s_barrier
; #define PG8_STAGE(bufoff, gbase, voff) do { _Pragma("unroll") for (int _i = 0; _i < 2; ++_i) \
;         __builtin_amdgcn_global_load_lds((const unsigned*)((const char*)(gbase) + (voff)[_i]), (PG8_LAS unsigned*)(lds + (bufoff) + ldsw + _i * 8192), 16, 0, 0); } while (0)
; #define PG8_LDA(dst, b, h) do { _Pragma("unroll") for (int m = 0; m < 4; ++m) _Pragma("unroll") for (int k = 0; k < 2; ++k) dst[m][k] = *(const PG8_LAS bf16x8*)(lds + PG8_SA(b, h) + aoff + m * 2048 + k * 1024); } while (0)
; #define PG8_LDB(dst, b, h) do { _Pragma("unroll") for (int n = 0; n < 2; ++n) _Pragma("unroll") for (int k = 0; k < 2; ++k) dst[n][k] = *(const PG8_LAS bf16x8*)(lds + PG8_SB(b, h) + boff + n * 2048 + k * 1024); } while (0)
; #define PG8_MMA(ai, bj, At, Bt) do { __builtin_amdgcn_s_setprio(1); _Pragma("unroll") for (int m = 0; m < 4; ++m) _Pragma("unroll") for (int n = 0; n < 2; ++n) _Pragma("unroll") for (int k = 0; k < 2; ++k) \
;         acc[ai][bj][m][n] = __builtin_amdgcn_mfma_f32_16x16x32_bf16(Bt[n][k], At[m][k], acc[ai][bj][m][n], 0, 0, 0); __builtin_amdgcn_s_setprio(0); } while (0)
; #define PG8_WAIT_V(n) asm volatile("s_waitcnt vmcnt(" #n ")" ::: "memory")
; #define PG8_WAIT_L(n) asm volatile("s_waitcnt lgkmcnt(" #n ")" ::: "memory")
; #define PG8_BAR __builtin_amdgcn_s_barrier()
; #define PG8_SCHED __builtin_amdgcn_sched_barrier(0)
; template <class Epi, class Sched, bool ALIGN_EPI = false, bool SP2 = false>
; __device__ __forceinline__ void gemm_phase(PG8_LAS unsigned char* lds, const Gemm g, const Sched& S, const Epi& E) {
;     ...
;             PG8_LDB(B0, 1, 0); PG8_LDB(B1, 1, 1); PG8_SCHED; PG8_LDA(At, 1, 0); PG8_STAGE(PG8_SA(0, 1), a2 + hstep, voffA);
;             PG8_WAIT_V(8); PG8_WAIT_L(0); PG8_BAR; PG8_MMA(0, 0, At, B0); PG8_MMA(0, 1, At, B1); PG8_BAR; PG8_SCHED;
;             PG8_LDA(At, 1, 1); PG8_STAGE(PG8_SB(1, 0), b3, voffB); PG8_STAGE(PG8_SB(1, 1), b3 + hstep, voffB); PG8_STAGE(PG8_SA(1, 0), a3, voffA);
;             PG8_WAIT_V(8); PG8_WAIT_L(0); PG8_BAR; PG8_MMA(1, 0, At, B0); PG8_MMA(1, 1, At, B1); PG8_BAR; PG8_SCHED;
	s_add_i32 s51, 0, 0x18000
	v_add_u32_e32 v155, s51, v149
	s_add_i32 s52, 0, 0x1c000
	ds_read_b128 v[144:147], v155
	ds_read_b128 v[156:159], v155 offset:1024
	ds_read_b128 v[160:163], v155 offset:2048
	ds_read_b128 v[164:167], v155 offset:3072
	v_add_u32_e32 v155, s52, v149
	ds_read_b128 v[168:171], v155
	ds_read_b128 v[172:175], v155 offset:1024
	ds_read_b128 v[176:179], v155 offset:2048
	ds_read_b128 v[180:183], v155 offset:3072
	s_add_u32 s30, s30, 0x40000
	s_addc_u32 s31, s31, 0
	s_mov_b32 m0, s37
	ds_read_b128 v[184:187], v153 offset:32768
	ds_read_b128 v[190:193], v153 offset:33792
	ds_read_b128 v[194:197], v153 offset:34816
	ds_read_b128 v[198:201], v153 offset:35840
	ds_read_b128 v[202:205], v153 offset:36864
	ds_read_b128 v[206:209], v153 offset:37888
	ds_read_b128 v[210:213], v153 offset:38912
	ds_read_b128 v[214:217], v153 offset:39936
	global_load_lds_dwordx4 v128, s[30:31]
	v_lshl_add_u64 v[226:227], s[30:31], 0, v[132:133]
	s_mov_b32 m0, s38
	s_nop 0
	global_load_lds_dwordx4 v[226:227], off
	s_waitcnt vmcnt(8)
	s_waitcnt lgkmcnt(0)
	s_barrier
	s_setprio 1
	v_mfma_f32_16x16x32_bf16 v[124:127], v[144:147], v[184:187], v[124:127]
	v_mfma_f32_16x16x32_bf16 v[120:123], v[160:163], v[184:187], v[120:123]
	v_mfma_f32_16x16x32_bf16 v[108:111], v[144:147], v[194:197], v[108:111]
	v_mfma_f32_16x16x32_bf16 v[104:107], v[160:163], v[194:197], v[104:107]
	v_mfma_f32_16x16x32_bf16 v[92:95], v[144:147], v[202:205], v[92:95]
	v_mfma_f32_16x16x32_bf16 v[88:91], v[160:163], v[202:205], v[88:91]
	v_mfma_f32_16x16x32_bf16 v[76:79], v[144:147], v[210:213], v[76:79]
	v_mfma_f32_16x16x32_bf16 v[72:75], v[160:163], v[210:213], v[72:75]
	v_mfma_f32_16x16x32_bf16 v[124:127], v[156:159], v[190:193], v[124:127]
	v_mfma_f32_16x16x32_bf16 v[120:123], v[164:167], v[190:193], v[120:123]
	v_mfma_f32_16x16x32_bf16 v[108:111], v[156:159], v[198:201], v[108:111]
	v_mfma_f32_16x16x32_bf16 v[104:107], v[164:167], v[198:201], v[104:107]
	v_mfma_f32_16x16x32_bf16 v[92:95], v[156:159], v[206:209], v[92:95]
	v_mfma_f32_16x16x32_bf16 v[88:91], v[164:167], v[206:209], v[88:91]
	v_mfma_f32_16x16x32_bf16 v[76:79], v[156:159], v[214:217], v[76:79]
	v_mfma_f32_16x16x32_bf16 v[72:75], v[164:167], v[214:217], v[72:75]
	v_mfma_f32_16x16x32_bf16 v[116:119], v[168:171], v[184:187], v[116:119]
	v_mfma_f32_16x16x32_bf16 v[112:115], v[176:179], v[184:187], v[112:115]
	v_mfma_f32_16x16x32_bf16 v[100:103], v[168:171], v[194:197], v[100:103]
	v_mfma_f32_16x16x32_bf16 v[96:99], v[176:179], v[194:197], v[96:99]
	v_mfma_f32_16x16x32_bf16 v[84:87], v[168:171], v[202:205], v[84:87]
	v_mfma_f32_16x16x32_bf16 v[80:83], v[176:179], v[202:205], v[80:83]
	v_mfma_f32_16x16x32_bf16 v[68:71], v[168:171], v[210:213], v[68:71]
	v_mfma_f32_16x16x32_bf16 v[64:67], v[176:179], v[210:213], v[64:67]
	v_mfma_f32_16x16x32_bf16 v[116:119], v[172:175], v[190:193], v[116:119]
	v_mfma_f32_16x16x32_bf16 v[112:115], v[180:183], v[190:193], v[112:115]
	v_mfma_f32_16x16x32_bf16 v[100:103], v[172:175], v[198:201], v[100:103]
	v_mfma_f32_16x16x32_bf16 v[96:99], v[180:183], v[198:201], v[96:99]
	v_mfma_f32_16x16x32_bf16 v[84:87], v[172:175], v[206:209], v[84:87]
	v_mfma_f32_16x16x32_bf16 v[80:83], v[180:183], v[206:209], v[80:83]
	v_mfma_f32_16x16x32_bf16 v[68:71], v[172:175], v[214:217], v[68:71]
	v_mfma_f32_16x16x32_bf16 v[64:67], v[180:183], v[214:217], v[64:67]
	s_setprio 0
	s_barrier
	s_add_i32 s30, s51, s35
	v_lshl_add_u64 v[218:219], v[218:219], 0, s[2:3]
	s_mov_b32 m0, s30
	ds_read_b128 v[184:187], v153 offset:49152
	ds_read_b128 v[190:193], v153 offset:50176
	ds_read_b128 v[194:197], v153 offset:51200
	ds_read_b128 v[198:201], v153 offset:52224
	ds_read_b128 v[202:205], v153 offset:53248
	ds_read_b128 v[206:209], v153 offset:54272
	ds_read_b128 v[210:213], v153 offset:55296
	ds_read_b128 v[214:217], v153 offset:56320
	global_load_lds_dwordx4 v[218:219], off
	s_add_i32 m0, s30, 0x2000
	s_add_u32 s28, s28, 0x40080
	v_lshl_add_u64 v[218:219], v[220:221], 0, s[2:3]
	s_addc_u32 s29, s29, 0
	s_add_i32 s30, s52, s35
	global_load_lds_dwordx4 v[218:219], off
	s_mov_b32 m0, s30
	s_nop 0
	global_load_lds_dwordx4 v130, s[28:29]
	s_add_i32 m0, s30, 0x2000
	s_nop 0
	global_load_lds_dwordx4 v134, s[28:29]
	v_lshl_add_u64 v[218:219], v[222:223], 0, s[2:3]
	s_mov_b32 m0, s40
	s_nop 0
	global_load_lds_dwordx4 v[218:219], off
	v_lshl_add_u64 v[218:219], v[224:225], 0, s[2:3]
	s_mov_b32 m0, s41
	s_nop 0
	global_load_lds_dwordx4 v[218:219], off
	s_waitcnt vmcnt(8)
	s_waitcnt lgkmcnt(0)
	s_barrier
	s_setprio 1
	v_mfma_f32_16x16x32_bf16 v[60:63], v[144:147], v[184:187], v[60:63]
	v_mfma_f32_16x16x32_bf16 v[56:59], v[160:163], v[184:187], v[56:59]
	v_mfma_f32_16x16x32_bf16 v[44:47], v[144:147], v[194:197], v[44:47]
	v_mfma_f32_16x16x32_bf16 v[40:43], v[160:163], v[194:197], v[40:43]
	v_mfma_f32_16x16x32_bf16 v[28:31], v[144:147], v[202:205], v[28:31]
	v_mfma_f32_16x16x32_bf16 v[24:27], v[160:163], v[202:205], v[24:27]
	v_mfma_f32_16x16x32_bf16 v[12:15], v[144:147], v[210:213], v[12:15]
	v_mfma_f32_16x16x32_bf16 v[8:11], v[160:163], v[210:213], v[8:11]
	v_mfma_f32_16x16x32_bf16 v[60:63], v[156:159], v[190:193], v[60:63]
	v_mfma_f32_16x16x32_bf16 v[56:59], v[164:167], v[190:193], v[56:59]
	v_mfma_f32_16x16x32_bf16 v[44:47], v[156:159], v[198:201], v[44:47]
	v_mfma_f32_16x16x32_bf16 v[40:43], v[164:167], v[198:201], v[40:43]
	v_mfma_f32_16x16x32_bf16 v[28:31], v[156:159], v[206:209], v[28:31]
	v_mfma_f32_16x16x32_bf16 v[24:27], v[164:167], v[206:209], v[24:27]
	v_mfma_f32_16x16x32_bf16 v[12:15], v[156:159], v[214:217], v[12:15]
	v_mfma_f32_16x16x32_bf16 v[8:11], v[164:167], v[214:217], v[8:11]
	v_mfma_f32_16x16x32_bf16 v[52:55], v[168:171], v[184:187], v[52:55]
	v_mfma_f32_16x16x32_bf16 v[48:51], v[176:179], v[184:187], v[48:51]
	v_mfma_f32_16x16x32_bf16 v[36:39], v[168:171], v[194:197], v[36:39]
	v_mfma_f32_16x16x32_bf16 v[32:35], v[176:179], v[194:197], v[32:35]
	v_mfma_f32_16x16x32_bf16 v[20:23], v[168:171], v[202:205], v[20:23]
	v_mfma_f32_16x16x32_bf16 v[16:19], v[176:179], v[202:205], v[16:19]
	v_mfma_f32_16x16x32_bf16 v[4:7], v[168:171], v[210:213], v[4:7]
	v_mfma_f32_16x16x32_bf16 v[0:3], v[176:179], v[210:213], v[0:3]
	v_mfma_f32_16x16x32_bf16 v[52:55], v[172:175], v[190:193], v[52:55]
	v_mfma_f32_16x16x32_bf16 v[48:51], v[180:183], v[190:193], v[48:51]
	v_mfma_f32_16x16x32_bf16 v[36:39], v[172:175], v[198:201], v[36:39]
	v_mfma_f32_16x16x32_bf16 v[32:35], v[180:183], v[198:201], v[32:35]
	v_mfma_f32_16x16x32_bf16 v[20:23], v[172:175], v[206:209], v[20:23]
	v_mfma_f32_16x16x32_bf16 v[16:19], v[180:183], v[206:209], v[16:19]
	v_mfma_f32_16x16x32_bf16 v[4:7], v[172:175], v[214:217], v[4:7]
	v_mfma_f32_16x16x32_bf16 v[0:3], v[180:183], v[214:217], v[0:3]
	s_setprio 0
	s_barrier
	s_add_i32 s50, s50, 2
	s_add_u32 s26, s26, 0x100
	s_addc_u32 s27, s27, 0
	s_add_u32 s48, s48, 0x100
	s_addc_u32 s49, s49, 0
	s_cmp_gt_u32 s50, 13
	s_cbranch_scc0 .LBB0_698
	s_and_b64 vcc, exec, s[12:13]
	s_cbranch_vccz .LBB0_701
	s_barrier

; #define PG8_STAGE(bufoff, gbase, voff) do { _Pragma("unroll") for (int _i = 0; _i < 2; ++_i) \
;         __builtin_amdgcn_global_load_lds((const unsigned*)((const char*)(gbase) + (voff)[_i]), (PG8_LAS unsigned*)(lds + (bufoff) + ldsw + _i * 8192), 16, 0, 0); } while (0)
; #define PG8_LDA(dst, b, h) do { _Pragma("unroll") for (int m = 0; m < 4; ++m) _Pragma("unroll") for (int k = 0; k < 2; ++k) dst[m][k] = *(const PG8_LAS bf16x8*)(lds + PG8_SA(b, h) + aoff + m * 2048 + k * 1024); } while (0)
; #define PG8_LDB(dst, b, h) do { _Pragma("unroll") for (int n = 0; n < 2; ++n) _Pragma("unroll") for (int k = 0; k < 2; ++k) dst[n][k] = *(const PG8_LAS bf16x8*)(lds + PG8_SB(b, h) + boff + n * 2048 + k * 1024); } while (0)
; #define PG8_WAIT_V(n) asm volatile("s_waitcnt vmcnt(" #n ")" ::: "memory")
; #define PG8_WAIT_L(n) asm volatile("s_waitcnt lgkmcnt(" #n ")" ::: "memory")
; #define PG8_BAR __builtin_amdgcn_s_barrier()
; #define PG8_SCHED __builtin_amdgcn_sched_barrier(0)
; template <class Epi, class Sched, bool ALIGN_EPI = false, bool SP2 = false>
; __device__ __forceinline__ void gemm_phase(PG8_LAS unsigned char* lds, const Gemm g, const Sched& S, const Epi& E) {
;     ...
;         const bool has_next = S.next(ui + 1, nxt);
;         const char* nA = has_next ? (const char*)g.A + (size_t)nxt.pm * tstep : cA; const char* nB = has_next ? (const char*)g.Bt + (size_t)nxt.pn * tstep : cB;
;         for (int t = 0; t < nt; t += 2) {
;             const bool last = (t == nt - 2);
;             const char* a1 = cA + (size_t)(t + 1) * kstep;
;             const char* a2 = last ? nA : cA + (size_t)(t + 2) * kstep; const char* b2 = last ? nB : cB + (size_t)(t + 2) * kstep;
;             const char* a3 = a2 + kstep; const char* b3 = b2 + kstep;
;             if (last && has_next) S.a_ready(nxt);
;             if constexpr (SP2) {
;             PG8_LDB(B0, 0, 0); PG8_LDB(B1, 0, 1); PG8_SCHED; PG8_LDA(At, 0, 0); PG8_STAGE(PG8_SA(1, 1), a1 + hstep, voffA);
;             PG8_WAIT_V(8); PG8_WAIT_L(0); PG8_BAR; PG8_MMA(0, 0, At, B0); PG8_MMA(0, 1, At, B1); PG8_BAR; PG8_SCHED;
;             PG8_LDA(At, 0, 1); PG8_STAGE(PG8_SB(0, 0), b2, voffB); PG8_STAGE(PG8_SB(0, 1), b2 + hstep, voffB); PG8_STAGE(PG8_SA(0, 0), a2, voffA);
;             PG8_WAIT_V(8); PG8_WAIT_L(0); PG8_BAR; PG8_MMA(1, 0, At, B0); PG8_MMA(1, 1, At, B1); PG8_BAR; PG8_SCHED;
.LBB0_781:
	s_ashr_i32 s17, s16, 31
	s_lshl_b64 s[18:19], s[16:17], 19
	s_add_u32 s18, s8, s18
	s_addc_u32 s19, s9, s19
	s_and_b64 s[20:21], s[4:5], exec
	s_cselect_b32 s17, s19, s23
	s_cselect_b32 s47, s18, s22
	s_ashr_i32 s15, s14, 31
	s_lshl_b64 s[20:21], s[14:15], 19
	s_add_u32 s20, s28, s20
	s_addc_u32 s21, s29, s21
	s_and_b64 s[26:27], s[4:5], exec
	s_cselect_b32 s15, s21, s25
	s_cselect_b32 s48, s20, s24
	s_add_u32 s22, s22, 0x40080
	s_addc_u32 s23, s23, 0
	s_add_u32 s49, s24, 0x100
	s_addc_u32 s50, s25, 0
	s_mov_b32 s51, -2
	ds_read_b128 v[144:147], v151
	ds_read_b128 v[156:159], v151 offset:1024
	ds_read_b128 v[160:163], v151 offset:2048
	ds_read_b128 v[164:167], v151 offset:3072
	ds_read_b128 v[168:171], v152
	ds_read_b128 v[172:175], v152 offset:1024
	ds_read_b128 v[176:179], v152 offset:2048
	ds_read_b128 v[180:183], v152 offset:3072
	s_add_u32 s24, s22, 0xfffc0080
	s_addc_u32 s25, s23, -1
	s_cmp_eq_u32 s51, 12
	s_cselect_b32 s27, s17, s25
	s_cselect_b32 s26, s47, s24
	s_cselect_b32 s25, s15, s50
	s_cselect_b32 s24, s48, s49
	s_add_i32 m0, s34, 0xc000
	ds_read_b128 v[184:187], v153
	ds_read_b128 v[190:193], v153 offset:1024
	ds_read_b128 v[194:197], v153 offset:2048
	ds_read_b128 v[198:201], v153 offset:3072
	ds_read_b128 v[202:205], v153 offset:4096
	ds_read_b128 v[206:209], v153 offset:5120
	ds_read_b128 v[210:213], v153 offset:6144
	ds_read_b128 v[214:217], v153 offset:7168
	global_load_lds_dwordx4 v136, s[22:23]
	s_add_i32 m0, s34, 0xe000
	s_nop 0
	global_load_lds_dwordx4 v138, s[22:23]
	s_waitcnt vmcnt(16)
	s_waitcnt lgkmcnt(0)
	s_barrier
	s_setprio 1
	v_mfma_f32_16x16x32_bf16 v[116:119], v[144:147], v[184:187], 0
	v_mfma_f32_16x16x32_bf16 v[112:115], v[160:163], v[184:187], 0
	v_mfma_f32_16x16x32_bf16 v[100:103], v[144:147], v[194:197], 0
	v_mfma_f32_16x16x32_bf16 v[96:99], v[160:163], v[194:197], 0
	v_mfma_f32_16x16x32_bf16 v[84:87], v[144:147], v[202:205], 0
	v_mfma_f32_16x16x32_bf16 v[80:83], v[160:163], v[202:205], 0
	v_mfma_f32_16x16x32_bf16 v[72:75], v[144:147], v[210:213], 0
	v_mfma_f32_16x16x32_bf16 v[64:67], v[160:163], v[210:213], 0
	v_mfma_f32_16x16x32_bf16 v[116:119], v[156:159], v[190:193], v[116:119]
	v_mfma_f32_16x16x32_bf16 v[112:115], v[164:167], v[190:193], v[112:115]
	v_mfma_f32_16x16x32_bf16 v[100:103], v[156:159], v[198:201], v[100:103]
	v_mfma_f32_16x16x32_bf16 v[96:99], v[164:167], v[198:201], v[96:99]
	v_mfma_f32_16x16x32_bf16 v[84:87], v[156:159], v[206:209], v[84:87]
	v_mfma_f32_16x16x32_bf16 v[80:83], v[164:167], v[206:209], v[80:83]
	v_mfma_f32_16x16x32_bf16 v[72:75], v[156:159], v[214:217], v[72:75]
	v_mfma_f32_16x16x32_bf16 v[64:67], v[164:167], v[214:217], v[64:67]
	v_mfma_f32_16x16x32_bf16 v[124:127], v[168:171], v[184:187], 0
	v_mfma_f32_16x16x32_bf16 v[120:123], v[176:179], v[184:187], 0
	v_mfma_f32_16x16x32_bf16 v[108:111], v[168:171], v[194:197], 0
	v_mfma_f32_16x16x32_bf16 v[104:107], v[176:179], v[194:197], 0
	v_mfma_f32_16x16x32_bf16 v[92:95], v[168:171], v[202:205], 0
	v_mfma_f32_16x16x32_bf16 v[88:91], v[176:179], v[202:205], 0
	v_mfma_f32_16x16x32_bf16 v[76:79], v[168:171], v[210:213], 0
	v_mfma_f32_16x16x32_bf16 v[68:71], v[176:179], v[210:213], 0
	v_mfma_f32_16x16x32_bf16 v[124:127], v[172:175], v[190:193], v[124:127]
	v_mfma_f32_16x16x32_bf16 v[120:123], v[180:183], v[190:193], v[120:123]
	v_mfma_f32_16x16x32_bf16 v[108:111], v[172:175], v[198:201], v[108:111]
	v_mfma_f32_16x16x32_bf16 v[104:107], v[180:183], v[198:201], v[104:107]
	v_mfma_f32_16x16x32_bf16 v[92:95], v[172:175], v[206:209], v[92:95]
	v_mfma_f32_16x16x32_bf16 v[88:91], v[180:183], v[206:209], v[88:91]
	v_mfma_f32_16x16x32_bf16 v[76:79], v[172:175], v[214:217], v[76:79]
	v_mfma_f32_16x16x32_bf16 v[68:71], v[180:183], v[214:217], v[68:71]
	s_setprio 0
	s_barrier
	s_add_i32 s52, s43, s30
	v_lshl_add_u64 v[218:219], s[24:25], 0, v[132:133]
	s_mov_b32 m0, s52
	ds_read_b128 v[184:187], v153 offset:16384
	ds_read_b128 v[190:193], v153 offset:17408
	ds_read_b128 v[194:197], v153 offset:18432
	ds_read_b128 v[198:201], v153 offset:19456
	ds_read_b128 v[202:205], v153 offset:20480
	ds_read_b128 v[206:209], v153 offset:21504
	ds_read_b128 v[210:213], v153 offset:22528
	ds_read_b128 v[214:217], v153 offset:23552
	global_load_lds_dwordx4 v[218:219], off
	s_add_i32 m0, s52, 0x2000
	s_add_u32 s52, s24, 0x40000
	v_lshl_add_u64 v[220:221], s[24:25], 0, v[128:129]
	s_addc_u32 s53, s25, 0
	s_add_i32 s54, s44, s30
	global_load_lds_dwordx4 v[220:221], off
	s_mov_b32 m0, s54
	v_lshl_add_u64 v[224:225], s[26:27], 0, v[130:131]
	global_load_lds_dwordx4 v132, s[52:53]
	s_add_i32 m0, s54, 0x2000
	s_nop 0
	global_load_lds_dwordx4 v128, s[52:53]
	v_lshl_add_u64 v[222:223], s[26:27], 0, v[134:135]
	s_mov_b32 m0, s34
	s_nop 0
	global_load_lds_dwordx4 v[222:223], off
	s_mov_b32 m0, s35
	s_nop 0
	global_load_lds_dwordx4 v[224:225], off
	s_waitcnt vmcnt(16)
	s_waitcnt lgkmcnt(0)
	s_barrier
; #define PG8_STAGE(bufoff, gbase, voff) do { _Pragma("unroll") for (int _i = 0; _i < 2; ++_i) \
;         __builtin_amdgcn_global_load_lds((const unsigned*)((const char*)(gbase) + (voff)[_i]), (PG8_LAS unsigned*)(lds + (bufoff) + ldsw + _i * 8192), 16, 0, 0); } while (0)
; #define PG8_LDA(dst, b, h) do { _Pragma("unroll") for (int m = 0; m < 4; ++m) _Pragma("unroll") for (int k = 0; k < 2; ++k) dst[m][k] = *(const PG8_LAS bf16x8*)(lds + PG8_SA(b, h) + aoff + m * 2048 + k * 1024); } while (0)
; #define PG8_LDB(dst, b, h) do { _Pragma("unroll") for (int n = 0; n < 2; ++n) _Pragma("unroll") for (int k = 0; k < 2; ++k) dst[n][k] = *(const PG8_LAS bf16x8*)(lds + PG8_SB(b, h) + boff + n * 2048 + k * 1024); } while (0)
; #define PG8_MMA(ai, bj, At, Bt) do { __builtin_amdgcn_s_setprio(1); _Pragma("unroll") for (int m = 0; m < 4; ++m) _Pragma("unroll") for (int n = 0; n < 2; ++n) _Pragma("unroll") for (int k = 0; k < 2; ++k) \
;         acc[ai][bj][m][n] = __builtin_amdgcn_mfma_f32_16x16x32_bf16(Bt[n][k], At[m][k], acc[ai][bj][m][n], 0, 0, 0); __builtin_amdgcn_s_setprio(0); } while (0)
; #define PG8_WAIT_V(n) asm volatile("s_waitcnt vmcnt(" #n ")" ::: "memory")
; #define PG8_WAIT_L(n) asm volatile("s_waitcnt lgkmcnt(" #n ")" ::: "memory")
; #define PG8_BAR __builtin_amdgcn_s_barrier()
; #define PG8_SCHED __builtin_amdgcn_sched_barrier(0)
; template <class Epi, class Sched, bool ALIGN_EPI = false, bool SP2 = false>
; __device__ __forceinline__ void gemm_phase(PG8_LAS unsigned char* lds, const Gemm g, const Sched& S, const Epi& E) {
;     ...
;             PG8_WAIT_V(8); PG8_WAIT_L(0); PG8_BAR; PG8_MMA(1, 0, At, B0); PG8_MMA(1, 1, At, B1); PG8_BAR; PG8_SCHED;
;             PG8_LDB(B0, 1, 0); PG8_LDB(B1, 1, 1); PG8_SCHED; PG8_LDA(At, 1, 0); PG8_STAGE(PG8_SA(0, 1), a2 + hstep, voffA);
;             PG8_WAIT_V(8); PG8_WAIT_L(0); PG8_BAR; PG8_MMA(0, 0, At, B0); PG8_MMA(0, 1, At, B1); PG8_BAR; PG8_SCHED;
	s_setprio 1
	v_mfma_f32_16x16x32_bf16 v[56:59], v[144:147], v[184:187], 0
	v_mfma_f32_16x16x32_bf16 v[48:51], v[160:163], v[184:187], 0
	v_mfma_f32_16x16x32_bf16 v[40:43], v[144:147], v[194:197], 0
	v_mfma_f32_16x16x32_bf16 v[32:35], v[160:163], v[194:197], 0
	v_mfma_f32_16x16x32_bf16 v[24:27], v[144:147], v[202:205], 0
	v_mfma_f32_16x16x32_bf16 v[16:19], v[160:163], v[202:205], 0
	v_mfma_f32_16x16x32_bf16 v[8:11], v[144:147], v[210:213], 0
	v_mfma_f32_16x16x32_bf16 v[0:3], v[160:163], v[210:213], 0
	v_mfma_f32_16x16x32_bf16 v[56:59], v[156:159], v[190:193], v[56:59]
	v_mfma_f32_16x16x32_bf16 v[48:51], v[164:167], v[190:193], v[48:51]
	v_mfma_f32_16x16x32_bf16 v[40:43], v[156:159], v[198:201], v[40:43]
	v_mfma_f32_16x16x32_bf16 v[32:35], v[164:167], v[198:201], v[32:35]
	v_mfma_f32_16x16x32_bf16 v[24:27], v[156:159], v[206:209], v[24:27]
	v_mfma_f32_16x16x32_bf16 v[16:19], v[164:167], v[206:209], v[16:19]
	v_mfma_f32_16x16x32_bf16 v[8:11], v[156:159], v[214:217], v[8:11]
	v_mfma_f32_16x16x32_bf16 v[0:3], v[164:167], v[214:217], v[0:3]
	v_mfma_f32_16x16x32_bf16 v[60:63], v[168:171], v[184:187], 0
	v_mfma_f32_16x16x32_bf16 v[52:55], v[176:179], v[184:187], 0
	v_mfma_f32_16x16x32_bf16 v[44:47], v[168:171], v[194:197], 0
	v_mfma_f32_16x16x32_bf16 v[36:39], v[176:179], v[194:197], 0
	v_mfma_f32_16x16x32_bf16 v[28:31], v[168:171], v[202:205], 0
	v_mfma_f32_16x16x32_bf16 v[20:23], v[176:179], v[202:205], 0
	v_mfma_f32_16x16x32_bf16 v[12:15], v[168:171], v[210:213], 0
	v_mfma_f32_16x16x32_bf16 v[4:7], v[176:179], v[210:213], 0
	v_mfma_f32_16x16x32_bf16 v[60:63], v[172:175], v[190:193], v[60:63]
	v_mfma_f32_16x16x32_bf16 v[52:55], v[180:183], v[190:193], v[52:55]
	v_mfma_f32_16x16x32_bf16 v[44:47], v[172:175], v[198:201], v[44:47]
	v_mfma_f32_16x16x32_bf16 v[36:39], v[180:183], v[198:201], v[36:39]
	v_mfma_f32_16x16x32_bf16 v[28:31], v[172:175], v[206:209], v[28:31]
	v_mfma_f32_16x16x32_bf16 v[20:23], v[180:183], v[206:209], v[20:23]
	v_mfma_f32_16x16x32_bf16 v[12:15], v[172:175], v[214:217], v[12:15]
	v_mfma_f32_16x16x32_bf16 v[4:7], v[180:183], v[214:217], v[4:7]
	s_setprio 0
	s_barrier
	s_add_i32 s52, 0, 0x18000
	v_add_u32_e32 v155, s52, v149
	s_add_i32 s53, 0, 0x1c000
	ds_read_b128 v[144:147], v155
	ds_read_b128 v[156:159], v155 offset:1024
	ds_read_b128 v[160:163], v155 offset:2048
	ds_read_b128 v[164:167], v155 offset:3072
	v_add_u32_e32 v155, s53, v149
	ds_read_b128 v[168:171], v155
	ds_read_b128 v[172:175], v155 offset:1024
	ds_read_b128 v[176:179], v155 offset:2048
	ds_read_b128 v[180:183], v155 offset:3072
	s_add_u32 s26, s26, 0x40000
	s_addc_u32 s27, s27, 0
	s_mov_b32 m0, s36
	ds_read_b128 v[184:187], v153 offset:32768
	ds_read_b128 v[190:193], v153 offset:33792
	ds_read_b128 v[194:197], v153 offset:34816
	ds_read_b128 v[198:201], v153 offset:35840
	ds_read_b128 v[202:205], v153 offset:36864
	ds_read_b128 v[206:209], v153 offset:37888
	ds_read_b128 v[210:213], v153 offset:38912
	ds_read_b128 v[214:217], v153 offset:39936
	global_load_lds_dwordx4 v134, s[26:27]
	v_lshl_add_u64 v[226:227], s[26:27], 0, v[130:131]
	s_mov_b32 m0, s37
	s_nop 0
	global_load_lds_dwordx4 v[226:227], off
	s_waitcnt vmcnt(8)
	s_waitcnt lgkmcnt(0)
	s_barrier
	s_setprio 1
	v_mfma_f32_16x16x32_bf16 v[116:119], v[144:147], v[184:187], v[116:119]
	v_mfma_f32_16x16x32_bf16 v[112:115], v[160:163], v[184:187], v[112:115]
	v_mfma_f32_16x16x32_bf16 v[100:103], v[144:147], v[194:197], v[100:103]
	v_mfma_f32_16x16x32_bf16 v[96:99], v[160:163], v[194:197], v[96:99]
	v_mfma_f32_16x16x32_bf16 v[84:87], v[144:147], v[202:205], v[84:87]
	v_mfma_f32_16x16x32_bf16 v[80:83], v[160:163], v[202:205], v[80:83]
	v_mfma_f32_16x16x32_bf16 v[72:75], v[144:147], v[210:213], v[72:75]
	v_mfma_f32_16x16x32_bf16 v[64:67], v[160:163], v[210:213], v[64:67]
	v_mfma_f32_16x16x32_bf16 v[116:119], v[156:159], v[190:193], v[116:119]
	v_mfma_f32_16x16x32_bf16 v[112:115], v[164:167], v[190:193], v[112:115]
	v_mfma_f32_16x16x32_bf16 v[100:103], v[156:159], v[198:201], v[100:103]
	v_mfma_f32_16x16x32_bf16 v[96:99], v[164:167], v[198:201], v[96:99]
	v_mfma_f32_16x16x32_bf16 v[84:87], v[156:159], v[206:209], v[84:87]
	v_mfma_f32_16x16x32_bf16 v[80:83], v[164:167], v[206:209], v[80:83]
	v_mfma_f32_16x16x32_bf16 v[72:75], v[156:159], v[214:217], v[72:75]
	v_mfma_f32_16x16x32_bf16 v[64:67], v[164:167], v[214:217], v[64:67]
	v_mfma_f32_16x16x32_bf16 v[124:127], v[168:171], v[184:187], v[124:127]
	v_mfma_f32_16x16x32_bf16 v[120:123], v[176:179], v[184:187], v[120:123]
	v_mfma_f32_16x16x32_bf16 v[108:111], v[168:171], v[194:197], v[108:111]
	v_mfma_f32_16x16x32_bf16 v[104:107], v[176:179], v[194:197], v[104:107]
	v_mfma_f32_16x16x32_bf16 v[92:95], v[168:171], v[202:205], v[92:95]
	v_mfma_f32_16x16x32_bf16 v[88:91], v[176:179], v[202:205], v[88:91]
	v_mfma_f32_16x16x32_bf16 v[76:79], v[168:171], v[210:213], v[76:79]
	v_mfma_f32_16x16x32_bf16 v[68:71], v[176:179], v[210:213], v[68:71]
	v_mfma_f32_16x16x32_bf16 v[124:127], v[172:175], v[190:193], v[124:127]
	v_mfma_f32_16x16x32_bf16 v[120:123], v[180:183], v[190:193], v[120:123]
	v_mfma_f32_16x16x32_bf16 v[108:111], v[172:175], v[198:201], v[108:111]
	v_mfma_f32_16x16x32_bf16 v[104:107], v[180:183], v[198:201], v[104:107]
	v_mfma_f32_16x16x32_bf16 v[92:95], v[172:175], v[206:209], v[92:95]
	v_mfma_f32_16x16x32_bf16 v[88:91], v[180:183], v[206:209], v[88:91]
	v_mfma_f32_16x16x32_bf16 v[76:79], v[172:175], v[214:217], v[76:79]
	v_mfma_f32_16x16x32_bf16 v[68:71], v[180:183], v[214:217], v[68:71]
	s_setprio 0
	s_barrier
; #define PG8_STAGE(bufoff, gbase, voff) do { _Pragma("unroll") for (int _i = 0; _i < 2; ++_i) \
;         __builtin_amdgcn_global_load_lds((const unsigned*)((const char*)(gbase) + (voff)[_i]), (PG8_LAS unsigned*)(lds + (bufoff) + ldsw + _i * 8192), 16, 0, 0); } while (0)
; #define PG8_LDA(dst, b, h) do { _Pragma("unroll") for (int m = 0; m < 4; ++m) _Pragma("unroll") for (int k = 0; k < 2; ++k) dst[m][k] = *(const PG8_LAS bf16x8*)(lds + PG8_SA(b, h) + aoff + m * 2048 + k * 1024); } while (0)
; #define PG8_LDB(dst, b, h) do { _Pragma("unroll") for (int n = 0; n < 2; ++n) _Pragma("unroll") for (int k = 0; k < 2; ++k) dst[n][k] = *(const PG8_LAS bf16x8*)(lds + PG8_SB(b, h) + boff + n * 2048 + k * 1024); } while (0)
; #define PG8_MMA(ai, bj, At, Bt) do { __builtin_amdgcn_s_setprio(1); _Pragma("unroll") for (int m = 0; m < 4; ++m) _Pragma("unroll") for (int n = 0; n < 2; ++n) _Pragma("unroll") for (int k = 0; k < 2; ++k) \
;         acc[ai][bj][m][n] = __builtin_amdgcn_mfma_f32_16x16x32_bf16(Bt[n][k], At[m][k], acc[ai][bj][m][n], 0, 0, 0); __builtin_amdgcn_s_setprio(0); } while (0)
; #define PG8_WAIT_V(n) asm volatile("s_waitcnt vmcnt(" #n ")" ::: "memory")
; #define PG8_WAIT_L(n) asm volatile("s_waitcnt lgkmcnt(" #n ")" ::: "memory")
; #define PG8_BAR __builtin_amdgcn_s_barrier()
; #define PG8_SCHED __builtin_amdgcn_sched_barrier(0)
; template <class Epi, class Sched, bool ALIGN_EPI = false, bool SP2 = false>
; __device__ __forceinline__ void gemm_phase(PG8_LAS unsigned char* lds, const Gemm g, const Sched& S, const Epi& E) {
;     ...
;             PG8_LDB(B0, 0, 0); PG8_LDB(B1, 0, 1); PG8_SCHED; PG8_LDA(At, 0, 0); PG8_STAGE(PG8_SA(1, 1), a1 + hstep, voffA);
;             PG8_WAIT_V(8); PG8_WAIT_L(0); PG8_BAR; PG8_MMA(0, 0, At, B0); PG8_MMA(0, 1, At, B1); PG8_BAR; PG8_SCHED;
;     ...
;             PG8_LDA(At, 1, 1); PG8_STAGE(PG8_SB(1, 0), b3, voffB); PG8_STAGE(PG8_SB(1, 1), b3 + hstep, voffB); PG8_STAGE(PG8_SA(1, 0), a3, voffA);
;             PG8_WAIT_V(8); PG8_WAIT_L(0); PG8_BAR; PG8_MMA(1, 0, At, B0); PG8_MMA(1, 1, At, B1); PG8_BAR; PG8_SCHED;
	s_add_i32 s26, s52, s30
	v_lshl_add_u64 v[218:219], v[218:219], 0, s[6:7]
	s_mov_b32 m0, s26
	ds_read_b128 v[184:187], v153 offset:49152
	ds_read_b128 v[190:193], v153 offset:50176
	ds_read_b128 v[194:197], v153 offset:51200
	ds_read_b128 v[198:201], v153 offset:52224
	ds_read_b128 v[202:205], v153 offset:53248
	ds_read_b128 v[206:209], v153 offset:54272
	ds_read_b128 v[210:213], v153 offset:55296
	ds_read_b128 v[214:217], v153 offset:56320
	global_load_lds_dwordx4 v[218:219], off
	s_add_i32 m0, s26, 0x2000
	s_add_u32 s24, s24, 0x40080
	v_lshl_add_u64 v[218:219], v[220:221], 0, s[6:7]
	s_addc_u32 s25, s25, 0
	s_add_i32 s26, s53, s30
	global_load_lds_dwordx4 v[218:219], off
	s_mov_b32 m0, s26
	s_nop 0
	global_load_lds_dwordx4 v132, s[24:25]
	s_add_i32 m0, s26, 0x2000
	s_nop 0
	global_load_lds_dwordx4 v128, s[24:25]
	v_lshl_add_u64 v[218:219], v[222:223], 0, s[6:7]
	s_mov_b32 m0, s39
	s_nop 0
	global_load_lds_dwordx4 v[218:219], off
	v_lshl_add_u64 v[218:219], v[224:225], 0, s[6:7]
	s_mov_b32 m0, s40
	s_nop 0
	global_load_lds_dwordx4 v[218:219], off
	s_waitcnt vmcnt(8)
	s_waitcnt lgkmcnt(0)
	s_barrier
	s_setprio 1
	v_mfma_f32_16x16x32_bf16 v[56:59], v[144:147], v[184:187], v[56:59]
	v_mfma_f32_16x16x32_bf16 v[48:51], v[160:163], v[184:187], v[48:51]
	v_mfma_f32_16x16x32_bf16 v[40:43], v[144:147], v[194:197], v[40:43]
	v_mfma_f32_16x16x32_bf16 v[32:35], v[160:163], v[194:197], v[32:35]
	v_mfma_f32_16x16x32_bf16 v[24:27], v[144:147], v[202:205], v[24:27]
	v_mfma_f32_16x16x32_bf16 v[16:19], v[160:163], v[202:205], v[16:19]
	v_mfma_f32_16x16x32_bf16 v[8:11], v[144:147], v[210:213], v[8:11]
	v_mfma_f32_16x16x32_bf16 v[0:3], v[160:163], v[210:213], v[0:3]
	v_mfma_f32_16x16x32_bf16 v[56:59], v[156:159], v[190:193], v[56:59]
	v_mfma_f32_16x16x32_bf16 v[48:51], v[164:167], v[190:193], v[48:51]
	v_mfma_f32_16x16x32_bf16 v[40:43], v[156:159], v[198:201], v[40:43]
	v_mfma_f32_16x16x32_bf16 v[32:35], v[164:167], v[198:201], v[32:35]
	v_mfma_f32_16x16x32_bf16 v[24:27], v[156:159], v[206:209], v[24:27]
	v_mfma_f32_16x16x32_bf16 v[16:19], v[164:167], v[206:209], v[16:19]
	v_mfma_f32_16x16x32_bf16 v[8:11], v[156:159], v[214:217], v[8:11]
	v_mfma_f32_16x16x32_bf16 v[0:3], v[164:167], v[214:217], v[0:3]
	v_mfma_f32_16x16x32_bf16 v[60:63], v[168:171], v[184:187], v[60:63]
	v_mfma_f32_16x16x32_bf16 v[52:55], v[176:179], v[184:187], v[52:55]
	v_mfma_f32_16x16x32_bf16 v[44:47], v[168:171], v[194:197], v[44:47]
	v_mfma_f32_16x16x32_bf16 v[36:39], v[176:179], v[194:197], v[36:39]
	v_mfma_f32_16x16x32_bf16 v[28:31], v[168:171], v[202:205], v[28:31]
	v_mfma_f32_16x16x32_bf16 v[20:23], v[176:179], v[202:205], v[20:23]
	v_mfma_f32_16x16x32_bf16 v[12:15], v[168:171], v[210:213], v[12:15]
	v_mfma_f32_16x16x32_bf16 v[4:7], v[176:179], v[210:213], v[4:7]
	v_mfma_f32_16x16x32_bf16 v[60:63], v[172:175], v[190:193], v[60:63]
	v_mfma_f32_16x16x32_bf16 v[52:55], v[180:183], v[190:193], v[52:55]
	v_mfma_f32_16x16x32_bf16 v[44:47], v[172:175], v[198:201], v[44:47]
	v_mfma_f32_16x16x32_bf16 v[36:39], v[180:183], v[198:201], v[36:39]
	v_mfma_f32_16x16x32_bf16 v[28:31], v[172:175], v[206:209], v[28:31]
	v_mfma_f32_16x16x32_bf16 v[20:23], v[180:183], v[206:209], v[20:23]
	v_mfma_f32_16x16x32_bf16 v[12:15], v[172:175], v[214:217], v[12:15]
	v_mfma_f32_16x16x32_bf16 v[4:7], v[180:183], v[214:217], v[4:7]
	s_setprio 0
	s_barrier
	s_add_i32 s51, s51, 2
	s_add_u32 s22, s22, 0x100
	s_addc_u32 s23, s23, 0
	s_add_u32 s49, s49, 0x100
	s_addc_u32 s50, s50, 0
.LBB0_782:
	ds_read_b128 v[144:147], v151
	ds_read_b128 v[156:159], v151 offset:1024
	ds_read_b128 v[160:163], v151 offset:2048
	ds_read_b128 v[164:167], v151 offset:3072
	ds_read_b128 v[168:171], v152
	ds_read_b128 v[172:175], v152 offset:1024
	ds_read_b128 v[176:179], v152 offset:2048
	ds_read_b128 v[180:183], v152 offset:3072
	s_add_u32 s24, s22, 0xfffc0080
	s_addc_u32 s25, s23, -1
	s_cmp_eq_u32 s51, 12
	s_cselect_b32 s27, s17, s25
	s_cselect_b32 s26, s47, s24
	s_cselect_b32 s25, s15, s50
	s_cselect_b32 s24, s48, s49
	s_add_i32 m0, s34, 0xc000
	ds_read_b128 v[184:187], v153
	ds_read_b128 v[190:193], v153 offset:1024
	ds_read_b128 v[194:197], v153 offset:2048
	ds_read_b128 v[198:201], v153 offset:3072
	ds_read_b128 v[202:205], v153 offset:4096
	ds_read_b128 v[206:209], v153 offset:5120
	ds_read_b128 v[210:213], v153 offset:6144
	ds_read_b128 v[214:217], v153 offset:7168
	global_load_lds_dwordx4 v136, s[22:23]
	s_add_i32 m0, s34, 0xe000
	s_nop 0
	global_load_lds_dwordx4 v138, s[22:23]
	s_waitcnt vmcnt(8)
	s_waitcnt lgkmcnt(0)
	s_barrier
; #define PG8_STAGE(bufoff, gbase, voff) do { _Pragma("unroll") for (int _i = 0; _i < 2; ++_i) \
;         __builtin_amdgcn_global_load_lds((const unsigned*)((const char*)(gbase) + (voff)[_i]), (PG8_LAS unsigned*)(lds + (bufoff) + ldsw + _i * 8192), 16, 0, 0); } while (0)
; #define PG8_LDA(dst, b, h) do { _Pragma("unroll") for (int m = 0; m < 4; ++m) _Pragma("unroll") for (int k = 0; k < 2; ++k) dst[m][k] = *(const PG8_LAS bf16x8*)(lds + PG8_SA(b, h) + aoff + m * 2048 + k * 1024); } while (0)
; #define PG8_LDB(dst, b, h) do { _Pragma("unroll") for (int n = 0; n < 2; ++n) _Pragma("unroll") for (int k = 0; k < 2; ++k) dst[n][k] = *(const PG8_LAS bf16x8*)(lds + PG8_SB(b, h) + boff + n * 2048 + k * 1024); } while (0)
; #define PG8_MMA(ai, bj, At, Bt) do { __builtin_amdgcn_s_setprio(1); _Pragma("unroll") for (int m = 0; m < 4; ++m) _Pragma("unroll") for (int n = 0; n < 2; ++n) _Pragma("unroll") for (int k = 0; k < 2; ++k) \
;         acc[ai][bj][m][n] = __builtin_amdgcn_mfma_f32_16x16x32_bf16(Bt[n][k], At[m][k], acc[ai][bj][m][n], 0, 0, 0); __builtin_amdgcn_s_setprio(0); } while (0)
; #define PG8_WAIT_V(n) asm volatile("s_waitcnt vmcnt(" #n ")" ::: "memory")
; #define PG8_WAIT_L(n) asm volatile("s_waitcnt lgkmcnt(" #n ")" ::: "memory")
; #define PG8_BAR __builtin_amdgcn_s_barrier()
; #define PG8_SCHED __builtin_amdgcn_sched_barrier(0)
; template <class Epi, class Sched, bool ALIGN_EPI = false, bool SP2 = false>
; __device__ __forceinline__ void gemm_phase(PG8_LAS unsigned char* lds, const Gemm g, const Sched& S, const Epi& E) {
;     ...
;             PG8_LDB(B0, 0, 0); PG8_LDB(B1, 0, 1); PG8_SCHED; PG8_LDA(At, 0, 0); PG8_STAGE(PG8_SA(1, 1), a1 + hstep, voffA);
;             PG8_WAIT_V(8); PG8_WAIT_L(0); PG8_BAR; PG8_MMA(0, 0, At, B0); PG8_MMA(0, 1, At, B1); PG8_BAR; PG8_SCHED;
;             PG8_LDA(At, 0, 1); PG8_STAGE(PG8_SB(0, 0), b2, voffB); PG8_STAGE(PG8_SB(0, 1), b2 + hstep, voffB); PG8_STAGE(PG8_SA(0, 0), a2, voffA);
;             PG8_WAIT_V(8); PG8_WAIT_L(0); PG8_BAR; PG8_MMA(1, 0, At, B0); PG8_MMA(1, 1, At, B1); PG8_BAR; PG8_SCHED;
;             PG8_LDB(B0, 1, 0); PG8_LDB(B1, 1, 1); PG8_SCHED; PG8_LDA(At, 1, 0); PG8_STAGE(PG8_SA(0, 1), a2 + hstep, voffA);
;             PG8_WAIT_V(8); PG8_WAIT_L(0); PG8_BAR; PG8_MMA(0, 0, At, B0); PG8_MMA(0, 1, At, B1); PG8_BAR; PG8_SCHED;
	s_setprio 1
	v_mfma_f32_16x16x32_bf16 v[116:119], v[144:147], v[184:187], v[116:119]
	v_mfma_f32_16x16x32_bf16 v[112:115], v[160:163], v[184:187], v[112:115]
	v_mfma_f32_16x16x32_bf16 v[100:103], v[144:147], v[194:197], v[100:103]
	v_mfma_f32_16x16x32_bf16 v[96:99], v[160:163], v[194:197], v[96:99]
	v_mfma_f32_16x16x32_bf16 v[84:87], v[144:147], v[202:205], v[84:87]
	v_mfma_f32_16x16x32_bf16 v[80:83], v[160:163], v[202:205], v[80:83]
	v_mfma_f32_16x16x32_bf16 v[72:75], v[144:147], v[210:213], v[72:75]
	v_mfma_f32_16x16x32_bf16 v[64:67], v[160:163], v[210:213], v[64:67]
	v_mfma_f32_16x16x32_bf16 v[116:119], v[156:159], v[190:193], v[116:119]
	v_mfma_f32_16x16x32_bf16 v[112:115], v[164:167], v[190:193], v[112:115]
	v_mfma_f32_16x16x32_bf16 v[100:103], v[156:159], v[198:201], v[100:103]
	v_mfma_f32_16x16x32_bf16 v[96:99], v[164:167], v[198:201], v[96:99]
	v_mfma_f32_16x16x32_bf16 v[84:87], v[156:159], v[206:209], v[84:87]
	v_mfma_f32_16x16x32_bf16 v[80:83], v[164:167], v[206:209], v[80:83]
	v_mfma_f32_16x16x32_bf16 v[72:75], v[156:159], v[214:217], v[72:75]
	v_mfma_f32_16x16x32_bf16 v[64:67], v[164:167], v[214:217], v[64:67]
	v_mfma_f32_16x16x32_bf16 v[124:127], v[168:171], v[184:187], v[124:127]
	v_mfma_f32_16x16x32_bf16 v[120:123], v[176:179], v[184:187], v[120:123]
	v_mfma_f32_16x16x32_bf16 v[108:111], v[168:171], v[194:197], v[108:111]
	v_mfma_f32_16x16x32_bf16 v[104:107], v[176:179], v[194:197], v[104:107]
	v_mfma_f32_16x16x32_bf16 v[92:95], v[168:171], v[202:205], v[92:95]
	v_mfma_f32_16x16x32_bf16 v[88:91], v[176:179], v[202:205], v[88:91]
	v_mfma_f32_16x16x32_bf16 v[76:79], v[168:171], v[210:213], v[76:79]
	v_mfma_f32_16x16x32_bf16 v[68:71], v[176:179], v[210:213], v[68:71]
	v_mfma_f32_16x16x32_bf16 v[124:127], v[172:175], v[190:193], v[124:127]
	v_mfma_f32_16x16x32_bf16 v[120:123], v[180:183], v[190:193], v[120:123]
	v_mfma_f32_16x16x32_bf16 v[108:111], v[172:175], v[198:201], v[108:111]
	v_mfma_f32_16x16x32_bf16 v[104:107], v[180:183], v[198:201], v[104:107]
	v_mfma_f32_16x16x32_bf16 v[92:95], v[172:175], v[206:209], v[92:95]
	v_mfma_f32_16x16x32_bf16 v[88:91], v[180:183], v[206:209], v[88:91]
	v_mfma_f32_16x16x32_bf16 v[76:79], v[172:175], v[214:217], v[76:79]
	v_mfma_f32_16x16x32_bf16 v[68:71], v[180:183], v[214:217], v[68:71]
	s_setprio 0
	s_barrier
	s_add_i32 s52, s43, s30
	v_lshl_add_u64 v[218:219], s[24:25], 0, v[132:133]
	s_mov_b32 m0, s52
	ds_read_b128 v[184:187], v153 offset:16384
	ds_read_b128 v[190:193], v153 offset:17408
	ds_read_b128 v[194:197], v153 offset:18432
	ds_read_b128 v[198:201], v153 offset:19456
	ds_read_b128 v[202:205], v153 offset:20480
	ds_read_b128 v[206:209], v153 offset:21504
	ds_read_b128 v[210:213], v153 offset:22528
	ds_read_b128 v[214:217], v153 offset:23552
	global_load_lds_dwordx4 v[218:219], off
	s_add_i32 m0, s52, 0x2000
	s_add_u32 s52, s24, 0x40000
	v_lshl_add_u64 v[220:221], s[24:25], 0, v[128:129]
	s_addc_u32 s53, s25, 0
	s_add_i32 s54, s44, s30
	global_load_lds_dwordx4 v[220:221], off
	s_mov_b32 m0, s54
	v_lshl_add_u64 v[224:225], s[26:27], 0, v[130:131]
	global_load_lds_dwordx4 v132, s[52:53]
	s_add_i32 m0, s54, 0x2000
	s_nop 0
	global_load_lds_dwordx4 v128, s[52:53]
	v_lshl_add_u64 v[222:223], s[26:27], 0, v[134:135]
	s_mov_b32 m0, s34
	s_nop 0
	global_load_lds_dwordx4 v[222:223], off
	s_mov_b32 m0, s35
	s_nop 0
	global_load_lds_dwordx4 v[224:225], off
	s_waitcnt vmcnt(8)
	s_waitcnt lgkmcnt(0)
	s_barrier
	s_setprio 1
	v_mfma_f32_16x16x32_bf16 v[56:59], v[144:147], v[184:187], v[56:59]
	v_mfma_f32_16x16x32_bf16 v[48:51], v[160:163], v[184:187], v[48:51]
	v_mfma_f32_16x16x32_bf16 v[40:43], v[144:147], v[194:197], v[40:43]
	v_mfma_f32_16x16x32_bf16 v[32:35], v[160:163], v[194:197], v[32:35]
	v_mfma_f32_16x16x32_bf16 v[24:27], v[144:147], v[202:205], v[24:27]
	v_mfma_f32_16x16x32_bf16 v[16:19], v[160:163], v[202:205], v[16:19]
	v_mfma_f32_16x16x32_bf16 v[8:11], v[144:147], v[210:213], v[8:11]
	v_mfma_f32_16x16x32_bf16 v[0:3], v[160:163], v[210:213], v[0:3]
	v_mfma_f32_16x16x32_bf16 v[56:59], v[156:159], v[190:193], v[56:59]
	v_mfma_f32_16x16x32_bf16 v[48:51], v[164:167], v[190:193], v[48:51]
	v_mfma_f32_16x16x32_bf16 v[40:43], v[156:159], v[198:201], v[40:43]
	v_mfma_f32_16x16x32_bf16 v[32:35], v[164:167], v[198:201], v[32:35]
	v_mfma_f32_16x16x32_bf16 v[24:27], v[156:159], v[206:209], v[24:27]
	v_mfma_f32_16x16x32_bf16 v[16:19], v[164:167], v[206:209], v[16:19]
	v_mfma_f32_16x16x32_bf16 v[8:11], v[156:159], v[214:217], v[8:11]
	v_mfma_f32_16x16x32_bf16 v[0:3], v[164:167], v[214:217], v[0:3]
	v_mfma_f32_16x16x32_bf16 v[60:63], v[168:171], v[184:187], v[60:63]
	v_mfma_f32_16x16x32_bf16 v[52:55], v[176:179], v[184:187], v[52:55]
	v_mfma_f32_16x16x32_bf16 v[44:47], v[168:171], v[194:197], v[44:47]
	v_mfma_f32_16x16x32_bf16 v[36:39], v[176:179], v[194:197], v[36:39]
	v_mfma_f32_16x16x32_bf16 v[28:31], v[168:171], v[202:205], v[28:31]
	v_mfma_f32_16x16x32_bf16 v[20:23], v[176:179], v[202:205], v[20:23]
	v_mfma_f32_16x16x32_bf16 v[12:15], v[168:171], v[210:213], v[12:15]
	v_mfma_f32_16x16x32_bf16 v[4:7], v[176:179], v[210:213], v[4:7]
	v_mfma_f32_16x16x32_bf16 v[60:63], v[172:175], v[190:193], v[60:63]
	v_mfma_f32_16x16x32_bf16 v[52:55], v[180:183], v[190:193], v[52:55]
	v_mfma_f32_16x16x32_bf16 v[44:47], v[172:175], v[198:201], v[44:47]
	v_mfma_f32_16x16x32_bf16 v[36:39], v[180:183], v[198:201], v[36:39]
	v_mfma_f32_16x16x32_bf16 v[28:31], v[172:175], v[206:209], v[28:31]
	v_mfma_f32_16x16x32_bf16 v[20:23], v[180:183], v[206:209], v[20:23]
	v_mfma_f32_16x16x32_bf16 v[12:15], v[172:175], v[214:217], v[12:15]
	v_mfma_f32_16x16x32_bf16 v[4:7], v[180:183], v[214:217], v[4:7]
	s_setprio 0
	s_barrier
; #define PG8_STAGE(bufoff, gbase, voff) do { _Pragma("unroll") for (int _i = 0; _i < 2; ++_i) \
;         __builtin_amdgcn_global_load_lds((const unsigned*)((const char*)(gbase) + (voff)[_i]), (PG8_LAS unsigned*)(lds + (bufoff) + ldsw + _i * 8192), 16, 0, 0); } while (0)
; #define PG8_LDA(dst, b, h) do { _Pragma("unroll") for (int m = 0; m < 4; ++m) _Pragma("unroll") for (int k = 0; k < 2; ++k) dst[m][k] = *(const PG8_LAS bf16x8*)(lds + PG8_SA(b, h) + aoff + m * 2048 + k * 1024); } while (0)
; #define PG8_LDB(dst, b, h) do { _Pragma("unroll") for (int n = 0; n < 2; ++n) _Pragma("unroll") for (int k = 0; k < 2; ++k) dst[n][k] = *(const PG8_LAS bf16x8*)(lds + PG8_SB(b, h) + boff + n * 2048 + k * 1024); } while (0)
; #define PG8_MMA(ai, bj, At, Bt) do { __builtin_amdgcn_s_setprio(1); _Pragma("unroll") for (int m = 0; m < 4; ++m) _Pragma("unroll") for (int n = 0; n < 2; ++n) _Pragma("unroll") for (int k = 0; k < 2; ++k) \
;         acc[ai][bj][m][n] = __builtin_amdgcn_mfma_f32_16x16x32_bf16(Bt[n][k], At[m][k], acc[ai][bj][m][n], 0, 0, 0); __builtin_amdgcn_s_setprio(0); } while (0)
; #define PG8_WAIT_V(n) asm volatile("s_waitcnt vmcnt(" #n ")" ::: "memory")
; #define PG8_WAIT_L(n) asm volatile("s_waitcnt lgkmcnt(" #n ")" ::: "memory")
; #define PG8_BAR __builtin_amdgcn_s_barrier()
; #define PG8_SCHED __builtin_amdgcn_sched_barrier(0)
; template <class Epi, class Sched, bool ALIGN_EPI = false, bool SP2 = false>
; __device__ __forceinline__ void gemm_phase(PG8_LAS unsigned char* lds, const Gemm g, const Sched& S, const Epi& E) {
;     ...
;             PG8_LDB(B0, 1, 0); PG8_LDB(B1, 1, 1); PG8_SCHED; PG8_LDA(At, 1, 0); PG8_STAGE(PG8_SA(0, 1), a2 + hstep, voffA);
;             PG8_WAIT_V(8); PG8_WAIT_L(0); PG8_BAR; PG8_MMA(0, 0, At, B0); PG8_MMA(0, 1, At, B1); PG8_BAR; PG8_SCHED;
;             PG8_LDA(At, 1, 1); PG8_STAGE(PG8_SB(1, 0), b3, voffB); PG8_STAGE(PG8_SB(1, 1), b3 + hstep, voffB); PG8_STAGE(PG8_SA(1, 0), a3, voffA);
;             PG8_WAIT_V(8); PG8_WAIT_L(0); PG8_BAR; PG8_MMA(1, 0, At, B0); PG8_MMA(1, 1, At, B1); PG8_BAR; PG8_SCHED;
;     ...
;         if constexpr (ALIGN_EPI) { if (wr == 0) PG8_BAR; }
	s_add_i32 s52, 0, 0x18000
	v_add_u32_e32 v155, s52, v149
	s_add_i32 s53, 0, 0x1c000
	ds_read_b128 v[144:147], v155
	ds_read_b128 v[156:159], v155 offset:1024
	ds_read_b128 v[160:163], v155 offset:2048
	ds_read_b128 v[164:167], v155 offset:3072
	v_add_u32_e32 v155, s53, v149
	ds_read_b128 v[168:171], v155
	ds_read_b128 v[172:175], v155 offset:1024
	ds_read_b128 v[176:179], v155 offset:2048
	ds_read_b128 v[180:183], v155 offset:3072
	s_add_u32 s26, s26, 0x40000
	s_addc_u32 s27, s27, 0
	s_mov_b32 m0, s36
	ds_read_b128 v[184:187], v153 offset:32768
	ds_read_b128 v[190:193], v153 offset:33792
	ds_read_b128 v[194:197], v153 offset:34816
	ds_read_b128 v[198:201], v153 offset:35840
	ds_read_b128 v[202:205], v153 offset:36864
	ds_read_b128 v[206:209], v153 offset:37888
	ds_read_b128 v[210:213], v153 offset:38912
	ds_read_b128 v[214:217], v153 offset:39936
	global_load_lds_dwordx4 v134, s[26:27]
	v_lshl_add_u64 v[226:227], s[26:27], 0, v[130:131]
	s_mov_b32 m0, s37
	s_nop 0
	global_load_lds_dwordx4 v[226:227], off
	s_waitcnt vmcnt(8)
	s_waitcnt lgkmcnt(0)
	s_barrier
	s_setprio 1
	v_mfma_f32_16x16x32_bf16 v[116:119], v[144:147], v[184:187], v[116:119]
	v_mfma_f32_16x16x32_bf16 v[112:115], v[160:163], v[184:187], v[112:115]
	v_mfma_f32_16x16x32_bf16 v[100:103], v[144:147], v[194:197], v[100:103]
	v_mfma_f32_16x16x32_bf16 v[96:99], v[160:163], v[194:197], v[96:99]
	v_mfma_f32_16x16x32_bf16 v[84:87], v[144:147], v[202:205], v[84:87]
	v_mfma_f32_16x16x32_bf16 v[80:83], v[160:163], v[202:205], v[80:83]
	v_mfma_f32_16x16x32_bf16 v[72:75], v[144:147], v[210:213], v[72:75]
	v_mfma_f32_16x16x32_bf16 v[64:67], v[160:163], v[210:213], v[64:67]
	v_mfma_f32_16x16x32_bf16 v[116:119], v[156:159], v[190:193], v[116:119]
	v_mfma_f32_16x16x32_bf16 v[112:115], v[164:167], v[190:193], v[112:115]
	v_mfma_f32_16x16x32_bf16 v[100:103], v[156:159], v[198:201], v[100:103]
	v_mfma_f32_16x16x32_bf16 v[96:99], v[164:167], v[198:201], v[96:99]
	v_mfma_f32_16x16x32_bf16 v[84:87], v[156:159], v[206:209], v[84:87]
	v_mfma_f32_16x16x32_bf16 v[80:83], v[164:167], v[206:209], v[80:83]
	v_mfma_f32_16x16x32_bf16 v[72:75], v[156:159], v[214:217], v[72:75]
	v_mfma_f32_16x16x32_bf16 v[64:67], v[164:167], v[214:217], v[64:67]
	v_mfma_f32_16x16x32_bf16 v[124:127], v[168:171], v[184:187], v[124:127]
	v_mfma_f32_16x16x32_bf16 v[120:123], v[176:179], v[184:187], v[120:123]
	v_mfma_f32_16x16x32_bf16 v[108:111], v[168:171], v[194:197], v[108:111]
	v_mfma_f32_16x16x32_bf16 v[104:107], v[176:179], v[194:197], v[104:107]
	v_mfma_f32_16x16x32_bf16 v[92:95], v[168:171], v[202:205], v[92:95]
	v_mfma_f32_16x16x32_bf16 v[88:91], v[176:179], v[202:205], v[88:91]
	v_mfma_f32_16x16x32_bf16 v[76:79], v[168:171], v[210:213], v[76:79]
	v_mfma_f32_16x16x32_bf16 v[68:71], v[176:179], v[210:213], v[68:71]
	v_mfma_f32_16x16x32_bf16 v[124:127], v[172:175], v[190:193], v[124:127]
	v_mfma_f32_16x16x32_bf16 v[120:123], v[180:183], v[190:193], v[120:123]
	v_mfma_f32_16x16x32_bf16 v[108:111], v[172:175], v[198:201], v[108:111]
	v_mfma_f32_16x16x32_bf16 v[104:107], v[180:183], v[198:201], v[104:107]
	v_mfma_f32_16x16x32_bf16 v[92:95], v[172:175], v[206:209], v[92:95]
	v_mfma_f32_16x16x32_bf16 v[88:91], v[180:183], v[206:209], v[88:91]
	v_mfma_f32_16x16x32_bf16 v[76:79], v[172:175], v[214:217], v[76:79]
	v_mfma_f32_16x16x32_bf16 v[68:71], v[180:183], v[214:217], v[68:71]
	s_setprio 0
	s_barrier
	s_add_i32 s26, s52, s30
	v_lshl_add_u64 v[218:219], v[218:219], 0, s[6:7]
	s_mov_b32 m0, s26
	ds_read_b128 v[184:187], v153 offset:49152
	ds_read_b128 v[190:193], v153 offset:50176
	ds_read_b128 v[194:197], v153 offset:51200
	ds_read_b128 v[198:201], v153 offset:52224
	ds_read_b128 v[202:205], v153 offset:53248
	ds_read_b128 v[206:209], v153 offset:54272
	ds_read_b128 v[210:213], v153 offset:55296
	ds_read_b128 v[214:217], v153 offset:56320
	global_load_lds_dwordx4 v[218:219], off
	s_add_i32 m0, s26, 0x2000
	s_add_u32 s24, s24, 0x40080
	v_lshl_add_u64 v[218:219], v[220:221], 0, s[6:7]
	s_addc_u32 s25, s25, 0
	s_add_i32 s26, s53, s30
	global_load_lds_dwordx4 v[218:219], off
	s_mov_b32 m0, s26
	s_nop 0
	global_load_lds_dwordx4 v132, s[24:25]
	s_add_i32 m0, s26, 0x2000
	s_nop 0
	global_load_lds_dwordx4 v128, s[24:25]
	v_lshl_add_u64 v[218:219], v[222:223], 0, s[6:7]
	s_mov_b32 m0, s39
	s_nop 0
	global_load_lds_dwordx4 v[218:219], off
	v_lshl_add_u64 v[218:219], v[224:225], 0, s[6:7]
	s_mov_b32 m0, s40
	s_nop 0
	global_load_lds_dwordx4 v[218:219], off
	s_waitcnt vmcnt(8)
	s_waitcnt lgkmcnt(0)
	s_barrier
	s_setprio 1
	v_mfma_f32_16x16x32_bf16 v[56:59], v[144:147], v[184:187], v[56:59]
	v_mfma_f32_16x16x32_bf16 v[48:51], v[160:163], v[184:187], v[48:51]
	v_mfma_f32_16x16x32_bf16 v[40:43], v[144:147], v[194:197], v[40:43]
	v_mfma_f32_16x16x32_bf16 v[32:35], v[160:163], v[194:197], v[32:35]
	v_mfma_f32_16x16x32_bf16 v[24:27], v[144:147], v[202:205], v[24:27]
	v_mfma_f32_16x16x32_bf16 v[16:19], v[160:163], v[202:205], v[16:19]
	v_mfma_f32_16x16x32_bf16 v[8:11], v[144:147], v[210:213], v[8:11]
	v_mfma_f32_16x16x32_bf16 v[0:3], v[160:163], v[210:213], v[0:3]
	v_mfma_f32_16x16x32_bf16 v[56:59], v[156:159], v[190:193], v[56:59]
	v_mfma_f32_16x16x32_bf16 v[48:51], v[164:167], v[190:193], v[48:51]
	v_mfma_f32_16x16x32_bf16 v[40:43], v[156:159], v[198:201], v[40:43]
	v_mfma_f32_16x16x32_bf16 v[32:35], v[164:167], v[198:201], v[32:35]
	v_mfma_f32_16x16x32_bf16 v[24:27], v[156:159], v[206:209], v[24:27]
	v_mfma_f32_16x16x32_bf16 v[16:19], v[164:167], v[206:209], v[16:19]
	v_mfma_f32_16x16x32_bf16 v[8:11], v[156:159], v[214:217], v[8:11]
	v_mfma_f32_16x16x32_bf16 v[0:3], v[164:167], v[214:217], v[0:3]
	v_mfma_f32_16x16x32_bf16 v[60:63], v[168:171], v[184:187], v[60:63]
	v_mfma_f32_16x16x32_bf16 v[52:55], v[176:179], v[184:187], v[52:55]
	v_mfma_f32_16x16x32_bf16 v[44:47], v[168:171], v[194:197], v[44:47]
	v_mfma_f32_16x16x32_bf16 v[36:39], v[176:179], v[194:197], v[36:39]
	v_mfma_f32_16x16x32_bf16 v[28:31], v[168:171], v[202:205], v[28:31]
	v_mfma_f32_16x16x32_bf16 v[20:23], v[176:179], v[202:205], v[20:23]
	v_mfma_f32_16x16x32_bf16 v[12:15], v[168:171], v[210:213], v[12:15]
	v_mfma_f32_16x16x32_bf16 v[4:7], v[176:179], v[210:213], v[4:7]
	v_mfma_f32_16x16x32_bf16 v[60:63], v[172:175], v[190:193], v[60:63]
	v_mfma_f32_16x16x32_bf16 v[52:55], v[180:183], v[190:193], v[52:55]
	v_mfma_f32_16x16x32_bf16 v[44:47], v[172:175], v[198:201], v[44:47]
	v_mfma_f32_16x16x32_bf16 v[36:39], v[180:183], v[198:201], v[36:39]
	v_mfma_f32_16x16x32_bf16 v[28:31], v[172:175], v[206:209], v[28:31]
	v_mfma_f32_16x16x32_bf16 v[20:23], v[180:183], v[206:209], v[20:23]
	v_mfma_f32_16x16x32_bf16 v[12:15], v[172:175], v[214:217], v[12:15]
	v_mfma_f32_16x16x32_bf16 v[4:7], v[180:183], v[214:217], v[4:7]
	s_setprio 0
	s_barrier
	s_add_i32 s51, s51, 2
	s_add_u32 s22, s22, 0x100
	s_addc_u32 s23, s23, 0
	s_add_u32 s49, s49, 0x100
	s_addc_u32 s50, s50, 0
	s_cmp_gt_u32 s51, 13
	s_cbranch_scc0 .LBB0_782
	s_and_b64 vcc, exec, s[12:13]
	s_cbranch_vccz .LBB0_785
	s_barrier
